# GEMM staging: each LDS-DMA piece reads 8 whole 128-byte rows (coalesced) instead of 16 half-rows; LDS half-tile image re-laid out with an XOR chunk swizzle and the fragment reads follow it
# speedup vs baseline: 1.0001x; 1.0001x over previous
; #define PG8_STAGE(bufoff, gbase, voff) do { _Pragma("unroll") for (int _i = 0; _i < 2; ++_i) \
;         __builtin_amdgcn_global_load_lds((const unsigned*)((const char*)(gbase) + (voff)[_i]), (PG8_LAS unsigned*)(lds + (bufoff) + ldsw + _i * 8192), 16, 0, 0); } while (0)
; #define PG8_BAR __builtin_amdgcn_s_barrier()
; template <class Epi, class Sched, bool ALIGN_EPI = false, bool SP2 = false>
; __device__ __forceinline__ void gemm_phase(PG8_LAS unsigned char* lds, const Gemm g, const Sched& S, const Epi& E) {
;     ...
;     for (int i = 0; i < 2; ++i) { int R, C; stage_rc(tid * 16 + i * 8192, R, C); const int Rb = Epi::PERM ? ((R & ~31) + perm32(R & 31)) : R;
;         voffA[i] = (unsigned)(R * K + C) * 2u; voffB[i] = (unsigned)(Rb * K + C) * 2u; }
;     ...
;     const char* cA = (const char*)g.A + (size_t)cur.pm * tstep; const char* cB = (const char*)g.Bt + (size_t)cur.pn * tstep;
;     S.a_ready(cur);
;     if constexpr (SP2) {
;         PG8_STAGE(PG8_SB(0, 0), cB, voffB); PG8_STAGE(PG8_SB(0, 1), cB + hstep, voffB); PG8_STAGE(PG8_SA(0, 0), cA, voffA); PG8_STAGE(PG8_SA(0, 1), cA + hstep, voffA);
;         if (wr == 1) PG8_BAR;
.LBB0_116:
	v_ashrrev_i32_e32 v3, 31, v10
	v_lshrrev_b32_e32 v3, 26, v3
	v_add_u32_e32 v3, v10, v3
	v_ashrrev_i32_e32 v11, 6, v3
	v_bfe_i32 v3, v10, 27, 1
	v_lshlrev_b32_e32 v2, 4, v10
	v_lshrrev_b32_e32 v3, 22, v3
	v_add_u32_e32 v3, v2, v3
	v_and_b32_e32 v3, 0xfffffc00, v3
	v_sub_u32_e32 v3, v2, v3
	v_lshrrev_b32_e32 v4, 4, v3
	v_bitop3_b32 v3, v4, v3, 32 bitop3:0x6c
	v_ashrrev_i32_e32 v5, 31, v3
	v_lshrrev_b32_e32 v5, 26, v5
	v_add_u32_e32 v5, v3, v5
	v_lshlrev_b32_e32 v4, 3, v11
	v_ashrrev_i32_e32 v12, 6, v5
	v_and_b32_e32 v5, 0xc0, v5
	v_and_b32_e32 v4, -16, v4
	v_sub_u32_e32 v3, v3, v5
	v_mov_b32_e32 v5, 1
	v_add_u32_e32 v4, v12, v4
	v_ashrrev_i16_sdwa v3, v5, sext(v3) dst_sel:DWORD dst_unused:UNUSED_PAD src0_sel:DWORD src1_sel:BYTE_0
	v_lshlrev_b32_e32 v6, 5, v11
	v_bfe_i32 v13, v3, 0, 16
	v_lshlrev_b32_e32 v3, 1, v4
	v_lshrrev_b32_e32 v7, 2, v4
	v_and_b32_e32 v8, 3, v12
	s_mov_b32 s4, 0xfffe0
	v_and_b32_e32 v6, 32, v6
	v_and_b32_e32 v3, 24, v3
	v_and_b32_e32 v7, 4, v7
	v_and_or_b32 v8, v4, s4, v8
	v_or3_b32 v3, v8, v7, v3
	v_add_lshl_u32 v6, v6, v13, 1
	v_add_u32_e32 v2, 0x2000, v2
	v_and_b32_e32 v154, 63, v0
	v_lshrrev_b32_e32 v155, 6, v0
	v_lshrrev_b32_e32 v156, 3, v154
	v_lshl_add_u32 v156, v155, 3, v156
	v_and_b32_e32 v157, 1, v155
	v_lshrrev_b32_e32 v166, 4, v154
	v_lshl_add_u32 v157, v157, 2, v166
	v_and_b32_e32 v166, 7, v154
	v_xor_b32_e32 v157, v157, v166
	v_lshlrev_b32_e32 v157, 4, v157
	v_mul_u32_u24_e32 v166, 0x1000, v156
	v_add_u32_e32 v150, v166, v157
	v_add_u32_e32 v151, 0x40000, v150
	v_and_b32_e32 v166, 31, v156
	v_bfe_u32 v167, v166, 2, 2
	v_lshlrev_b32_e32 v167, 3, v167
	v_lshrrev_b32_e32 v154, 4, v166
	v_lshl_add_u32 v167, v154, 2, v167
	v_and_b32_e32 v154, 3, v166
	v_add_u32_e32 v167, v167, v154
	v_and_b32_e32 v154, -32, v156
	v_add_u32_e32 v167, v167, v154
	v_mul_u32_u24_e32 v167, 0x1000, v167
	v_add_u32_e32 v152, v167, v157
	v_add_u32_e32 v153, 0x40000, v152
	v_mov_b32_e32 v132, v152
	v_ashrrev_i32_e32 v3, 31, v2
	v_lshrrev_b32_e32 v3, 22, v3
	v_add_u32_e32 v3, v2, v3
	v_ashrrev_i32_e32 v14, 10, v3
	v_mul_i32_i24_e32 v3, 0x400, v14
	v_sub_u32_e32 v2, v2, v3
	v_lshrrev_b32_e32 v3, 4, v2
	v_bitop3_b32 v2, v3, v2, 32 bitop3:0x6c
	v_mov_b32_e32 v130, v150
	v_ashrrev_i32_e32 v4, 31, v2
	v_lshrrev_b32_e32 v4, 26, v4
	v_add_u32_e32 v4, v2, v4
	v_lshlrev_b32_e32 v3, 3, v14
	v_ashrrev_i32_e32 v15, 6, v4
	v_and_b32_e32 v4, 0xc0, v4
	s_ashr_i32 s7, s22, 6
	s_ashr_i32 s35, s34, 31
	s_ashr_i32 s9, s8, 31
	s_ashr_i32 s6, s22, 8
	v_and_b32_e32 v3, -16, v3
	v_sub_u32_e32 v2, v2, v4
	s_lshl_b32 s48, s7, 10
	s_lshl_b64 s[16:17], s[34:35], 20
	s_lshl_b64 s[18:19], s[8:9], 20
	v_add_u32_e32 v3, v15, v3
	v_ashrrev_i16_sdwa v2, v5, sext(v2) dst_sel:DWORD dst_unused:UNUSED_PAD src0_sel:DWORD src1_sel:BYTE_0
	s_add_u32 s38, s12, s18
	v_lshlrev_b32_e32 v6, 5, v14
	v_bfe_i32 v16, v2, 0, 16
	v_lshlrev_b32_e32 v2, 1, v3
	v_lshrrev_b32_e32 v4, 2, v3
	v_and_b32_e32 v5, 3, v15
	s_addc_u32 s39, s13, s19
	s_add_i32 s49, s48, 0
	v_and_b32_e32 v6, 32, v6
	v_and_b32_e32 v2, 24, v2
	v_and_b32_e32 v4, 4, v4
	v_and_or_b32 v5, v3, s4, v5
	s_add_i32 m0, s49, 0x10000
	v_or3_b32 v2, v5, v4, v2
	v_add_lshl_u32 v4, v6, v16, 1
	global_load_lds_dwordx4 v132, s[38:39]
	s_add_i32 m0, s49, 0x12000
	v_mov_b32_e32 v136, v153
	s_add_u32 s18, s38, 0x80000
	global_load_lds_dwordx4 v136, s[38:39]
	s_addc_u32 s19, s39, 0
	s_add_i32 m0, s49, 0x14000
	v_mov_b32_e32 v134, v151
	global_load_lds_dwordx4 v132, s[18:19]
	s_add_i32 m0, s49, 0x16000
	s_add_u32 s36, s81, s16
	s_addc_u32 s37, s82, s17
	s_add_i32 s50, s49, 0x2000
	global_load_lds_dwordx4 v136, s[18:19]
	s_mov_b32 m0, s49
	s_add_u32 s16, s36, 0x80000
	global_load_lds_dwordx4 v130, s[36:37]
	s_mov_b32 m0, s50
	s_addc_u32 s17, s37, 0
	s_add_i32 s51, s49, 0x4000
	global_load_lds_dwordx4 v134, s[36:37]
	s_mov_b32 m0, s51
	s_add_i32 s52, s49, 0x6000
	global_load_lds_dwordx4 v130, s[16:17]
	s_mov_b32 m0, s52
	v_mov_b32_e32 v139, 0
	global_load_lds_dwordx4 v134, s[16:17]
	v_mov_b32_e32 v133, v139
	v_mov_b32_e32 v137, v139
	v_mov_b32_e32 v131, v139
	v_mov_b32_e32 v135, v139
	s_cmp_eq_u32 s6, 1
	s_mov_b32 s53, 0
	v_lshl_add_u64 v[8:9], s[38:39], 0, v[132:133]
	v_lshl_add_u64 v[6:7], s[38:39], 0, v[136:137]
	v_lshl_add_u64 v[2:3], s[36:37], 0, v[130:131]
	s_cselect_b64 s[16:17], -1, 0
	s_cmp_lg_u32 s6, 1
	v_lshl_add_u64 v[4:5], s[36:37], 0, v[134:135]
	s_cbranch_scc1 .LBB0_118
	s_barrier
; #define PG8_STAGE(bufoff, gbase, voff) do { _Pragma("unroll") for (int _i = 0; _i < 2; ++_i) \
;         __builtin_amdgcn_global_load_lds((const unsigned*)((const char*)(gbase) + (voff)[_i]), (PG8_LAS unsigned*)(lds + (bufoff) + ldsw + _i * 8192), 16, 0, 0); } while (0)
; #define PG8_WAIT_V(n) asm volatile("s_waitcnt vmcnt(" #n ")" ::: "memory")
; #define PG8_BAR __builtin_amdgcn_s_barrier()
; template <class Epi, class Sched, bool ALIGN_EPI = false, bool SP2 = false>
; __device__ __forceinline__ void gemm_phase(PG8_LAS unsigned char* lds, const Gemm g, const Sched& S, const Epi& E) {
;     ...
;     const int aoff = lds_byte(wr * 64 + fr, fq * 8), boff = lds_byte(wc * 32 + fr, fq * 8);
;     ...
;         PG8_WAIT_V(2); PG8_BAR;
;         PG8_STAGE(PG8_SB(1, 0), cB + kstep, voffB); PG8_STAGE(PG8_SA(1, 0), cA + kstep, voffA); PG8_STAGE(PG8_SB(1, 1), cB + hstep + kstep, voffB);
;         PG8_WAIT_V(6); PG8_BAR;
.LBB0_118:
	s_lshl_b32 s5, s7, 5
	s_and_b32 s5, s5, 0x60
	s_lshl_b32 s4, s6, 13
	s_lshl_b32 s7, s5, 7
	s_add_u32 s18, s42, 0x1ee00000
	s_mov_b64 s[20:21], 0x80
	s_addc_u32 s19, s43, 0
	s_add_i32 m0, s49, 0x18000
	v_lshl_add_u64 v[8:9], v[8:9], 0, s[20:21]
	s_waitcnt vmcnt(2)
	s_barrier
	global_load_lds_dwordx4 v[8:9], off
	v_lshl_add_u64 v[6:7], v[6:7], 0, s[20:21]
	s_add_i32 m0, s49, 0x1a000
	s_add_i32 s58, s49, 0x8000
	s_add_i32 s59, s49, 0xa000
	global_load_lds_dwordx4 v[6:7], off
	v_lshl_add_u64 v[2:3], v[2:3], 0, s[20:21]
	s_mov_b32 m0, s58
	s_add_u32 s24, s38, 0x80080
	global_load_lds_dwordx4 v[2:3], off
	v_lshl_add_u64 v[2:3], v[4:5], 0, s[20:21]
	s_mov_b32 m0, s59
	s_addc_u32 s25, s39, 0
	global_load_lds_dwordx4 v[2:3], off
	s_add_i32 m0, s49, 0x1c000
	v_lshl_add_u64 v[2:3], s[24:25], 0, v[132:133]
	global_load_lds_dwordx4 v[2:3], off
	v_lshl_add_u64 v[2:3], s[24:25], 0, v[136:137]
	s_add_i32 m0, s49, 0x1e000
	s_cmpk_lt_u32 s22, 0x100
	global_load_lds_dwordx4 v[2:3], off
	v_lshrrev_b32_e32 v3, 1, v10
	v_and_b32_e32 v3, 24, v3
	v_and_b32_e32 v2, 15, v10
	v_lshlrev_b32_e32 v4, 1, v3
	v_lshl_or_b32 v158, s6, 6, v2
	v_lshl_or_b32 v2, v2, 6, v4
	v_lshlrev_b32_e32 v4, 2, v10
	v_and_b32_e32 v4, 32, v4
	v_bitop3_b32 v5, v2, s4, v4 bitop3:0xde
	v_bitop3_b32 v159, v2, s7, v4 bitop3:0xde
	v_lshlrev_b32_e32 v2, 15, v11
	v_and_b32_e32 v2, 0xffff0000, v2
	v_or_b32_e32 v160, s5, v3
	v_lshl_add_u32 v2, v12, 12, v2
	v_and_b32_e32 v3, 1, v11
	v_lshl_or_b32 v2, v3, 6, v2
	v_lshl_add_u32 v140, v13, 1, v2
	v_lshlrev_b32_e32 v2, 15, v14
	v_and_b32_e32 v2, 0xffff0000, v2
	s_waitcnt vmcnt(6)
	v_lshl_add_u32 v2, v15, 12, v2
	v_and_b32_e32 v3, 1, v14
	s_cselect_b64 s[22:23], -1, 0
	v_lshl_or_b32 v2, v3, 6, v2
	s_add_i32 s64, 0, 0x10000
	s_add_i32 s65, 0, 0x14000
	s_ashr_i32 s60, s46, 31
	s_mov_b32 s61, s46
	s_ashr_i32 s62, s2, 31
	v_mov_b32_e32 v141, v139
	v_lshl_add_u32 v142, v16, 1, v2
	v_and_b32_e32 v154, 63, v0
	v_lshrrev_b32_e32 v155, 6, v0
	v_lshrrev_b32_e32 v156, 1, v155
	v_lshrrev_b32_e32 v157, 2, v154
	v_lshl_add_u32 v156, v156, 4, v157
	v_and_b32_e32 v157, 3, v154
	v_lshlrev_b32_e32 v157, 4, v157
	v_bfe_u32 v166, v154, 5, 1
	v_lshlrev_b32_e32 v166, 5, v166
	v_xor_b32_e32 v157, v157, v166
	v_and_b32_e32 v166, 1, v155
	v_lshl_add_u32 v157, v166, 6, v157
	v_mul_u32_u24_e32 v156, 0x1000, v156
	v_add_u32_e32 v156, v156, v157
	v_sub_u32_e32 v156, v130, v156
	v_add_u32_e32 v140, v140, v156
	v_add_u32_e32 v142, v142, v156
	v_mov_b32_e32 v143, v139
	v_mov_b64_e32 v[144:145], 0x600
	v_mov_b64_e32 v[146:147], 0x5ff
	s_movk_i32 s63, 0xc1
	v_add_u32_e32 v161, s64, v159
	v_add_u32_e32 v162, s65, v159
	v_add_u32_e32 v163, 0, v5
	s_movk_i32 s66, 0x3000
	v_mov_b32_e32 v164, 0x3e38aa3b
	s_barrier
	s_branch .LBB0_121

; template <class Epi, class Sched, bool ALIGN_EPI = false, bool SP2 = false>
; __device__ __forceinline__ void gemm_phase(PG8_LAS unsigned char* lds, const Gemm g, const Sched& S, const Epi& E) {
;     ...
;     const int aoff = lds_byte(wr * 64 + fr, fq * 8), boff = lds_byte(wc * 32 + fr, fq * 8);
;     ...
; #pragma unroll
;         for (int a = 0; a < 2; ++a)
; #pragma unroll
;             for (int b = 0; b < 2; ++b)
; #pragma unroll
;                 for (int m = 0; m < 4; ++m)
; #pragma unroll
;                     for (int n = 0; n < 2; ++n) acc[a][b][m][n] = (f32x4){0.f, 0.f, 0.f, 0.f};
;         cur = nxt; cA = nA; cB = nB; ++ui;
.LBB0_123:
	s_ashr_i32 s27, s26, 31
	s_lshl_b64 s[28:29], s[26:27], 20
	s_add_u32 s28, s81, s28
	s_addc_u32 s29, s82, s29
	s_and_b64 s[30:31], s[6:7], exec
	s_cselect_b32 s9, s29, s37
	s_cselect_b32 s27, s28, s36
	s_ashr_i32 s25, s24, 31
	s_lshl_b64 s[30:31], s[24:25], 20
	s_add_u32 s30, s12, s30
	s_addc_u32 s31, s13, s31
	s_and_b64 s[40:41], s[6:7], exec
	s_cselect_b32 s25, s31, s39
	s_cselect_b32 s35, s30, s38
	s_add_u32 s36, s36, 0x80080
	s_addc_u32 s37, s37, 0
	s_add_u32 s67, s38, 0x100
	v_mov_b32_e32 v2, 0
	s_addc_u32 s68, s39, 0
	s_mov_b32 s69, -2
	v_mov_b32_e32 v3, v2
	v_mov_b32_e32 v4, v2
	v_mov_b32_e32 v5, v2
	v_mov_b32_e32 v6, v2
	v_mov_b32_e32 v7, v2
	v_mov_b32_e32 v8, v2
	v_mov_b32_e32 v9, v2
	v_mov_b32_e32 v18, v2
	v_mov_b32_e32 v19, v2
	v_mov_b32_e32 v20, v2
	v_mov_b32_e32 v21, v2
	v_mov_b32_e32 v22, v2
	v_mov_b32_e32 v23, v2
	v_mov_b32_e32 v24, v2
	v_mov_b32_e32 v25, v2
	v_mov_b32_e32 v34, v2
	v_mov_b32_e32 v35, v2
	v_mov_b32_e32 v36, v2
	v_mov_b32_e32 v37, v2
	v_mov_b32_e32 v38, v2
	v_mov_b32_e32 v39, v2
	v_mov_b32_e32 v40, v2
	v_mov_b32_e32 v41, v2
	v_mov_b32_e32 v50, v2
	v_mov_b32_e32 v51, v2
	v_mov_b32_e32 v52, v2
	v_mov_b32_e32 v53, v2
	v_mov_b32_e32 v54, v2
	v_mov_b32_e32 v55, v2
	v_mov_b32_e32 v56, v2
	v_mov_b32_e32 v57, v2
	v_mov_b32_e32 v10, v2
	v_mov_b32_e32 v11, v2
	v_mov_b32_e32 v12, v2
	v_mov_b32_e32 v13, v2
	v_mov_b32_e32 v14, v2
	v_mov_b32_e32 v15, v2
	v_mov_b32_e32 v16, v2
	v_mov_b32_e32 v17, v2
	v_mov_b32_e32 v26, v2
	v_mov_b32_e32 v27, v2
	v_mov_b32_e32 v28, v2
	v_mov_b32_e32 v29, v2
	v_mov_b32_e32 v30, v2
	v_mov_b32_e32 v31, v2
	v_mov_b32_e32 v32, v2
	v_mov_b32_e32 v33, v2
	v_mov_b32_e32 v42, v2
	v_mov_b32_e32 v43, v2
	v_mov_b32_e32 v44, v2
	v_mov_b32_e32 v45, v2
	v_mov_b32_e32 v46, v2
	v_mov_b32_e32 v47, v2
	v_mov_b32_e32 v48, v2
	v_mov_b32_e32 v49, v2
	v_mov_b32_e32 v58, v2
	v_mov_b32_e32 v59, v2
	v_mov_b32_e32 v60, v2
	v_mov_b32_e32 v61, v2
	v_mov_b32_e32 v62, v2
	v_mov_b32_e32 v63, v2
	v_mov_b32_e32 v64, v2
	v_mov_b32_e32 v65, v2
	v_mov_b32_e32 v66, v2
	v_mov_b32_e32 v67, v2
	v_mov_b32_e32 v68, v2
	v_mov_b32_e32 v69, v2
	v_mov_b32_e32 v70, v2
	v_mov_b32_e32 v71, v2
	v_mov_b32_e32 v72, v2
	v_mov_b32_e32 v73, v2
	v_mov_b32_e32 v82, v2
	v_mov_b32_e32 v83, v2
	v_mov_b32_e32 v84, v2
	v_mov_b32_e32 v85, v2
	v_mov_b32_e32 v86, v2
	v_mov_b32_e32 v87, v2
	v_mov_b32_e32 v88, v2
	v_mov_b32_e32 v89, v2
	v_mov_b32_e32 v98, v2
	v_mov_b32_e32 v99, v2
	v_mov_b32_e32 v100, v2
	v_mov_b32_e32 v101, v2
	v_mov_b32_e32 v102, v2
	v_mov_b32_e32 v103, v2
	v_mov_b32_e32 v104, v2
	v_mov_b32_e32 v105, v2
	v_mov_b32_e32 v114, v2
	v_mov_b32_e32 v115, v2
	v_mov_b32_e32 v116, v2
	v_mov_b32_e32 v117, v2
	v_mov_b32_e32 v118, v2
	v_mov_b32_e32 v119, v2
	v_mov_b32_e32 v120, v2
	v_mov_b32_e32 v121, v2
	v_mov_b32_e32 v74, v2
	v_mov_b32_e32 v75, v2
	v_mov_b32_e32 v76, v2
	v_mov_b32_e32 v77, v2
	v_mov_b32_e32 v78, v2
	v_mov_b32_e32 v79, v2
	v_mov_b32_e32 v80, v2
	v_mov_b32_e32 v81, v2
	v_mov_b32_e32 v90, v2
	v_mov_b32_e32 v91, v2
	v_mov_b32_e32 v92, v2
	v_mov_b32_e32 v93, v2
	v_mov_b32_e32 v94, v2
	v_mov_b32_e32 v95, v2
	v_mov_b32_e32 v96, v2
	v_mov_b32_e32 v97, v2
	v_mov_b32_e32 v106, v2
	v_mov_b32_e32 v107, v2
	v_mov_b32_e32 v108, v2
	v_mov_b32_e32 v109, v2
	v_mov_b32_e32 v110, v2
	v_mov_b32_e32 v111, v2
	v_mov_b32_e32 v112, v2
	v_mov_b32_e32 v113, v2
	v_mov_b32_e32 v122, v2
	v_mov_b32_e32 v123, v2
	v_mov_b32_e32 v124, v2
	v_mov_b32_e32 v125, v2
	v_mov_b32_e32 v126, v2
	v_mov_b32_e32 v127, v2
	v_mov_b32_e32 v128, v2
	v_mov_b32_e32 v129, v2
	v_and_b32_e32 v150, 63, v0
	v_lshrrev_b32_e32 v151, 6, v0
	v_and_b32_e32 v152, 15, v150
	v_lshrrev_b32_e32 v153, 4, v150
	v_bfe_u32 v154, v152, 1, 3
	v_xor_b32_e32 v153, v153, v154
	v_lshlrev_b32_e32 v153, 4, v153
	v_and_b32_e32 v154, 7, v152
	v_lshl_add_u32 v153, v154, 7, v153
	v_lshrrev_b32_e32 v154, 3, v152
	v_lshl_add_u32 v153, v154, 10, v153
	v_lshrrev_b32_e32 v154, 2, v151
	v_lshl_add_u32 v163, v154, 13, v153
	v_and_b32_e32 v154, 3, v151
	v_lshl_add_u32 v159, v154, 12, v153
	v_add_u32_e32 v161, 0x10000, v159
	v_add_u32_e32 v162, 0x14000, v159
	v_xor_b32_e32 v222, 64, v163
	v_xor_b32_e32 v223, 64, v161
	v_xor_b32_e32 v224, 64, v162
	v_add_u32_e32 v225, 0x18000, v159
	v_xor_b32_e32 v226, 64, v225
	v_add_u32_e32 v227, 0x1c000, v159
	v_xor_b32_e32 v228, 64, v227
; #define PG8_STAGE(bufoff, gbase, voff) do { _Pragma("unroll") for (int _i = 0; _i < 2; ++_i) \
;         __builtin_amdgcn_global_load_lds((const unsigned*)((const char*)(gbase) + (voff)[_i]), (PG8_LAS unsigned*)(lds + (bufoff) + ldsw + _i * 8192), 16, 0, 0); } while (0)
; #define PG8_LDA(dst, b, h) do { _Pragma("unroll") for (int m = 0; m < 4; ++m) _Pragma("unroll") for (int k = 0; k < 2; ++k) dst[m][k] = *(const PG8_LAS bf16x8*)(lds + PG8_SA(b, h) + aoff + m * 2048 + k * 1024); } while (0)
; #define PG8_LDB(dst, b, h) do { _Pragma("unroll") for (int n = 0; n < 2; ++n) _Pragma("unroll") for (int k = 0; k < 2; ++k) dst[n][k] = *(const PG8_LAS bf16x8*)(lds + PG8_SB(b, h) + boff + n * 2048 + k * 1024); } while (0)
; #define PG8_MMA(ai, bj, At, Bt) do { __builtin_amdgcn_s_setprio(1); _Pragma("unroll") for (int m = 0; m < 4; ++m) _Pragma("unroll") for (int n = 0; n < 2; ++n) _Pragma("unroll") for (int k = 0; k < 2; ++k) \
;         acc[ai][bj][m][n] = __builtin_amdgcn_mfma_f32_16x16x32_bf16(Bt[n][k], At[m][k], acc[ai][bj][m][n], 0, 0, 0); __builtin_amdgcn_s_setprio(0); } while (0)
; #define PG8_WAIT_V(n) asm volatile("s_waitcnt vmcnt(" #n ")" ::: "memory")
; #define PG8_WAIT_L(n) asm volatile("s_waitcnt lgkmcnt(" #n ")" ::: "memory")
; #define PG8_BAR __builtin_amdgcn_s_barrier()
; #define PG8_SCHED __builtin_amdgcn_sched_barrier(0)
; template <class Epi, class Sched, bool ALIGN_EPI = false, bool SP2 = false>
; __device__ __forceinline__ void gemm_phase(PG8_LAS unsigned char* lds, const Gemm g, const Sched& S, const Epi& E) {
;     ...
;             PG8_LDB(B0, 0, 0); PG8_LDB(B1, 0, 1); PG8_SCHED; PG8_LDA(At, 0, 0); PG8_STAGE(PG8_SA(1, 1), a1 + hstep, voffA);
;             PG8_WAIT_V(8); PG8_WAIT_L(0); PG8_BAR; PG8_MMA(0, 0, At, B0); PG8_MMA(0, 1, At, B1); PG8_BAR; PG8_SCHED;
;             PG8_LDA(At, 0, 1); PG8_STAGE(PG8_SB(0, 0), b2, voffB); PG8_STAGE(PG8_SB(0, 1), b2 + hstep, voffB); PG8_STAGE(PG8_SA(0, 0), a2, voffA);
;             PG8_WAIT_V(8); PG8_WAIT_L(0); PG8_BAR; PG8_MMA(1, 0, At, B0); PG8_MMA(1, 1, At, B1); PG8_BAR; PG8_SCHED;
.LBB0_124:
	ds_read_b128 v[150:153], v161
	ds_read_b128 v[154:157], v223
	ds_read_b128 v[166:169], v161 offset:2048
	ds_read_b128 v[170:173], v223 offset:2048
	ds_read_b128 v[174:177], v162
	ds_read_b128 v[178:181], v224
	ds_read_b128 v[182:185], v162 offset:2048
	ds_read_b128 v[186:189], v224 offset:2048
	s_add_u32 s4, s36, 0xfff80080
	s_addc_u32 s5, s37, -1
	s_cmp_eq_u32 s69, 28
	s_cselect_b32 s41, s9, s5
	s_cselect_b32 s40, s27, s4
	s_cselect_b32 s39, s25, s68
	s_cselect_b32 s38, s35, s67
	s_add_i32 m0, s49, 0xc000
	ds_read_b128 v[190:193], v163
	ds_read_b128 v[194:197], v222
	ds_read_b128 v[198:201], v163 offset:2048
	ds_read_b128 v[202:205], v222 offset:2048
	ds_read_b128 v[206:209], v163 offset:4096
	ds_read_b128 v[210:213], v222 offset:4096
	ds_read_b128 v[214:217], v163 offset:6144
	ds_read_b128 v[218:221], v222 offset:6144
	global_load_lds_dwordx4 v140, s[36:37]
	s_add_i32 m0, s49, 0xe000
	s_nop 0
	global_load_lds_dwordx4 v142, s[36:37]
	s_waitcnt vmcnt(8)
	s_waitcnt lgkmcnt(0)
	s_barrier
	s_setprio 1
	s_waitcnt lgkmcnt(0)
	v_mfma_f32_16x16x32_bf16 v[126:129], v[150:153], v[190:193], v[126:129]
	v_mfma_f32_16x16x32_bf16 v[122:125], v[166:169], v[190:193], v[122:125]
	v_mfma_f32_16x16x32_bf16 v[110:113], v[150:153], v[198:201], v[110:113]
	v_mfma_f32_16x16x32_bf16 v[106:109], v[166:169], v[198:201], v[106:109]
	v_mfma_f32_16x16x32_bf16 v[94:97], v[150:153], v[206:209], v[94:97]
	v_mfma_f32_16x16x32_bf16 v[90:93], v[166:169], v[206:209], v[90:93]
	v_mfma_f32_16x16x32_bf16 v[78:81], v[150:153], v[214:217], v[78:81]
	v_mfma_f32_16x16x32_bf16 v[74:77], v[166:169], v[214:217], v[74:77]
	v_mfma_f32_16x16x32_bf16 v[126:129], v[154:157], v[194:197], v[126:129]
	v_mfma_f32_16x16x32_bf16 v[122:125], v[170:173], v[194:197], v[122:125]
	v_mfma_f32_16x16x32_bf16 v[110:113], v[154:157], v[202:205], v[110:113]
	v_mfma_f32_16x16x32_bf16 v[106:109], v[170:173], v[202:205], v[106:109]
	v_mfma_f32_16x16x32_bf16 v[94:97], v[154:157], v[210:213], v[94:97]
	v_mfma_f32_16x16x32_bf16 v[90:93], v[170:173], v[210:213], v[90:93]
	v_mfma_f32_16x16x32_bf16 v[78:81], v[154:157], v[218:221], v[78:81]
	v_mfma_f32_16x16x32_bf16 v[74:77], v[170:173], v[218:221], v[74:77]
	s_setprio 0
	s_setprio 1
	v_mfma_f32_16x16x32_bf16 v[118:121], v[174:177], v[190:193], v[118:121]
	v_mfma_f32_16x16x32_bf16 v[114:117], v[182:185], v[190:193], v[114:117]
	v_mfma_f32_16x16x32_bf16 v[102:105], v[174:177], v[198:201], v[102:105]
	v_mfma_f32_16x16x32_bf16 v[98:101], v[182:185], v[198:201], v[98:101]
	v_mfma_f32_16x16x32_bf16 v[86:89], v[174:177], v[206:209], v[86:89]
	v_mfma_f32_16x16x32_bf16 v[82:85], v[182:185], v[206:209], v[82:85]
	v_mfma_f32_16x16x32_bf16 v[70:73], v[174:177], v[214:217], v[70:73]
	v_mfma_f32_16x16x32_bf16 v[66:69], v[182:185], v[214:217], v[66:69]
	v_mfma_f32_16x16x32_bf16 v[118:121], v[178:181], v[194:197], v[118:121]
	v_mfma_f32_16x16x32_bf16 v[114:117], v[186:189], v[194:197], v[114:117]
	v_mfma_f32_16x16x32_bf16 v[102:105], v[178:181], v[202:205], v[102:105]
	v_mfma_f32_16x16x32_bf16 v[98:101], v[186:189], v[202:205], v[98:101]
	v_mfma_f32_16x16x32_bf16 v[86:89], v[178:181], v[210:213], v[86:89]
	v_mfma_f32_16x16x32_bf16 v[82:85], v[186:189], v[210:213], v[82:85]
	v_mfma_f32_16x16x32_bf16 v[70:73], v[178:181], v[218:221], v[70:73]
	v_mfma_f32_16x16x32_bf16 v[66:69], v[186:189], v[218:221], v[66:69]
	s_setprio 0
	s_barrier
	s_add_i32 s4, s64, s48
	s_mov_b32 m0, s4
	ds_read_b128 v[190:193], v163 offset:16384
	ds_read_b128 v[194:197], v222 offset:16384
	ds_read_b128 v[198:201], v163 offset:18432
	ds_read_b128 v[202:205], v222 offset:18432
	ds_read_b128 v[206:209], v163 offset:20480
	ds_read_b128 v[210:213], v222 offset:20480
	ds_read_b128 v[214:217], v163 offset:22528
	ds_read_b128 v[218:221], v222 offset:22528
	global_load_lds_dwordx4 v132, s[38:39]
	s_add_i32 m0, s4, 0x2000
	s_add_u32 s70, s38, 0x80000
	s_addc_u32 s71, s39, 0
	s_add_i32 s4, s65, s48
	global_load_lds_dwordx4 v136, s[38:39]
	s_mov_b32 m0, s4
	s_nop 0
	global_load_lds_dwordx4 v132, s[70:71]
	s_add_i32 m0, s4, 0x2000
	s_nop 0
	global_load_lds_dwordx4 v136, s[70:71]
	s_waitcnt vmcnt(6)
	s_waitcnt lgkmcnt(0)
	s_barrier
	s_setprio 1
	s_waitcnt lgkmcnt(0)
	v_mfma_f32_16x16x32_bf16 v[62:65], v[150:153], v[190:193], v[62:65]
	v_mfma_f32_16x16x32_bf16 v[58:61], v[166:169], v[190:193], v[58:61]
	v_mfma_f32_16x16x32_bf16 v[46:49], v[150:153], v[198:201], v[46:49]
	v_mfma_f32_16x16x32_bf16 v[42:45], v[166:169], v[198:201], v[42:45]
	v_mfma_f32_16x16x32_bf16 v[30:33], v[150:153], v[206:209], v[30:33]
	v_mfma_f32_16x16x32_bf16 v[26:29], v[166:169], v[206:209], v[26:29]
	v_mfma_f32_16x16x32_bf16 v[14:17], v[150:153], v[214:217], v[14:17]
	v_mfma_f32_16x16x32_bf16 v[10:13], v[166:169], v[214:217], v[10:13]
	v_mfma_f32_16x16x32_bf16 v[62:65], v[154:157], v[194:197], v[62:65]
	v_mfma_f32_16x16x32_bf16 v[58:61], v[170:173], v[194:197], v[58:61]
	v_mfma_f32_16x16x32_bf16 v[46:49], v[154:157], v[202:205], v[46:49]
	v_mfma_f32_16x16x32_bf16 v[42:45], v[170:173], v[202:205], v[42:45]
	v_mfma_f32_16x16x32_bf16 v[30:33], v[154:157], v[210:213], v[30:33]
	v_mfma_f32_16x16x32_bf16 v[26:29], v[170:173], v[210:213], v[26:29]
	v_mfma_f32_16x16x32_bf16 v[14:17], v[154:157], v[218:221], v[14:17]
	v_mfma_f32_16x16x32_bf16 v[10:13], v[170:173], v[218:221], v[10:13]
	s_setprio 0
	s_setprio 1
	v_mfma_f32_16x16x32_bf16 v[54:57], v[174:177], v[190:193], v[54:57]
	v_mfma_f32_16x16x32_bf16 v[50:53], v[182:185], v[190:193], v[50:53]
	v_mfma_f32_16x16x32_bf16 v[38:41], v[174:177], v[198:201], v[38:41]
	v_mfma_f32_16x16x32_bf16 v[34:37], v[182:185], v[198:201], v[34:37]
	v_mfma_f32_16x16x32_bf16 v[22:25], v[174:177], v[206:209], v[22:25]
	v_mfma_f32_16x16x32_bf16 v[18:21], v[182:185], v[206:209], v[18:21]
	v_mfma_f32_16x16x32_bf16 v[6:9], v[174:177], v[214:217], v[6:9]
	v_mfma_f32_16x16x32_bf16 v[2:5], v[182:185], v[214:217], v[2:5]
	v_mfma_f32_16x16x32_bf16 v[54:57], v[178:181], v[194:197], v[54:57]
	v_mfma_f32_16x16x32_bf16 v[50:53], v[186:189], v[194:197], v[50:53]
	v_mfma_f32_16x16x32_bf16 v[38:41], v[178:181], v[202:205], v[38:41]
	v_mfma_f32_16x16x32_bf16 v[34:37], v[186:189], v[202:205], v[34:37]
	v_mfma_f32_16x16x32_bf16 v[22:25], v[178:181], v[210:213], v[22:25]
	v_mfma_f32_16x16x32_bf16 v[18:21], v[186:189], v[210:213], v[18:21]
	v_mfma_f32_16x16x32_bf16 v[6:9], v[178:181], v[218:221], v[6:9]
	v_mfma_f32_16x16x32_bf16 v[2:5], v[186:189], v[218:221], v[2:5]
	s_setprio 0
	s_barrier
; #define PG8_STAGE(bufoff, gbase, voff) do { _Pragma("unroll") for (int _i = 0; _i < 2; ++_i) \
;         __builtin_amdgcn_global_load_lds((const unsigned*)((const char*)(gbase) + (voff)[_i]), (PG8_LAS unsigned*)(lds + (bufoff) + ldsw + _i * 8192), 16, 0, 0); } while (0)
; #define PG8_LDA(dst, b, h) do { _Pragma("unroll") for (int m = 0; m < 4; ++m) _Pragma("unroll") for (int k = 0; k < 2; ++k) dst[m][k] = *(const PG8_LAS bf16x8*)(lds + PG8_SA(b, h) + aoff + m * 2048 + k * 1024); } while (0)
; #define PG8_LDB(dst, b, h) do { _Pragma("unroll") for (int n = 0; n < 2; ++n) _Pragma("unroll") for (int k = 0; k < 2; ++k) dst[n][k] = *(const PG8_LAS bf16x8*)(lds + PG8_SB(b, h) + boff + n * 2048 + k * 1024); } while (0)
; #define PG8_MMA(ai, bj, At, Bt) do { __builtin_amdgcn_s_setprio(1); _Pragma("unroll") for (int m = 0; m < 4; ++m) _Pragma("unroll") for (int n = 0; n < 2; ++n) _Pragma("unroll") for (int k = 0; k < 2; ++k) \
;         acc[ai][bj][m][n] = __builtin_amdgcn_mfma_f32_16x16x32_bf16(Bt[n][k], At[m][k], acc[ai][bj][m][n], 0, 0, 0); __builtin_amdgcn_s_setprio(0); } while (0)
; #define PG8_WAIT_V(n) asm volatile("s_waitcnt vmcnt(" #n ")" ::: "memory")
; #define PG8_WAIT_L(n) asm volatile("s_waitcnt lgkmcnt(" #n ")" ::: "memory")
; #define PG8_BAR __builtin_amdgcn_s_barrier()
; #define PG8_SCHED __builtin_amdgcn_sched_barrier(0)
; template <class Epi, class Sched, bool ALIGN_EPI = false, bool SP2 = false>
; __device__ __forceinline__ void gemm_phase(PG8_LAS unsigned char* lds, const Gemm g, const Sched& S, const Epi& E) {
;     ...
;             PG8_LDB(B0, 1, 0); PG8_LDB(B1, 1, 1); PG8_SCHED; PG8_LDA(At, 1, 0); PG8_STAGE(PG8_SA(0, 1), a2 + hstep, voffA);
;             PG8_WAIT_V(8); PG8_WAIT_L(0); PG8_BAR; PG8_MMA(0, 0, At, B0); PG8_MMA(0, 1, At, B1); PG8_BAR; PG8_SCHED;
;             PG8_LDA(At, 1, 1); PG8_STAGE(PG8_SB(1, 0), b3, voffB); PG8_STAGE(PG8_SB(1, 1), b3 + hstep, voffB); PG8_STAGE(PG8_SA(1, 0), a3, voffA);
;             PG8_WAIT_V(8); PG8_WAIT_L(0); PG8_BAR; PG8_MMA(1, 0, At, B0); PG8_MMA(1, 1, At, B1); PG8_BAR; PG8_SCHED;
	s_add_i32 s4, 0, 0x18000
	s_add_i32 s5, 0, 0x1c000
	ds_read_b128 v[150:153], v225
	ds_read_b128 v[154:157], v226
	ds_read_b128 v[166:169], v225 offset:2048
	ds_read_b128 v[170:173], v226 offset:2048
	ds_read_b128 v[174:177], v227
	ds_read_b128 v[178:181], v228
	ds_read_b128 v[182:185], v227 offset:2048
	ds_read_b128 v[186:189], v228 offset:2048
	s_add_u32 s70, s40, 0x80000
	s_addc_u32 s71, s41, 0
	s_mov_b32 m0, s49
	s_nop 0
	global_load_lds_dwordx4 v130, s[40:41]
	s_mov_b32 m0, s50
	s_nop 0
	global_load_lds_dwordx4 v134, s[40:41]
	s_mov_b32 m0, s51
	ds_read_b128 v[190:193], v163 offset:32768
	ds_read_b128 v[194:197], v222 offset:32768
	ds_read_b128 v[198:201], v163 offset:34816
	ds_read_b128 v[202:205], v222 offset:34816
	ds_read_b128 v[206:209], v163 offset:36864
	ds_read_b128 v[210:213], v222 offset:36864
	ds_read_b128 v[214:217], v163 offset:38912
	ds_read_b128 v[218:221], v222 offset:38912
	global_load_lds_dwordx4 v130, s[70:71]
	s_mov_b32 m0, s52
	s_nop 0
	global_load_lds_dwordx4 v134, s[70:71]
	s_waitcnt vmcnt(8)
	s_waitcnt lgkmcnt(0)
	s_barrier
	s_setprio 1
	s_waitcnt lgkmcnt(0)
	v_mfma_f32_16x16x32_bf16 v[126:129], v[150:153], v[190:193], v[126:129]
	v_mfma_f32_16x16x32_bf16 v[122:125], v[166:169], v[190:193], v[122:125]
	v_mfma_f32_16x16x32_bf16 v[110:113], v[150:153], v[198:201], v[110:113]
	v_mfma_f32_16x16x32_bf16 v[106:109], v[166:169], v[198:201], v[106:109]
	v_mfma_f32_16x16x32_bf16 v[94:97], v[150:153], v[206:209], v[94:97]
	v_mfma_f32_16x16x32_bf16 v[90:93], v[166:169], v[206:209], v[90:93]
	v_mfma_f32_16x16x32_bf16 v[78:81], v[150:153], v[214:217], v[78:81]
	v_mfma_f32_16x16x32_bf16 v[74:77], v[166:169], v[214:217], v[74:77]
	v_mfma_f32_16x16x32_bf16 v[126:129], v[154:157], v[194:197], v[126:129]
	v_mfma_f32_16x16x32_bf16 v[122:125], v[170:173], v[194:197], v[122:125]
	v_mfma_f32_16x16x32_bf16 v[110:113], v[154:157], v[202:205], v[110:113]
	v_mfma_f32_16x16x32_bf16 v[106:109], v[170:173], v[202:205], v[106:109]
	v_mfma_f32_16x16x32_bf16 v[94:97], v[154:157], v[210:213], v[94:97]
	v_mfma_f32_16x16x32_bf16 v[90:93], v[170:173], v[210:213], v[90:93]
	v_mfma_f32_16x16x32_bf16 v[78:81], v[154:157], v[218:221], v[78:81]
	v_mfma_f32_16x16x32_bf16 v[74:77], v[170:173], v[218:221], v[74:77]
	s_setprio 0
	s_setprio 1
	v_mfma_f32_16x16x32_bf16 v[118:121], v[174:177], v[190:193], v[118:121]
	v_mfma_f32_16x16x32_bf16 v[114:117], v[182:185], v[190:193], v[114:117]
	v_mfma_f32_16x16x32_bf16 v[102:105], v[174:177], v[198:201], v[102:105]
	v_mfma_f32_16x16x32_bf16 v[98:101], v[182:185], v[198:201], v[98:101]
	v_mfma_f32_16x16x32_bf16 v[86:89], v[174:177], v[206:209], v[86:89]
	v_mfma_f32_16x16x32_bf16 v[82:85], v[182:185], v[206:209], v[82:85]
	v_mfma_f32_16x16x32_bf16 v[70:73], v[174:177], v[214:217], v[70:73]
	v_mfma_f32_16x16x32_bf16 v[66:69], v[182:185], v[214:217], v[66:69]
	v_mfma_f32_16x16x32_bf16 v[118:121], v[178:181], v[194:197], v[118:121]
	v_mfma_f32_16x16x32_bf16 v[114:117], v[186:189], v[194:197], v[114:117]
	v_mfma_f32_16x16x32_bf16 v[102:105], v[178:181], v[202:205], v[102:105]
	v_mfma_f32_16x16x32_bf16 v[98:101], v[186:189], v[202:205], v[98:101]
	v_mfma_f32_16x16x32_bf16 v[86:89], v[178:181], v[210:213], v[86:89]
	v_mfma_f32_16x16x32_bf16 v[82:85], v[186:189], v[210:213], v[82:85]
	v_mfma_f32_16x16x32_bf16 v[70:73], v[178:181], v[218:221], v[70:73]
	v_mfma_f32_16x16x32_bf16 v[66:69], v[186:189], v[218:221], v[66:69]
	s_setprio 0
	s_barrier
	s_add_i32 s4, s4, s48
	s_add_i32 m0, s4, 0xffffff80
	ds_read_b128 v[190:193], v163 offset:49152
	ds_read_b128 v[194:197], v222 offset:49152
	ds_read_b128 v[198:201], v163 offset:51200
	ds_read_b128 v[202:205], v222 offset:51200
	ds_read_b128 v[206:209], v163 offset:53248
	ds_read_b128 v[210:213], v222 offset:53248
	ds_read_b128 v[214:217], v163 offset:55296
	ds_read_b128 v[218:221], v222 offset:55296
	global_load_lds_dwordx4 v132, s[38:39] offset:128
	s_add_i32 m0, s4, 0x1f80
	s_nop 0
	global_load_lds_dwordx4 v136, s[38:39] offset:128
	s_add_u32 s38, s38, 0x80080
	s_addc_u32 s39, s39, 0
	s_add_i32 s4, s5, s48
	s_mov_b32 m0, s4
	s_nop 0
	global_load_lds_dwordx4 v132, s[38:39]
	s_add_i32 m0, s4, 0x2000
	s_nop 0
	global_load_lds_dwordx4 v136, s[38:39]
	s_add_i32 m0, s58, 0xffffff80
	s_nop 0
	global_load_lds_dwordx4 v130, s[40:41] offset:128
	s_add_i32 m0, s59, 0xffffff80
	s_nop 0
	global_load_lds_dwordx4 v134, s[40:41] offset:128
	s_waitcnt vmcnt(8)
	s_waitcnt lgkmcnt(0)
	s_barrier
	s_setprio 1
	s_waitcnt lgkmcnt(0)
	v_mfma_f32_16x16x32_bf16 v[62:65], v[150:153], v[190:193], v[62:65]
	v_mfma_f32_16x16x32_bf16 v[58:61], v[166:169], v[190:193], v[58:61]
	v_mfma_f32_16x16x32_bf16 v[46:49], v[150:153], v[198:201], v[46:49]
	v_mfma_f32_16x16x32_bf16 v[42:45], v[166:169], v[198:201], v[42:45]
	v_mfma_f32_16x16x32_bf16 v[30:33], v[150:153], v[206:209], v[30:33]
	v_mfma_f32_16x16x32_bf16 v[26:29], v[166:169], v[206:209], v[26:29]
	v_mfma_f32_16x16x32_bf16 v[14:17], v[150:153], v[214:217], v[14:17]
	v_mfma_f32_16x16x32_bf16 v[10:13], v[166:169], v[214:217], v[10:13]
	v_mfma_f32_16x16x32_bf16 v[62:65], v[154:157], v[194:197], v[62:65]
	v_mfma_f32_16x16x32_bf16 v[58:61], v[170:173], v[194:197], v[58:61]
	v_mfma_f32_16x16x32_bf16 v[46:49], v[154:157], v[202:205], v[46:49]
	v_mfma_f32_16x16x32_bf16 v[42:45], v[170:173], v[202:205], v[42:45]
	v_mfma_f32_16x16x32_bf16 v[30:33], v[154:157], v[210:213], v[30:33]
	v_mfma_f32_16x16x32_bf16 v[26:29], v[170:173], v[210:213], v[26:29]
	v_mfma_f32_16x16x32_bf16 v[14:17], v[154:157], v[218:221], v[14:17]
	v_mfma_f32_16x16x32_bf16 v[10:13], v[170:173], v[218:221], v[10:13]
	s_setprio 0
	s_setprio 1
	v_mfma_f32_16x16x32_bf16 v[54:57], v[174:177], v[190:193], v[54:57]
	v_mfma_f32_16x16x32_bf16 v[50:53], v[182:185], v[190:193], v[50:53]
	v_mfma_f32_16x16x32_bf16 v[38:41], v[174:177], v[198:201], v[38:41]
	v_mfma_f32_16x16x32_bf16 v[34:37], v[182:185], v[198:201], v[34:37]
	v_mfma_f32_16x16x32_bf16 v[22:25], v[174:177], v[206:209], v[22:25]
	v_mfma_f32_16x16x32_bf16 v[18:21], v[182:185], v[206:209], v[18:21]
	v_mfma_f32_16x16x32_bf16 v[6:9], v[174:177], v[214:217], v[6:9]
	v_mfma_f32_16x16x32_bf16 v[2:5], v[182:185], v[214:217], v[2:5]
	v_mfma_f32_16x16x32_bf16 v[54:57], v[178:181], v[194:197], v[54:57]
	v_mfma_f32_16x16x32_bf16 v[50:53], v[186:189], v[194:197], v[50:53]
	v_mfma_f32_16x16x32_bf16 v[38:41], v[178:181], v[202:205], v[38:41]
	v_mfma_f32_16x16x32_bf16 v[34:37], v[186:189], v[202:205], v[34:37]
	v_mfma_f32_16x16x32_bf16 v[22:25], v[178:181], v[210:213], v[22:25]
	v_mfma_f32_16x16x32_bf16 v[18:21], v[186:189], v[210:213], v[18:21]
	v_mfma_f32_16x16x32_bf16 v[6:9], v[178:181], v[218:221], v[6:9]
	v_mfma_f32_16x16x32_bf16 v[2:5], v[186:189], v[218:221], v[2:5]
	s_setprio 0
	s_barrier
	s_add_i32 s69, s69, 2
	s_add_u32 s36, s36, 0x100
	s_addc_u32 s37, s37, 0
	s_add_u32 s67, s67, 0x100
	s_addc_u32 s68, s68, 0
	s_cmp_gt_u32 s69, 29
	s_cbranch_scc0 .LBB0_124
	s_and_b64 vcc, exec, s[22:23]
	s_cbranch_vccz .LBB0_127
	s_barrier

; #define PG8_STAGE(bufoff, gbase, voff) do { _Pragma("unroll") for (int _i = 0; _i < 2; ++_i) \
;         __builtin_amdgcn_global_load_lds((const unsigned*)((const char*)(gbase) + (voff)[_i]), (PG8_LAS unsigned*)(lds + (bufoff) + ldsw + _i * 8192), 16, 0, 0); } while (0)
; #define PG8_BAR __builtin_amdgcn_s_barrier()
; template <class Epi, class Sched, bool ALIGN_EPI = false, bool SP2 = false>
; __device__ __forceinline__ void gemm_phase(PG8_LAS unsigned char* lds, const Gemm g, const Sched& S, const Epi& E) {
;     ...
;     for (int i = 0; i < 2; ++i) { int R, C; stage_rc(tid * 16 + i * 8192, R, C); const int Rb = Epi::PERM ? ((R & ~31) + perm32(R & 31)) : R;
;         voffA[i] = (unsigned)(R * K + C) * 2u; voffB[i] = (unsigned)(Rb * K + C) * 2u; }
;     ...
;     const char* cA = (const char*)g.A + (size_t)cur.pm * tstep; const char* cB = (const char*)g.Bt + (size_t)cur.pn * tstep;
;     S.a_ready(cur);
;     if constexpr (SP2) {
;         PG8_STAGE(PG8_SB(0, 0), cB, voffB); PG8_STAGE(PG8_SB(0, 1), cB + hstep, voffB); PG8_STAGE(PG8_SA(0, 0), cA, voffA); PG8_STAGE(PG8_SA(0, 1), cA + hstep, voffA);
;         if (wr == 1) PG8_BAR;
.LBB0_751:
	v_ashrrev_i32_e32 v2, 31, v10
	v_lshrrev_b32_e32 v2, 26, v2
	v_add_u32_e32 v2, v10, v2
	v_ashrrev_i32_e32 v11, 6, v2
	v_bfe_i32 v2, v10, 27, 1
	v_lshlrev_b32_e32 v1, 4, v10
	v_lshrrev_b32_e32 v2, 22, v2
	v_add_u32_e32 v2, v1, v2
	v_and_b32_e32 v2, 0xfffffc00, v2
	v_sub_u32_e32 v2, v1, v2
	v_lshrrev_b32_e32 v3, 4, v2
	v_bitop3_b32 v2, v3, v2, 32 bitop3:0x6c
	v_ashrrev_i32_e32 v4, 31, v2
	v_lshrrev_b32_e32 v4, 26, v4
	v_add_u32_e32 v4, v2, v4
	v_lshlrev_b32_e32 v3, 3, v11
	v_ashrrev_i32_e32 v12, 6, v4
	v_and_b32_e32 v4, 0xc0, v4
	v_and_b32_e32 v3, -16, v3
	v_sub_u32_e32 v2, v2, v4
	v_mov_b32_e32 v4, 1
	v_add_u32_e32 v3, v12, v3
	v_ashrrev_i16_sdwa v2, v4, sext(v2) dst_sel:DWORD dst_unused:UNUSED_PAD src0_sel:DWORD src1_sel:BYTE_0
	s_waitcnt lgkmcnt(0)
	v_lshlrev_b32_e32 v5, 5, v11
	v_bfe_i32 v13, v2, 0, 16
	v_lshlrev_b32_e32 v2, 1, v3
	v_lshrrev_b32_e32 v6, 2, v3
	v_and_b32_e32 v7, 3, v12
	s_mov_b32 s5, 0xfffe0
	v_and_b32_e32 v5, 32, v5
	v_and_b32_e32 v2, 24, v2
	v_and_b32_e32 v6, 4, v6
	v_and_or_b32 v7, v3, s5, v7
	v_or3_b32 v2, v7, v6, v2
	v_add_lshl_u32 v5, v5, v13, 1
	v_add_u32_e32 v1, 0x2000, v1
	v_and_b32_e32 v158, 63, v0
	v_lshrrev_b32_e32 v159, 6, v0
	v_lshrrev_b32_e32 v160, 3, v158
	v_lshl_add_u32 v160, v159, 3, v160
	v_and_b32_e32 v161, 1, v159
	v_lshrrev_b32_e32 v162, 4, v158
	v_lshl_add_u32 v161, v161, 2, v162
	v_and_b32_e32 v162, 7, v158
	v_xor_b32_e32 v161, v161, v162
	v_lshlrev_b32_e32 v161, 4, v161
	v_mul_u32_u24_e32 v162, 0x1000, v160
	v_add_u32_e32 v154, v162, v161
	v_add_u32_e32 v155, 0x40000, v154
	v_and_b32_e32 v162, 31, v160
	v_bfe_u32 v163, v162, 2, 2
	v_lshlrev_b32_e32 v163, 3, v163
	v_lshrrev_b32_e32 v158, 4, v162
	v_lshl_add_u32 v163, v158, 2, v163
	v_and_b32_e32 v158, 3, v162
	v_add_u32_e32 v163, v163, v158
	v_and_b32_e32 v158, -32, v160
	v_add_u32_e32 v163, v163, v158
	v_mul_u32_u24_e32 v163, 0x1000, v163
	v_add_u32_e32 v156, v163, v161
	v_add_u32_e32 v157, 0x40000, v156
	v_mov_b32_e32 v132, v156
	v_ashrrev_i32_e32 v2, 31, v1
	v_lshrrev_b32_e32 v2, 22, v2
	v_add_u32_e32 v2, v1, v2
	v_ashrrev_i32_e32 v14, 10, v2
	v_mul_i32_i24_e32 v2, 0x400, v14
	v_sub_u32_e32 v1, v1, v2
	v_lshrrev_b32_e32 v2, 4, v1
	v_bitop3_b32 v1, v2, v1, 32 bitop3:0x6c
	v_mov_b32_e32 v130, v154
	v_ashrrev_i32_e32 v3, 31, v1
	v_lshrrev_b32_e32 v3, 26, v3
	v_add_u32_e32 v3, v1, v3
	s_ashr_i32 s4, s13, 3
	v_lshlrev_b32_e32 v2, 3, v14
	v_ashrrev_i32_e32 v15, 6, v3
	v_and_b32_e32 v3, 0xc0, v3
	s_add_u32 s52, s42, 0x2400000
	v_and_b32_e32 v2, -16, v2
	v_sub_u32_e32 v1, v1, v3
	s_addc_u32 s53, s43, 0
	v_add_u32_e32 v2, v15, v2
	v_ashrrev_i16_sdwa v1, v4, sext(v1) dst_sel:DWORD dst_unused:UNUSED_PAD src0_sel:DWORD src1_sel:BYTE_0
	v_and_b32_e32 v4, 3, v15
	s_add_i32 s4, s12, s4
	v_and_or_b32 v4, v2, s5, v4
	s_ashr_i32 s5, s4, 31
	s_lshr_b32 s5, s5, 26
	s_add_i32 s5, s4, s5
	s_ashr_i32 s6, s5, 6
	s_andn2_b32 s5, s5, 63
	s_sub_i32 s4, s4, s5
	s_bfe_i32 s5, s4, 0x80000
	s_bfe_u32 s5, s5, 0x3000c
	s_add_i32 s5, s4, s5
	s_lshl_b32 s12, s6, 3
	s_bfe_i32 s6, s5, 0x80000
	s_and_b32 s5, s5, 0xf8
	s_sub_i32 s4, s4, s5
	s_sext_i32_i16 s6, s6
	s_sext_i32_i8 s4, s4
	s_ashr_i32 s7, s20, 6
	s_lshr_b32 s6, s6, 3
	s_add_i32 s38, s12, s4
	s_ashr_i32 s39, s38, 31
	s_bfe_i64 s[12:13], s[6:7], 0x100000
	s_ashr_i32 s21, s20, 8
	s_lshl_b32 s58, s7, 10
	s_lshl_b64 s[4:5], s[38:39], 20
	s_lshl_b64 s[12:13], s[12:13], 20
	s_add_u32 s48, s52, s12
	v_lshlrev_b32_e32 v5, 5, v14
	v_bfe_i32 v16, v1, 0, 16
	v_lshlrev_b32_e32 v1, 1, v2
	v_lshrrev_b32_e32 v3, 2, v2
	s_addc_u32 s49, s53, s13
	s_add_i32 s39, s58, 0
	v_and_b32_e32 v5, 32, v5
	v_and_b32_e32 v1, 24, v1
	v_and_b32_e32 v3, 4, v3
	s_add_i32 m0, s39, 0x10000
	v_or3_b32 v1, v4, v3, v1
	v_add_lshl_u32 v3, v5, v16, 1
	global_load_lds_dwordx4 v132, s[48:49]
	s_add_i32 m0, s39, 0x12000
	v_mov_b32_e32 v136, v157
	s_add_u32 s12, s48, 0x80000
	global_load_lds_dwordx4 v136, s[48:49]
	s_addc_u32 s13, s49, 0
	s_add_i32 m0, s39, 0x14000
	v_mov_b32_e32 v134, v155
	global_load_lds_dwordx4 v132, s[12:13]
	s_add_i32 m0, s39, 0x16000
	s_add_u32 s40, s10, s4
	s_addc_u32 s41, s11, s5
	s_add_i32 s59, s39, 0x2000
	global_load_lds_dwordx4 v136, s[12:13]
	s_mov_b32 m0, s39
	s_add_u32 s4, s40, 0x80000
	global_load_lds_dwordx4 v130, s[40:41]
	s_mov_b32 m0, s59
	s_addc_u32 s5, s41, 0
	s_add_i32 s60, s39, 0x4000
	global_load_lds_dwordx4 v134, s[40:41]
	s_mov_b32 m0, s60
	s_add_i32 s61, s39, 0x6000
	global_load_lds_dwordx4 v130, s[4:5]
	s_mov_b32 m0, s61
	v_mov_b32_e32 v133, 0
	global_load_lds_dwordx4 v134, s[4:5]
	v_mov_b32_e32 v137, v133
	v_mov_b32_e32 v131, v133
	v_mov_b32_e32 v135, v133
	s_cmp_eq_u32 s21, 1
	s_mov_b32 s62, 0
	v_lshl_add_u64 v[8:9], s[48:49], 0, v[132:133]
	v_lshl_add_u64 v[4:5], s[48:49], 0, v[136:137]
	s_mov_b64 s[12:13], 0x80000
	v_lshl_add_u64 v[2:3], s[40:41], 0, v[130:131]
	s_cselect_b64 s[14:15], -1, 0
	s_cmp_lg_u32 s21, 1
	v_lshl_add_u64 v[6:7], s[40:41], 0, v[134:135]
	s_cbranch_scc1 .LBB0_753
	s_barrier
; #define PG8_STAGE(bufoff, gbase, voff) do { _Pragma("unroll") for (int _i = 0; _i < 2; ++_i) \
;         __builtin_amdgcn_global_load_lds((const unsigned*)((const char*)(gbase) + (voff)[_i]), (PG8_LAS unsigned*)(lds + (bufoff) + ldsw + _i * 8192), 16, 0, 0); } while (0)
; #define PG8_WAIT_V(n) asm volatile("s_waitcnt vmcnt(" #n ")" ::: "memory")
; #define PG8_BAR __builtin_amdgcn_s_barrier()
; template <class Epi, class Sched, bool ALIGN_EPI = false, bool SP2 = false>
; __device__ __forceinline__ void gemm_phase(PG8_LAS unsigned char* lds, const Gemm g, const Sched& S, const Epi& E) {
;     ...
;     const int aoff = lds_byte(wr * 64 + fr, fq * 8), boff = lds_byte(wc * 32 + fr, fq * 8);
;     ...
;         PG8_WAIT_V(2); PG8_BAR;
;         PG8_STAGE(PG8_SB(1, 0), cB + kstep, voffB); PG8_STAGE(PG8_SA(1, 0), cA + kstep, voffA); PG8_STAGE(PG8_SB(1, 1), cB + hstep + kstep, voffB);
;         PG8_WAIT_V(6); PG8_BAR;
.LBB0_753:
	s_add_u32 s16, s42, 0x16e00000
	s_addc_u32 s17, s43, 0
	s_lshl_b32 s4, s7, 5
	s_mov_b64 s[18:19], 0x80
	s_and_b32 s7, s4, 0x60
	s_add_i32 m0, s39, 0x18000
	v_lshl_add_u64 v[8:9], v[8:9], 0, s[18:19]
	s_lshl_b32 s22, s21, 13
	s_lshl_b32 s23, s7, 7
	s_waitcnt vmcnt(2)
	s_barrier
	global_load_lds_dwordx4 v[8:9], off
	v_lshl_add_u64 v[4:5], v[4:5], 0, s[18:19]
	s_add_i32 m0, s39, 0x1a000
	s_add_i32 s63, s39, 0x8000
	s_add_i32 s64, s39, 0xa000
	global_load_lds_dwordx4 v[4:5], off
	v_lshl_add_u64 v[2:3], v[2:3], 0, s[18:19]
	s_mov_b32 m0, s63
	s_add_u32 s4, s48, 0x80080
	global_load_lds_dwordx4 v[2:3], off
	v_lshl_add_u64 v[2:3], v[6:7], 0, s[18:19]
	s_mov_b32 m0, s64
	s_addc_u32 s5, s49, 0
	global_load_lds_dwordx4 v[2:3], off
	s_add_i32 m0, s39, 0x1c000
	v_lshl_add_u64 v[2:3], s[4:5], 0, v[132:133]
	global_load_lds_dwordx4 v[2:3], off
	v_lshl_add_u64 v[2:3], s[4:5], 0, v[136:137]
	s_add_i32 m0, s39, 0x1e000
	s_cmpk_lt_u32 s20, 0x100
	global_load_lds_dwordx4 v[2:3], off
	v_lshrrev_b32_e32 v3, 1, v10
	v_and_b32_e32 v3, 24, v3
	v_and_b32_e32 v2, 15, v10
	v_lshlrev_b32_e32 v4, 1, v3
	v_lshl_or_b32 v1, s21, 6, v2
	v_lshl_or_b32 v2, v2, 6, v4
	v_lshlrev_b32_e32 v4, 2, v10
	v_and_b32_e32 v4, 32, v4
	v_bitop3_b32 v5, v2, s22, v4 bitop3:0xde
	v_bitop3_b32 v148, v2, s23, v4 bitop3:0xde
	v_lshlrev_b32_e32 v2, 15, v11
	v_and_b32_e32 v2, 0xffff0000, v2
	v_or_b32_e32 v149, s7, v3
	v_lshl_add_u32 v2, v12, 12, v2
	v_and_b32_e32 v3, 1, v11
	v_lshl_or_b32 v2, v3, 6, v2
	v_lshl_add_u32 v138, v13, 1, v2
	v_lshlrev_b32_e32 v2, 15, v14
	v_and_b32_e32 v2, 0xffff0000, v2
	s_waitcnt vmcnt(6)
	v_lshl_add_u32 v2, v15, 12, v2
	v_and_b32_e32 v3, 1, v14
	s_cselect_b64 s[20:21], -1, 0
	v_lshl_or_b32 v2, v3, 6, v2
	s_add_i32 s67, 0, 0x10000
	s_add_i32 s68, 0, 0x14000
	s_sext_i32_i8 s73, s6
	s_ashr_i32 s65, s46, 31
	s_mov_b32 s66, s46
	v_mov_b32_e32 v139, v133
	v_lshl_add_u32 v140, v16, 1, v2
	v_and_b32_e32 v158, 63, v0
	v_lshrrev_b32_e32 v159, 6, v0
	v_lshrrev_b32_e32 v160, 1, v159
	v_lshrrev_b32_e32 v161, 2, v158
	v_lshl_add_u32 v160, v160, 4, v161
	v_and_b32_e32 v161, 3, v158
	v_lshlrev_b32_e32 v161, 4, v161
	v_bfe_u32 v162, v158, 5, 1
	v_lshlrev_b32_e32 v162, 5, v162
	v_xor_b32_e32 v161, v161, v162
	v_and_b32_e32 v162, 1, v159
	v_lshl_add_u32 v161, v162, 6, v161
	v_mul_u32_u24_e32 v160, 0x1000, v160
	v_add_u32_e32 v160, v160, v161
	v_sub_u32_e32 v160, v130, v160
	v_add_u32_e32 v138, v138, v160
	v_add_u32_e32 v140, v140, v160
	v_mov_b32_e32 v141, v133
	v_mov_b64_e32 v[142:143], 0x200
	v_mov_b64_e32 v[144:145], 0x1ff
	v_add_u32_e32 v150, s67, v148
	v_add_u32_e32 v151, s68, v148
	v_add_u32_e32 v152, 0, v5
	s_mov_b32 s69, 0x80000
	s_mov_b64 s[22:23], 0x90000
	s_mov_b32 s70, 0x90000
	s_mov_b64 s[24:25], 0xa0000
	s_mov_b32 s71, 0xa0000
	s_mov_b64 s[26:27], 0xb0000
	s_mov_b32 s72, 0xb0000
	s_barrier
	s_branch .LBB0_756

; template <class Epi, class Sched, bool ALIGN_EPI = false, bool SP2 = false>
; __device__ __forceinline__ void gemm_phase(PG8_LAS unsigned char* lds, const Gemm g, const Sched& S, const Epi& E) {
;     ...
;     const int aoff = lds_byte(wr * 64 + fr, fq * 8), boff = lds_byte(wc * 32 + fr, fq * 8);
;     ...
; #pragma unroll
;         for (int a = 0; a < 2; ++a)
; #pragma unroll
;             for (int b = 0; b < 2; ++b)
; #pragma unroll
;                 for (int m = 0; m < 4; ++m)
; #pragma unroll
;                     for (int n = 0; n < 2; ++n) acc[a][b][m][n] = (f32x4){0.f, 0.f, 0.f, 0.f};
;         cur = nxt; cA = nA; cB = nB; ++ui;
.LBB0_762:
	s_ashr_i32 s31, s30, 31
	s_lshl_b64 s[4:5], s[30:31], 20
	s_add_u32 s34, s10, s4
	s_addc_u32 s35, s11, s5
	s_and_b64 s[4:5], s[6:7], exec
	s_cselect_b32 s31, s35, s41
	s_cselect_b32 s74, s34, s40
	s_ashr_i32 s29, s28, 31
	s_lshl_b64 s[4:5], s[28:29], 20
	s_add_u32 s36, s52, s4
	s_addc_u32 s37, s53, s5
	s_and_b64 s[4:5], s[6:7], exec
	s_cselect_b32 s29, s37, s49
	s_cselect_b32 s75, s36, s48
	s_add_u32 s40, s40, 0x80080
	s_addc_u32 s41, s41, 0
	s_add_u32 s76, s48, 0x100
	v_mov_b32_e32 v2, 0
	s_addc_u32 s77, s49, 0
	s_mov_b32 s78, -2
	v_mov_b32_e32 v3, v2
	v_mov_b32_e32 v4, v2
	v_mov_b32_e32 v5, v2
	v_mov_b32_e32 v6, v2
	v_mov_b32_e32 v7, v2
	v_mov_b32_e32 v8, v2
	v_mov_b32_e32 v9, v2
	v_mov_b32_e32 v14, v2
	v_mov_b32_e32 v15, v2
	v_mov_b32_e32 v16, v2
	v_mov_b32_e32 v17, v2
	v_mov_b32_e32 v22, v2
	v_mov_b32_e32 v23, v2
	v_mov_b32_e32 v24, v2
	v_mov_b32_e32 v25, v2
	v_mov_b32_e32 v30, v2
	v_mov_b32_e32 v31, v2
	v_mov_b32_e32 v32, v2
	v_mov_b32_e32 v33, v2
	v_mov_b32_e32 v38, v2
	v_mov_b32_e32 v39, v2
	v_mov_b32_e32 v40, v2
	v_mov_b32_e32 v41, v2
	v_mov_b32_e32 v46, v2
	v_mov_b32_e32 v47, v2
	v_mov_b32_e32 v48, v2
	v_mov_b32_e32 v49, v2
	v_mov_b32_e32 v54, v2
	v_mov_b32_e32 v55, v2
	v_mov_b32_e32 v56, v2
	v_mov_b32_e32 v57, v2
	v_mov_b32_e32 v10, v2
	v_mov_b32_e32 v11, v2
	v_mov_b32_e32 v12, v2
	v_mov_b32_e32 v13, v2
	v_mov_b32_e32 v18, v2
	v_mov_b32_e32 v19, v2
	v_mov_b32_e32 v20, v2
	v_mov_b32_e32 v21, v2
	v_mov_b32_e32 v26, v2
	v_mov_b32_e32 v27, v2
	v_mov_b32_e32 v28, v2
	v_mov_b32_e32 v29, v2
	v_mov_b32_e32 v34, v2
	v_mov_b32_e32 v35, v2
	v_mov_b32_e32 v36, v2
	v_mov_b32_e32 v37, v2
	v_mov_b32_e32 v42, v2
	v_mov_b32_e32 v43, v2
	v_mov_b32_e32 v44, v2
	v_mov_b32_e32 v45, v2
	v_mov_b32_e32 v50, v2
	v_mov_b32_e32 v51, v2
	v_mov_b32_e32 v52, v2
	v_mov_b32_e32 v53, v2
	v_mov_b32_e32 v58, v2
	v_mov_b32_e32 v59, v2
	v_mov_b32_e32 v60, v2
	v_mov_b32_e32 v61, v2
	v_mov_b32_e32 v62, v2
	v_mov_b32_e32 v63, v2
	v_mov_b32_e32 v64, v2
	v_mov_b32_e32 v65, v2
	v_mov_b32_e32 v66, v2
	v_mov_b32_e32 v67, v2
	v_mov_b32_e32 v68, v2
	v_mov_b32_e32 v69, v2
	v_mov_b32_e32 v70, v2
	v_mov_b32_e32 v71, v2
	v_mov_b32_e32 v72, v2
	v_mov_b32_e32 v73, v2
	v_mov_b32_e32 v78, v2
	v_mov_b32_e32 v79, v2
	v_mov_b32_e32 v80, v2
	v_mov_b32_e32 v81, v2
	v_mov_b32_e32 v86, v2
	v_mov_b32_e32 v87, v2
	v_mov_b32_e32 v88, v2
	v_mov_b32_e32 v89, v2
	v_mov_b32_e32 v94, v2
	v_mov_b32_e32 v95, v2
	v_mov_b32_e32 v96, v2
	v_mov_b32_e32 v97, v2
	v_mov_b32_e32 v102, v2
	v_mov_b32_e32 v103, v2
	v_mov_b32_e32 v104, v2
	v_mov_b32_e32 v105, v2
	v_mov_b32_e32 v110, v2
	v_mov_b32_e32 v111, v2
	v_mov_b32_e32 v112, v2
	v_mov_b32_e32 v113, v2
	v_mov_b32_e32 v118, v2
	v_mov_b32_e32 v119, v2
	v_mov_b32_e32 v120, v2
	v_mov_b32_e32 v121, v2
	v_mov_b32_e32 v74, v2
	v_mov_b32_e32 v75, v2
	v_mov_b32_e32 v76, v2
	v_mov_b32_e32 v77, v2
	v_mov_b32_e32 v82, v2
	v_mov_b32_e32 v83, v2
	v_mov_b32_e32 v84, v2
	v_mov_b32_e32 v85, v2
	v_mov_b32_e32 v90, v2
	v_mov_b32_e32 v91, v2
	v_mov_b32_e32 v92, v2
	v_mov_b32_e32 v93, v2
	v_mov_b32_e32 v98, v2
	v_mov_b32_e32 v99, v2
	v_mov_b32_e32 v100, v2
	v_mov_b32_e32 v101, v2
	v_mov_b32_e32 v106, v2
	v_mov_b32_e32 v107, v2
	v_mov_b32_e32 v108, v2
	v_mov_b32_e32 v109, v2
	v_mov_b32_e32 v114, v2
	v_mov_b32_e32 v115, v2
	v_mov_b32_e32 v116, v2
	v_mov_b32_e32 v117, v2
	v_mov_b32_e32 v122, v2
	v_mov_b32_e32 v123, v2
	v_mov_b32_e32 v124, v2
	v_mov_b32_e32 v125, v2
	v_mov_b32_e32 v126, v2
	v_mov_b32_e32 v127, v2
	v_mov_b32_e32 v128, v2
	v_mov_b32_e32 v129, v2
	v_and_b32_e32 v154, 63, v0
	v_lshrrev_b32_e32 v155, 6, v0
	v_and_b32_e32 v156, 15, v154
	v_lshrrev_b32_e32 v157, 4, v154
	v_bfe_u32 v158, v156, 1, 3
	v_xor_b32_e32 v157, v157, v158
	v_lshlrev_b32_e32 v157, 4, v157
	v_and_b32_e32 v158, 7, v156
	v_lshl_add_u32 v157, v158, 7, v157
	v_lshrrev_b32_e32 v158, 3, v156
	v_lshl_add_u32 v157, v158, 10, v157
	v_lshrrev_b32_e32 v158, 2, v155
	v_lshl_add_u32 v152, v158, 13, v157
	v_and_b32_e32 v158, 3, v155
	v_lshl_add_u32 v148, v158, 12, v157
	v_add_u32_e32 v150, 0x10000, v148
	v_add_u32_e32 v151, 0x14000, v148
	v_xor_b32_e32 v146, 64, v152
	v_xor_b32_e32 v147, 64, v150
	v_xor_b32_e32 v218, 64, v151
	v_add_u32_e32 v219, 0x18000, v148
	v_xor_b32_e32 v220, 64, v219
	v_add_u32_e32 v221, 0x1c000, v148
	v_xor_b32_e32 v222, 64, v221
; #define PG8_STAGE(bufoff, gbase, voff) do { _Pragma("unroll") for (int _i = 0; _i < 2; ++_i) \
;         __builtin_amdgcn_global_load_lds((const unsigned*)((const char*)(gbase) + (voff)[_i]), (PG8_LAS unsigned*)(lds + (bufoff) + ldsw + _i * 8192), 16, 0, 0); } while (0)
; #define PG8_LDA(dst, b, h) do { _Pragma("unroll") for (int m = 0; m < 4; ++m) _Pragma("unroll") for (int k = 0; k < 2; ++k) dst[m][k] = *(const PG8_LAS bf16x8*)(lds + PG8_SA(b, h) + aoff + m * 2048 + k * 1024); } while (0)
; #define PG8_LDB(dst, b, h) do { _Pragma("unroll") for (int n = 0; n < 2; ++n) _Pragma("unroll") for (int k = 0; k < 2; ++k) dst[n][k] = *(const PG8_LAS bf16x8*)(lds + PG8_SB(b, h) + boff + n * 2048 + k * 1024); } while (0)
; #define PG8_MMA(ai, bj, At, Bt) do { __builtin_amdgcn_s_setprio(1); _Pragma("unroll") for (int m = 0; m < 4; ++m) _Pragma("unroll") for (int n = 0; n < 2; ++n) _Pragma("unroll") for (int k = 0; k < 2; ++k) \
;         acc[ai][bj][m][n] = __builtin_amdgcn_mfma_f32_16x16x32_bf16(Bt[n][k], At[m][k], acc[ai][bj][m][n], 0, 0, 0); __builtin_amdgcn_s_setprio(0); } while (0)
; #define PG8_WAIT_V(n) asm volatile("s_waitcnt vmcnt(" #n ")" ::: "memory")
; #define PG8_WAIT_L(n) asm volatile("s_waitcnt lgkmcnt(" #n ")" ::: "memory")
; #define PG8_BAR __builtin_amdgcn_s_barrier()
; #define PG8_SCHED __builtin_amdgcn_sched_barrier(0)
; template <class Epi, class Sched, bool ALIGN_EPI = false, bool SP2 = false>
; __device__ __forceinline__ void gemm_phase(PG8_LAS unsigned char* lds, const Gemm g, const Sched& S, const Epi& E) {
;     ...
;             PG8_LDB(B0, 0, 0); PG8_LDB(B1, 0, 1); PG8_SCHED; PG8_LDA(At, 0, 0); PG8_STAGE(PG8_SA(1, 1), a1 + hstep, voffA);
;             PG8_WAIT_V(8); PG8_WAIT_L(0); PG8_BAR; PG8_MMA(0, 0, At, B0); PG8_MMA(0, 1, At, B1); PG8_BAR; PG8_SCHED;
;             PG8_LDA(At, 0, 1); PG8_STAGE(PG8_SB(0, 0), b2, voffB); PG8_STAGE(PG8_SB(0, 1), b2 + hstep, voffB); PG8_STAGE(PG8_SA(0, 0), a2, voffA);
;             PG8_WAIT_V(8); PG8_WAIT_L(0); PG8_BAR; PG8_MMA(1, 0, At, B0); PG8_MMA(1, 1, At, B1); PG8_BAR; PG8_SCHED;
.LBB0_763:
	ds_read_b128 v[154:157], v150
	ds_read_b128 v[158:161], v147
	ds_read_b128 v[162:165], v150 offset:2048
	ds_read_b128 v[166:169], v147 offset:2048
	ds_read_b128 v[170:173], v151
	ds_read_b128 v[174:177], v218
	ds_read_b128 v[178:181], v151 offset:2048
	ds_read_b128 v[182:185], v218 offset:2048
	s_add_u32 s4, s40, 0xfff80080
	s_addc_u32 s5, s41, -1
	s_cmp_eq_u32 s78, 28
	s_cselect_b32 s51, s31, s5
	s_cselect_b32 s50, s74, s4
	s_cselect_b32 s49, s29, s77
	s_cselect_b32 s48, s75, s76
	s_add_i32 m0, s39, 0xc000
	ds_read_b128 v[186:189], v152
	ds_read_b128 v[190:193], v146
	ds_read_b128 v[194:197], v152 offset:2048
	ds_read_b128 v[198:201], v146 offset:2048
	ds_read_b128 v[202:205], v152 offset:4096
	ds_read_b128 v[206:209], v146 offset:4096
	ds_read_b128 v[210:213], v152 offset:6144
	ds_read_b128 v[214:217], v146 offset:6144
	global_load_lds_dwordx4 v138, s[40:41]
	s_add_i32 m0, s39, 0xe000
	s_nop 0
	global_load_lds_dwordx4 v140, s[40:41]
	s_waitcnt vmcnt(8)
	s_waitcnt lgkmcnt(0)
	s_barrier
	s_setprio 1
	s_waitcnt lgkmcnt(0)
	v_mfma_f32_16x16x32_bf16 v[126:129], v[154:157], v[186:189], v[126:129]
	v_mfma_f32_16x16x32_bf16 v[122:125], v[162:165], v[186:189], v[122:125]
	v_mfma_f32_16x16x32_bf16 v[114:117], v[154:157], v[194:197], v[114:117]
	v_mfma_f32_16x16x32_bf16 v[106:109], v[162:165], v[194:197], v[106:109]
	v_mfma_f32_16x16x32_bf16 v[98:101], v[154:157], v[202:205], v[98:101]
	v_mfma_f32_16x16x32_bf16 v[90:93], v[162:165], v[202:205], v[90:93]
	v_mfma_f32_16x16x32_bf16 v[82:85], v[154:157], v[210:213], v[82:85]
	v_mfma_f32_16x16x32_bf16 v[74:77], v[162:165], v[210:213], v[74:77]
	v_mfma_f32_16x16x32_bf16 v[126:129], v[158:161], v[190:193], v[126:129]
	v_mfma_f32_16x16x32_bf16 v[122:125], v[166:169], v[190:193], v[122:125]
	v_mfma_f32_16x16x32_bf16 v[114:117], v[158:161], v[198:201], v[114:117]
	v_mfma_f32_16x16x32_bf16 v[106:109], v[166:169], v[198:201], v[106:109]
	v_mfma_f32_16x16x32_bf16 v[98:101], v[158:161], v[206:209], v[98:101]
	v_mfma_f32_16x16x32_bf16 v[90:93], v[166:169], v[206:209], v[90:93]
	v_mfma_f32_16x16x32_bf16 v[82:85], v[158:161], v[214:217], v[82:85]
	v_mfma_f32_16x16x32_bf16 v[74:77], v[166:169], v[214:217], v[74:77]
	s_setprio 0
	s_setprio 1
	v_mfma_f32_16x16x32_bf16 v[118:121], v[170:173], v[186:189], v[118:121]
	v_mfma_f32_16x16x32_bf16 v[110:113], v[178:181], v[186:189], v[110:113]
	v_mfma_f32_16x16x32_bf16 v[102:105], v[170:173], v[194:197], v[102:105]
	v_mfma_f32_16x16x32_bf16 v[94:97], v[178:181], v[194:197], v[94:97]
	v_mfma_f32_16x16x32_bf16 v[86:89], v[170:173], v[202:205], v[86:89]
	v_mfma_f32_16x16x32_bf16 v[78:81], v[178:181], v[202:205], v[78:81]
	v_mfma_f32_16x16x32_bf16 v[70:73], v[170:173], v[210:213], v[70:73]
	v_mfma_f32_16x16x32_bf16 v[66:69], v[178:181], v[210:213], v[66:69]
	v_mfma_f32_16x16x32_bf16 v[118:121], v[174:177], v[190:193], v[118:121]
	v_mfma_f32_16x16x32_bf16 v[110:113], v[182:185], v[190:193], v[110:113]
	v_mfma_f32_16x16x32_bf16 v[102:105], v[174:177], v[198:201], v[102:105]
	v_mfma_f32_16x16x32_bf16 v[94:97], v[182:185], v[198:201], v[94:97]
	v_mfma_f32_16x16x32_bf16 v[86:89], v[174:177], v[206:209], v[86:89]
	v_mfma_f32_16x16x32_bf16 v[78:81], v[182:185], v[206:209], v[78:81]
	v_mfma_f32_16x16x32_bf16 v[70:73], v[174:177], v[214:217], v[70:73]
	v_mfma_f32_16x16x32_bf16 v[66:69], v[182:185], v[214:217], v[66:69]
	s_setprio 0
	s_barrier
	s_add_i32 s4, s67, s58
	s_mov_b32 m0, s4
	ds_read_b128 v[186:189], v152 offset:16384
	ds_read_b128 v[190:193], v146 offset:16384
	ds_read_b128 v[194:197], v152 offset:18432
	ds_read_b128 v[198:201], v146 offset:18432
	ds_read_b128 v[202:205], v152 offset:20480
	ds_read_b128 v[206:209], v146 offset:20480
	ds_read_b128 v[210:213], v152 offset:22528
	ds_read_b128 v[214:217], v146 offset:22528
	global_load_lds_dwordx4 v132, s[48:49]
	s_add_i32 m0, s4, 0x2000
	s_add_u32 s4, s48, 0x80000
	s_addc_u32 s5, s49, 0
	s_add_i32 s79, s68, s58
	global_load_lds_dwordx4 v136, s[48:49]
	s_mov_b32 m0, s79
	s_nop 0
	global_load_lds_dwordx4 v132, s[4:5]
	s_add_i32 m0, s79, 0x2000
	s_nop 0
	global_load_lds_dwordx4 v136, s[4:5]
	s_waitcnt vmcnt(6)
	s_waitcnt lgkmcnt(0)
	s_barrier
	s_setprio 1
	s_waitcnt lgkmcnt(0)
	v_mfma_f32_16x16x32_bf16 v[62:65], v[154:157], v[186:189], v[62:65]
	v_mfma_f32_16x16x32_bf16 v[58:61], v[162:165], v[186:189], v[58:61]
	v_mfma_f32_16x16x32_bf16 v[50:53], v[154:157], v[194:197], v[50:53]
	v_mfma_f32_16x16x32_bf16 v[42:45], v[162:165], v[194:197], v[42:45]
	v_mfma_f32_16x16x32_bf16 v[34:37], v[154:157], v[202:205], v[34:37]
	v_mfma_f32_16x16x32_bf16 v[26:29], v[162:165], v[202:205], v[26:29]
	v_mfma_f32_16x16x32_bf16 v[18:21], v[154:157], v[210:213], v[18:21]
	v_mfma_f32_16x16x32_bf16 v[10:13], v[162:165], v[210:213], v[10:13]
	v_mfma_f32_16x16x32_bf16 v[62:65], v[158:161], v[190:193], v[62:65]
	v_mfma_f32_16x16x32_bf16 v[58:61], v[166:169], v[190:193], v[58:61]
	v_mfma_f32_16x16x32_bf16 v[50:53], v[158:161], v[198:201], v[50:53]
	v_mfma_f32_16x16x32_bf16 v[42:45], v[166:169], v[198:201], v[42:45]
	v_mfma_f32_16x16x32_bf16 v[34:37], v[158:161], v[206:209], v[34:37]
	v_mfma_f32_16x16x32_bf16 v[26:29], v[166:169], v[206:209], v[26:29]
	v_mfma_f32_16x16x32_bf16 v[18:21], v[158:161], v[214:217], v[18:21]
	v_mfma_f32_16x16x32_bf16 v[10:13], v[166:169], v[214:217], v[10:13]
	s_setprio 0
	s_setprio 1
	v_mfma_f32_16x16x32_bf16 v[54:57], v[170:173], v[186:189], v[54:57]
	v_mfma_f32_16x16x32_bf16 v[46:49], v[178:181], v[186:189], v[46:49]
	v_mfma_f32_16x16x32_bf16 v[38:41], v[170:173], v[194:197], v[38:41]
	v_mfma_f32_16x16x32_bf16 v[30:33], v[178:181], v[194:197], v[30:33]
	v_mfma_f32_16x16x32_bf16 v[22:25], v[170:173], v[202:205], v[22:25]
	v_mfma_f32_16x16x32_bf16 v[14:17], v[178:181], v[202:205], v[14:17]
	v_mfma_f32_16x16x32_bf16 v[6:9], v[170:173], v[210:213], v[6:9]
	v_mfma_f32_16x16x32_bf16 v[2:5], v[178:181], v[210:213], v[2:5]
	v_mfma_f32_16x16x32_bf16 v[54:57], v[174:177], v[190:193], v[54:57]
	v_mfma_f32_16x16x32_bf16 v[46:49], v[182:185], v[190:193], v[46:49]
	v_mfma_f32_16x16x32_bf16 v[38:41], v[174:177], v[198:201], v[38:41]
	v_mfma_f32_16x16x32_bf16 v[30:33], v[182:185], v[198:201], v[30:33]
	v_mfma_f32_16x16x32_bf16 v[22:25], v[174:177], v[206:209], v[22:25]
	v_mfma_f32_16x16x32_bf16 v[14:17], v[182:185], v[206:209], v[14:17]
	v_mfma_f32_16x16x32_bf16 v[6:9], v[174:177], v[214:217], v[6:9]
	v_mfma_f32_16x16x32_bf16 v[2:5], v[182:185], v[214:217], v[2:5]
	s_setprio 0
	s_barrier
; #define PG8_STAGE(bufoff, gbase, voff) do { _Pragma("unroll") for (int _i = 0; _i < 2; ++_i) \
;         __builtin_amdgcn_global_load_lds((const unsigned*)((const char*)(gbase) + (voff)[_i]), (PG8_LAS unsigned*)(lds + (bufoff) + ldsw + _i * 8192), 16, 0, 0); } while (0)
; #define PG8_LDA(dst, b, h) do { _Pragma("unroll") for (int m = 0; m < 4; ++m) _Pragma("unroll") for (int k = 0; k < 2; ++k) dst[m][k] = *(const PG8_LAS bf16x8*)(lds + PG8_SA(b, h) + aoff + m * 2048 + k * 1024); } while (0)
; #define PG8_LDB(dst, b, h) do { _Pragma("unroll") for (int n = 0; n < 2; ++n) _Pragma("unroll") for (int k = 0; k < 2; ++k) dst[n][k] = *(const PG8_LAS bf16x8*)(lds + PG8_SB(b, h) + boff + n * 2048 + k * 1024); } while (0)
; #define PG8_MMA(ai, bj, At, Bt) do { __builtin_amdgcn_s_setprio(1); _Pragma("unroll") for (int m = 0; m < 4; ++m) _Pragma("unroll") for (int n = 0; n < 2; ++n) _Pragma("unroll") for (int k = 0; k < 2; ++k) \
;         acc[ai][bj][m][n] = __builtin_amdgcn_mfma_f32_16x16x32_bf16(Bt[n][k], At[m][k], acc[ai][bj][m][n], 0, 0, 0); __builtin_amdgcn_s_setprio(0); } while (0)
; #define PG8_WAIT_V(n) asm volatile("s_waitcnt vmcnt(" #n ")" ::: "memory")
; #define PG8_WAIT_L(n) asm volatile("s_waitcnt lgkmcnt(" #n ")" ::: "memory")
; #define PG8_BAR __builtin_amdgcn_s_barrier()
; #define PG8_SCHED __builtin_amdgcn_sched_barrier(0)
; template <class Epi, class Sched, bool ALIGN_EPI = false, bool SP2 = false>
; __device__ __forceinline__ void gemm_phase(PG8_LAS unsigned char* lds, const Gemm g, const Sched& S, const Epi& E) {
;     ...
;             PG8_LDB(B0, 1, 0); PG8_LDB(B1, 1, 1); PG8_SCHED; PG8_LDA(At, 1, 0); PG8_STAGE(PG8_SA(0, 1), a2 + hstep, voffA);
;             PG8_WAIT_V(8); PG8_WAIT_L(0); PG8_BAR; PG8_MMA(0, 0, At, B0); PG8_MMA(0, 1, At, B1); PG8_BAR; PG8_SCHED;
;             PG8_LDA(At, 1, 1); PG8_STAGE(PG8_SB(1, 0), b3, voffB); PG8_STAGE(PG8_SB(1, 1), b3 + hstep, voffB); PG8_STAGE(PG8_SA(1, 0), a3, voffA);
;             PG8_WAIT_V(8); PG8_WAIT_L(0); PG8_BAR; PG8_MMA(1, 0, At, B0); PG8_MMA(1, 1, At, B1); PG8_BAR; PG8_SCHED;
	s_add_i32 s79, 0, 0x18000
	s_add_i32 s80, 0, 0x1c000
	ds_read_b128 v[154:157], v219
	ds_read_b128 v[158:161], v220
	ds_read_b128 v[162:165], v219 offset:2048
	ds_read_b128 v[166:169], v220 offset:2048
	ds_read_b128 v[170:173], v221
	ds_read_b128 v[174:177], v222
	ds_read_b128 v[178:181], v221 offset:2048
	ds_read_b128 v[182:185], v222 offset:2048
	s_add_u32 s4, s50, 0x80000
	s_addc_u32 s5, s51, 0
	s_mov_b32 m0, s39
	s_nop 0
	global_load_lds_dwordx4 v130, s[50:51]
	s_mov_b32 m0, s59
	s_nop 0
	global_load_lds_dwordx4 v134, s[50:51]
	s_mov_b32 m0, s60
	ds_read_b128 v[186:189], v152 offset:32768
	ds_read_b128 v[190:193], v146 offset:32768
	ds_read_b128 v[194:197], v152 offset:34816
	ds_read_b128 v[198:201], v146 offset:34816
	ds_read_b128 v[202:205], v152 offset:36864
	ds_read_b128 v[206:209], v146 offset:36864
	ds_read_b128 v[210:213], v152 offset:38912
	ds_read_b128 v[214:217], v146 offset:38912
	global_load_lds_dwordx4 v130, s[4:5]
	s_mov_b32 m0, s61
	s_nop 0
	global_load_lds_dwordx4 v134, s[4:5]
	s_waitcnt vmcnt(8)
	s_waitcnt lgkmcnt(0)
	s_barrier
	s_setprio 1
	s_waitcnt lgkmcnt(0)
	v_mfma_f32_16x16x32_bf16 v[126:129], v[154:157], v[186:189], v[126:129]
	v_mfma_f32_16x16x32_bf16 v[122:125], v[162:165], v[186:189], v[122:125]
	v_mfma_f32_16x16x32_bf16 v[114:117], v[154:157], v[194:197], v[114:117]
	v_mfma_f32_16x16x32_bf16 v[106:109], v[162:165], v[194:197], v[106:109]
	v_mfma_f32_16x16x32_bf16 v[98:101], v[154:157], v[202:205], v[98:101]
	v_mfma_f32_16x16x32_bf16 v[90:93], v[162:165], v[202:205], v[90:93]
	v_mfma_f32_16x16x32_bf16 v[82:85], v[154:157], v[210:213], v[82:85]
	v_mfma_f32_16x16x32_bf16 v[74:77], v[162:165], v[210:213], v[74:77]
	v_mfma_f32_16x16x32_bf16 v[126:129], v[158:161], v[190:193], v[126:129]
	v_mfma_f32_16x16x32_bf16 v[122:125], v[166:169], v[190:193], v[122:125]
	v_mfma_f32_16x16x32_bf16 v[114:117], v[158:161], v[198:201], v[114:117]
	v_mfma_f32_16x16x32_bf16 v[106:109], v[166:169], v[198:201], v[106:109]
	v_mfma_f32_16x16x32_bf16 v[98:101], v[158:161], v[206:209], v[98:101]
	v_mfma_f32_16x16x32_bf16 v[90:93], v[166:169], v[206:209], v[90:93]
	v_mfma_f32_16x16x32_bf16 v[82:85], v[158:161], v[214:217], v[82:85]
	v_mfma_f32_16x16x32_bf16 v[74:77], v[166:169], v[214:217], v[74:77]
	s_setprio 0
	s_setprio 1
	v_mfma_f32_16x16x32_bf16 v[118:121], v[170:173], v[186:189], v[118:121]
	v_mfma_f32_16x16x32_bf16 v[110:113], v[178:181], v[186:189], v[110:113]
	v_mfma_f32_16x16x32_bf16 v[102:105], v[170:173], v[194:197], v[102:105]
	v_mfma_f32_16x16x32_bf16 v[94:97], v[178:181], v[194:197], v[94:97]
	v_mfma_f32_16x16x32_bf16 v[86:89], v[170:173], v[202:205], v[86:89]
	v_mfma_f32_16x16x32_bf16 v[78:81], v[178:181], v[202:205], v[78:81]
	v_mfma_f32_16x16x32_bf16 v[70:73], v[170:173], v[210:213], v[70:73]
	v_mfma_f32_16x16x32_bf16 v[66:69], v[178:181], v[210:213], v[66:69]
	v_mfma_f32_16x16x32_bf16 v[118:121], v[174:177], v[190:193], v[118:121]
	v_mfma_f32_16x16x32_bf16 v[110:113], v[182:185], v[190:193], v[110:113]
	v_mfma_f32_16x16x32_bf16 v[102:105], v[174:177], v[198:201], v[102:105]
	v_mfma_f32_16x16x32_bf16 v[94:97], v[182:185], v[198:201], v[94:97]
	v_mfma_f32_16x16x32_bf16 v[86:89], v[174:177], v[206:209], v[86:89]
	v_mfma_f32_16x16x32_bf16 v[78:81], v[182:185], v[206:209], v[78:81]
	v_mfma_f32_16x16x32_bf16 v[70:73], v[174:177], v[214:217], v[70:73]
	v_mfma_f32_16x16x32_bf16 v[66:69], v[182:185], v[214:217], v[66:69]
	s_setprio 0
	s_barrier
	s_add_i32 s4, s79, s58
	s_add_i32 m0, s4, 0xffffff80
	ds_read_b128 v[186:189], v152 offset:49152
	ds_read_b128 v[190:193], v146 offset:49152
	ds_read_b128 v[194:197], v152 offset:51200
	ds_read_b128 v[198:201], v146 offset:51200
	ds_read_b128 v[202:205], v152 offset:53248
	ds_read_b128 v[206:209], v146 offset:53248
	ds_read_b128 v[210:213], v152 offset:55296
	ds_read_b128 v[214:217], v146 offset:55296
	global_load_lds_dwordx4 v132, s[48:49] offset:128
	s_add_i32 m0, s4, 0x1f80
	s_add_u32 s4, s48, 0x80080
	s_addc_u32 s5, s49, 0
	global_load_lds_dwordx4 v136, s[48:49] offset:128
	s_add_i32 s48, s80, s58
	s_mov_b32 m0, s48
	s_nop 0
	global_load_lds_dwordx4 v132, s[4:5]
	s_add_i32 m0, s48, 0x2000
	s_nop 0
	global_load_lds_dwordx4 v136, s[4:5]
	s_add_i32 m0, s63, 0xffffff80
	s_nop 0
	global_load_lds_dwordx4 v130, s[50:51] offset:128
	s_add_i32 m0, s64, 0xffffff80
	s_nop 0
	global_load_lds_dwordx4 v134, s[50:51] offset:128
	s_waitcnt vmcnt(8)
	s_waitcnt lgkmcnt(0)
	s_barrier
	s_setprio 1
	s_waitcnt lgkmcnt(0)
	v_mfma_f32_16x16x32_bf16 v[62:65], v[154:157], v[186:189], v[62:65]
	v_mfma_f32_16x16x32_bf16 v[58:61], v[162:165], v[186:189], v[58:61]
	v_mfma_f32_16x16x32_bf16 v[50:53], v[154:157], v[194:197], v[50:53]
	v_mfma_f32_16x16x32_bf16 v[42:45], v[162:165], v[194:197], v[42:45]
	v_mfma_f32_16x16x32_bf16 v[34:37], v[154:157], v[202:205], v[34:37]
	v_mfma_f32_16x16x32_bf16 v[26:29], v[162:165], v[202:205], v[26:29]
	v_mfma_f32_16x16x32_bf16 v[18:21], v[154:157], v[210:213], v[18:21]
	v_mfma_f32_16x16x32_bf16 v[10:13], v[162:165], v[210:213], v[10:13]
	v_mfma_f32_16x16x32_bf16 v[62:65], v[158:161], v[190:193], v[62:65]
	v_mfma_f32_16x16x32_bf16 v[58:61], v[166:169], v[190:193], v[58:61]
	v_mfma_f32_16x16x32_bf16 v[50:53], v[158:161], v[198:201], v[50:53]
	v_mfma_f32_16x16x32_bf16 v[42:45], v[166:169], v[198:201], v[42:45]
	v_mfma_f32_16x16x32_bf16 v[34:37], v[158:161], v[206:209], v[34:37]
	v_mfma_f32_16x16x32_bf16 v[26:29], v[166:169], v[206:209], v[26:29]
	v_mfma_f32_16x16x32_bf16 v[18:21], v[158:161], v[214:217], v[18:21]
	v_mfma_f32_16x16x32_bf16 v[10:13], v[166:169], v[214:217], v[10:13]
	s_setprio 0
	s_setprio 1
	v_mfma_f32_16x16x32_bf16 v[54:57], v[170:173], v[186:189], v[54:57]
	v_mfma_f32_16x16x32_bf16 v[46:49], v[178:181], v[186:189], v[46:49]
	v_mfma_f32_16x16x32_bf16 v[38:41], v[170:173], v[194:197], v[38:41]
	v_mfma_f32_16x16x32_bf16 v[30:33], v[178:181], v[194:197], v[30:33]
	v_mfma_f32_16x16x32_bf16 v[22:25], v[170:173], v[202:205], v[22:25]
	v_mfma_f32_16x16x32_bf16 v[14:17], v[178:181], v[202:205], v[14:17]
	v_mfma_f32_16x16x32_bf16 v[6:9], v[170:173], v[210:213], v[6:9]
	v_mfma_f32_16x16x32_bf16 v[2:5], v[178:181], v[210:213], v[2:5]
	v_mfma_f32_16x16x32_bf16 v[54:57], v[174:177], v[190:193], v[54:57]
	v_mfma_f32_16x16x32_bf16 v[46:49], v[182:185], v[190:193], v[46:49]
	v_mfma_f32_16x16x32_bf16 v[38:41], v[174:177], v[198:201], v[38:41]
	v_mfma_f32_16x16x32_bf16 v[30:33], v[182:185], v[198:201], v[30:33]
	v_mfma_f32_16x16x32_bf16 v[22:25], v[174:177], v[206:209], v[22:25]
	v_mfma_f32_16x16x32_bf16 v[14:17], v[182:185], v[206:209], v[14:17]
	v_mfma_f32_16x16x32_bf16 v[6:9], v[174:177], v[214:217], v[6:9]
	v_mfma_f32_16x16x32_bf16 v[2:5], v[182:185], v[214:217], v[2:5]
	s_setprio 0
	s_barrier
	s_add_i32 s78, s78, 2
	s_add_u32 s40, s40, 0x100
	s_addc_u32 s41, s41, 0
	s_add_u32 s76, s76, 0x100
	s_addc_u32 s77, s77, 0
	s_cmp_gt_u32 s78, 29
	s_cbranch_scc0 .LBB0_763
	s_and_b64 vcc, exec, s[20:21]
	s_cbranch_vccz .LBB0_766
	s_barrier

; #define PG8_STAGE(bufoff, gbase, voff) do { _Pragma("unroll") for (int _i = 0; _i < 2; ++_i) \
;         __builtin_amdgcn_global_load_lds((const unsigned*)((const char*)(gbase) + (voff)[_i]), (PG8_LAS unsigned*)(lds + (bufoff) + ldsw + _i * 8192), 16, 0, 0); } while (0)
; #define PG8_WAIT_V(n) asm volatile("s_waitcnt vmcnt(" #n ")" ::: "memory")
; #define PG8_BAR __builtin_amdgcn_s_barrier()
; template <class Epi, class Sched, bool ALIGN_EPI = false, bool SP2 = false>
; __device__ __forceinline__ void gemm_phase(PG8_LAS unsigned char* lds, const Gemm g, const Sched& S, const Epi& E) {
;     ...
;     unsigned voffA[2], voffB[2];
; #pragma unroll
;     for (int i = 0; i < 2; ++i) { int R, C; stage_rc(tid * 16 + i * 8192, R, C); const int Rb = Epi::PERM ? ((R & ~31) + perm32(R & 31)) : R;
;         voffA[i] = (unsigned)(R * K + C) * 2u; voffB[i] = (unsigned)(Rb * K + C) * 2u; }
;     ...
;     const char* cA = (const char*)g.A + (size_t)cur.pm * tstep; const char* cB = (const char*)g.Bt + (size_t)cur.pn * tstep;
;     S.a_ready(cur);
;     if constexpr (SP2) {
;         PG8_STAGE(PG8_SB(0, 0), cB, voffB); PG8_STAGE(PG8_SB(0, 1), cB + hstep, voffB); PG8_STAGE(PG8_SA(0, 0), cA, voffA); PG8_STAGE(PG8_SA(0, 1), cA + hstep, voffA);
;         if (wr == 1) PG8_BAR;
;         PG8_WAIT_V(2); PG8_BAR;
.LBB0_904:
	v_mov_b32_e32 v12, v0
	s_cmpk_gt_i32 s2, 0xaff
	v_readfirstlane_b32 s7, v12
	s_cbranch_scc1 .LBB0_920
	v_lshlrev_b32_e32 v2, 4, v12
	v_add_u32_e32 v3, 0x2000, v2
	v_ashrrev_i32_e32 v4, 31, v3
	v_lshrrev_b32_e32 v4, 22, v4
	v_add_u32_e32 v4, v3, v4
	v_ashrrev_i32_e32 v10, 10, v4
	v_mul_i32_i24_e32 v4, 0x400, v10
	v_sub_u32_e32 v3, v3, v4
	v_lshrrev_b32_e32 v4, 4, v3
	v_bitop3_b32 v3, v4, v3, 32 bitop3:0x6c
	v_ashrrev_i32_e32 v4, 31, v3
	v_lshrrev_b32_e32 v4, 26, v4
	v_add_u32_e32 v4, v3, v4
	s_waitcnt lgkmcnt(0)
	v_lshlrev_b32_e32 v5, 3, v10
	v_ashrrev_i32_e32 v11, 6, v4
	v_and_b32_e32 v5, -16, v5
	v_add_u32_e32 v5, v11, v5
	v_and_b32_e32 v6, 3, v11
	s_mov_b32 s4, 0xfffe0
	v_lshrrev_b32_e32 v7, 2, v5
	v_lshlrev_b32_e32 v8, 1, v5
	v_and_b32_e32 v4, 0xc0, v4
	v_and_or_b32 v6, v5, s4, v6
	v_and_b32_e32 v7, 4, v7
	v_and_b32_e32 v8, 24, v8
	v_sub_u32_e32 v3, v3, v4
	v_mov_b32_e32 v4, 1
	v_or3_b32 v6, v6, v7, v8
	v_lshlrev_b32_e32 v7, 5, v10
	v_ashrrev_i16_sdwa v3, v4, sext(v3) dst_sel:DWORD dst_unused:UNUSED_PAD src0_sel:DWORD src1_sel:BYTE_0
	v_and_b32_e32 v7, 32, v7
	v_bfe_i32 v13, v3, 0, 16
	v_add_lshl_u32 v3, v7, v13, 1
	v_and_b32_e32 v160, 63, v0
	v_lshrrev_b32_e32 v161, 6, v0
	v_lshrrev_b32_e32 v162, 3, v160
	v_lshl_add_u32 v162, v161, 3, v162
	v_and_b32_e32 v163, 1, v161
	v_lshrrev_b32_e32 v164, 4, v160
	v_lshl_add_u32 v163, v163, 2, v164
	v_and_b32_e32 v164, 7, v160
	v_xor_b32_e32 v163, v163, v164
	v_lshlrev_b32_e32 v163, 4, v163
	v_mul_u32_u24_e32 v164, 0x1000, v162
	v_add_u32_e32 v156, v164, v163
	v_add_u32_e32 v157, 0x40000, v156
	v_and_b32_e32 v164, 31, v162
	v_bfe_u32 v165, v164, 2, 2
	v_lshlrev_b32_e32 v165, 3, v165
	v_lshrrev_b32_e32 v160, 4, v164
	v_lshl_add_u32 v165, v160, 2, v165
	v_and_b32_e32 v160, 3, v164
	v_add_u32_e32 v165, v165, v160
	v_and_b32_e32 v160, -32, v162
	v_add_u32_e32 v165, v165, v160
	v_mul_u32_u24_e32 v165, 0x1000, v165
	v_add_u32_e32 v158, v165, v163
	v_add_u32_e32 v159, 0x40000, v158
	v_mov_b32_e32 v130, v159
	v_mov_b32_e32 v132, v157
	v_bfe_i32 v3, v12, 27, 1
	v_lshrrev_b32_e32 v3, 22, v3
	v_add_u32_e32 v3, v2, v3
	v_and_b32_e32 v3, 0xfffffc00, v3
	v_sub_u32_e32 v2, v2, v3
	v_lshrrev_b32_e32 v3, 4, v2
	v_ashrrev_i32_e32 v5, 31, v12
	v_bitop3_b32 v2, v3, v2, 32 bitop3:0x6c
	v_lshrrev_b32_e32 v5, 26, v5
	v_ashrrev_i32_e32 v3, 31, v2
	v_add_u32_e32 v5, v12, v5
	v_lshrrev_b32_e32 v3, 26, v3
	v_ashrrev_i32_e32 v15, 6, v5
	v_add_u32_e32 v3, v2, v3
	v_lshlrev_b32_e32 v5, 3, v15
	v_ashrrev_i32_e32 v14, 6, v3
	v_and_b32_e32 v5, -16, v5
	v_add_u32_e32 v5, v14, v5
	v_and_b32_e32 v6, 3, v14
	s_ashr_i32 s41, s2, 31
	v_and_or_b32 v6, v5, s4, v6
	s_lshr_b32 s4, s41, 29
	s_add_i32 s4, s2, s4
	s_ashr_i32 s18, s7, 6
	s_ashr_i32 s5, s4, 3
	s_and_b32 s4, s4, -8
	s_ashr_i32 s20, s7, 8
	s_lshl_b32 s40, s18, 10
	s_sub_i32 s4, s2, s4
	s_cmp_lt_i32 s4, 0
	s_movk_i32 s48, 0x161
	s_cselect_b32 s6, s48, 0x160
	s_mul_i32 s4, s4, s6
	s_add_i32 s4, s4, s5
	s_mul_hi_i32 s5, s4, 0x2e8ba2e9
	s_lshr_b32 s6, s5, 31
	s_ashr_i32 s5, s5, 6
	s_add_i32 s5, s5, s6
	s_lshl_b32 s16, s5, 3
	s_mulk_i32 s5, 0x160
	s_sub_i32 s4, s4, s5
	s_sext_i32_i16 s5, s4
	s_bfe_u32 s5, s5, 0x3001c
	s_add_i32 s5, s4, s5
	s_sext_i32_i16 s6, s5
	s_and_b32 s5, s5, 0xfff8
	s_sub_i32 s4, s4, s5
	s_sext_i32_i16 s4, s4
	v_lshrrev_b32_e32 v7, 2, v5
	v_lshlrev_b32_e32 v8, 1, v5
	v_and_b32_e32 v3, 0xc0, v3
	s_lshr_b32 s6, s6, 3
	s_add_i32 s30, s16, s4
	v_and_b32_e32 v7, 4, v7
	v_and_b32_e32 v8, 24, v8
	v_sub_u32_e32 v2, v2, v3
	s_ashr_i32 s31, s30, 31
	s_bfe_i64 s[16:17], s[6:7], 0x100000
	v_or3_b32 v6, v6, v7, v8
	v_lshlrev_b32_e32 v7, 5, v15
	v_ashrrev_i16_sdwa v2, v4, sext(v2) dst_sel:DWORD dst_unused:UNUSED_PAD src0_sel:DWORD src1_sel:BYTE_0
	s_lshl_b64 s[4:5], s[30:31], 20
	s_lshl_b64 s[16:17], s[16:17], 20
	v_and_b32_e32 v7, 32, v7
	v_bfe_i32 v16, v2, 0, 16
	s_add_u32 s36, s12, s16
	v_add_lshl_u32 v2, v7, v16, 1
	s_addc_u32 s37, s13, s17
	s_add_i32 s31, s40, 0
	v_mov_b32_e32 v134, v158
	s_add_i32 m0, s31, 0x10000
	v_mov_b32_e32 v136, v156
	global_load_lds_dwordx4 v134, s[36:37]
	s_add_i32 m0, s31, 0x12000
	s_add_u32 s16, s36, 0x80000
	global_load_lds_dwordx4 v130, s[36:37]
	s_addc_u32 s17, s37, 0
	s_add_i32 m0, s31, 0x14000
	v_mov_b32_e32 v135, 0
	global_load_lds_dwordx4 v134, s[16:17]
	s_add_i32 m0, s31, 0x16000
	s_add_u32 s34, s81, s4
	s_addc_u32 s35, s82, s5
	s_add_i32 s49, s31, 0x2000
	global_load_lds_dwordx4 v130, s[16:17]
	s_mov_b32 m0, s31
	s_add_u32 s4, s34, 0x80000
	global_load_lds_dwordx4 v136, s[34:35]
	s_mov_b32 m0, s49
	s_addc_u32 s5, s35, 0
	s_add_i32 s50, s31, 0x4000
	global_load_lds_dwordx4 v132, s[34:35]
	s_mov_b32 m0, s50
	s_add_i32 s51, s31, 0x6000
	global_load_lds_dwordx4 v136, s[4:5]
	s_mov_b32 m0, s51
	v_mov_b32_e32 v131, v135
	global_load_lds_dwordx4 v132, s[4:5]
	v_mov_b32_e32 v137, v135
	v_mov_b32_e32 v133, v135
	s_cmp_eq_u32 s20, 1
	s_mov_b32 s52, 0
	v_lshl_add_u64 v[8:9], s[36:37], 0, v[134:135]
	v_lshl_add_u64 v[6:7], s[36:37], 0, v[130:131]
	v_lshl_add_u64 v[2:3], s[34:35], 0, v[136:137]
	s_cselect_b64 s[16:17], -1, 0
	s_cmp_lg_u32 s20, 1
	v_lshl_add_u64 v[4:5], s[34:35], 0, v[132:133]
	s_cbranch_scc1 .LBB0_907
	s_barrier
; #define PG8_STAGE(bufoff, gbase, voff) do { _Pragma("unroll") for (int _i = 0; _i < 2; ++_i) \
;         __builtin_amdgcn_global_load_lds((const unsigned*)((const char*)(gbase) + (voff)[_i]), (PG8_LAS unsigned*)(lds + (bufoff) + ldsw + _i * 8192), 16, 0, 0); } while (0)
; #define PG8_WAIT_V(n) asm volatile("s_waitcnt vmcnt(" #n ")" ::: "memory")
; #define PG8_BAR __builtin_amdgcn_s_barrier()
; template <class Epi, class Sched, bool ALIGN_EPI = false, bool SP2 = false>
; __device__ __forceinline__ void gemm_phase(PG8_LAS unsigned char* lds, const Gemm g, const Sched& S, const Epi& E) {
;     ...
;     const size_t kstep = (size_t)(BK * 2);
;     const size_t hstep = (size_t)HALF * K * 2;
;     const size_t tstep = 2 * hstep;
;     const unsigned ldsw = (unsigned)wid * 1024u;
;     const int aoff = lds_byte(wr * 64 + fr, fq * 8), boff = lds_byte(wc * 32 + fr, fq * 8);
;     ...
;         PG8_STAGE(PG8_SB(1, 0), cB + kstep, voffB); PG8_STAGE(PG8_SA(1, 0), cA + kstep, voffA); PG8_STAGE(PG8_SB(1, 1), cB + hstep + kstep, voffB);
;         PG8_WAIT_V(6); PG8_BAR;
.LBB0_907:
	s_lshl_b32 s4, s18, 5
	s_mov_b64 s[18:19], 0x80
	s_and_b32 s22, s4, 0x60
	s_add_i32 m0, s31, 0x18000
	v_lshl_add_u64 v[8:9], v[8:9], 0, s[18:19]
	s_lshl_b32 s21, s20, 13
	s_lshl_b32 s23, s22, 7
	s_waitcnt vmcnt(2)
	s_barrier
	global_load_lds_dwordx4 v[8:9], off
	v_lshl_add_u64 v[6:7], v[6:7], 0, s[18:19]
	s_add_i32 m0, s31, 0x1a000
	s_add_i32 s53, s31, 0x8000
	s_add_i32 s58, s31, 0xa000
	global_load_lds_dwordx4 v[6:7], off
	v_lshl_add_u64 v[2:3], v[2:3], 0, s[18:19]
	s_mov_b32 m0, s53
	s_add_u32 s4, s36, 0x80080
	global_load_lds_dwordx4 v[2:3], off
	v_lshl_add_u64 v[2:3], v[4:5], 0, s[18:19]
	s_mov_b32 m0, s58
	s_addc_u32 s5, s37, 0
	global_load_lds_dwordx4 v[2:3], off
	s_add_i32 m0, s31, 0x1c000
	v_lshl_add_u64 v[2:3], s[4:5], 0, v[134:135]
	global_load_lds_dwordx4 v[2:3], off
	v_lshl_add_u64 v[2:3], s[4:5], 0, v[130:131]
	s_add_i32 m0, s31, 0x1e000
	s_cmpk_lt_u32 s7, 0x100
	global_load_lds_dwordx4 v[2:3], off
	v_lshrrev_b32_e32 v3, 1, v12
	v_and_b32_e32 v3, 24, v3
	v_and_b32_e32 v2, 15, v12
	v_lshlrev_b32_e32 v4, 1, v3
	v_lshl_or_b32 v149, s20, 6, v2
	v_lshl_or_b32 v2, v2, 6, v4
	v_lshlrev_b32_e32 v4, 2, v12
	v_and_b32_e32 v4, 32, v4
	v_bitop3_b32 v5, v2, s21, v4 bitop3:0xde
	v_bitop3_b32 v150, v2, s23, v4 bitop3:0xde
	v_lshlrev_b32_e32 v2, 15, v15
	v_and_b32_e32 v2, 0xffff0000, v2
	v_or_b32_e32 v151, s22, v3
	v_lshl_add_u32 v2, v14, 12, v2
	v_and_b32_e32 v3, 1, v15
	v_lshl_or_b32 v2, v3, 6, v2
	v_lshl_add_u32 v138, v16, 1, v2
	v_lshlrev_b32_e32 v2, 15, v10
	v_and_b32_e32 v2, 0xffff0000, v2
	s_waitcnt vmcnt(6)
	v_lshl_add_u32 v2, v11, 12, v2
	v_and_b32_e32 v3, 1, v10
	s_cselect_b64 s[20:21], -1, 0
	v_lshl_or_b32 v2, v3, 6, v2
	s_add_i32 s61, 0, 0x10000
	s_add_i32 s62, 0, 0x14000
	s_sext_i32_i16 s64, s6
	s_ashr_i32 s59, s46, 31
	s_mov_b32 s60, s46
	v_mov_b32_e32 v139, v135
	v_lshl_add_u32 v140, v13, 1, v2
	v_and_b32_e32 v160, 63, v0
	v_lshrrev_b32_e32 v161, 6, v0
	v_lshrrev_b32_e32 v162, 1, v161
	v_lshrrev_b32_e32 v163, 2, v160
	v_lshl_add_u32 v162, v162, 4, v163
	v_and_b32_e32 v163, 3, v160
	v_lshlrev_b32_e32 v163, 4, v163
	v_bfe_u32 v164, v160, 5, 1
	v_lshlrev_b32_e32 v164, 5, v164
	v_xor_b32_e32 v163, v163, v164
	v_and_b32_e32 v164, 1, v161
	v_lshl_add_u32 v163, v164, 6, v163
	v_mul_u32_u24_e32 v162, 0x1000, v162
	v_add_u32_e32 v162, v162, v163
	v_sub_u32_e32 v162, v136, v162
	v_add_u32_e32 v138, v138, v162
	v_add_u32_e32 v140, v140, v162
	v_mov_b32_e32 v141, v135
	v_mov_b64_e32 v[142:143], 0xb00
	v_mov_b64_e32 v[144:145], 0xaff
	v_add_u32_e32 v152, s61, v150
	v_add_u32_e32 v153, s62, v150
	v_add_u32_e32 v154, 0, v5
	s_movk_i32 s63, 0x2c00
	s_barrier
	s_branch .LBB0_910

; template <class Epi, class Sched, bool ALIGN_EPI = false, bool SP2 = false>
; __device__ __forceinline__ void gemm_phase(PG8_LAS unsigned char* lds, const Gemm g, const Sched& S, const Epi& E) {
;     ...
;         if (!has_next) break;
; #pragma unroll
;         for (int a = 0; a < 2; ++a)
; #pragma unroll
;             for (int b = 0; b < 2; ++b)
; #pragma unroll
;                 for (int m = 0; m < 4; ++m)
; #pragma unroll
;                     for (int n = 0; n < 2; ++n) acc[a][b][m][n] = (f32x4){0.f, 0.f, 0.f, 0.f};
;         cur = nxt; cA = nA; cB = nB; ++ui;
.LBB0_912:
	s_ashr_i32 s25, s24, 31
	s_lshl_b64 s[4:5], s[24:25], 20
	s_add_u32 s26, s81, s4
	s_addc_u32 s27, s82, s5
	s_and_b64 s[4:5], s[6:7], exec
	s_cselect_b32 s25, s27, s35
	s_cselect_b32 s65, s26, s34
	s_ashr_i32 s23, s22, 31
	s_lshl_b64 s[4:5], s[22:23], 20
	s_add_u32 s28, s12, s4
	s_addc_u32 s29, s13, s5
	s_and_b64 s[4:5], s[6:7], exec
	s_cselect_b32 s23, s29, s37
	s_cselect_b32 s66, s28, s36
	s_add_u32 s34, s34, 0x80080
	s_addc_u32 s35, s35, 0
	s_add_u32 s67, s36, 0x100
	v_mov_b32_e32 v2, 0
	s_addc_u32 s68, s37, 0
	s_mov_b32 s69, -2
	v_mov_b32_e32 v3, v2
	v_mov_b32_e32 v4, v2
	v_mov_b32_e32 v5, v2
	v_mov_b32_e32 v6, v2
	v_mov_b32_e32 v7, v2
	v_mov_b32_e32 v8, v2
	v_mov_b32_e32 v9, v2
	v_mov_b32_e32 v18, v2
	v_mov_b32_e32 v19, v2
	v_mov_b32_e32 v20, v2
	v_mov_b32_e32 v21, v2
	v_mov_b32_e32 v22, v2
	v_mov_b32_e32 v23, v2
	v_mov_b32_e32 v24, v2
	v_mov_b32_e32 v25, v2
	v_mov_b32_e32 v34, v2
	v_mov_b32_e32 v35, v2
	v_mov_b32_e32 v36, v2
	v_mov_b32_e32 v37, v2
	v_mov_b32_e32 v38, v2
	v_mov_b32_e32 v39, v2
	v_mov_b32_e32 v40, v2
	v_mov_b32_e32 v41, v2
	v_mov_b32_e32 v50, v2
	v_mov_b32_e32 v51, v2
	v_mov_b32_e32 v52, v2
	v_mov_b32_e32 v53, v2
	v_mov_b32_e32 v54, v2
	v_mov_b32_e32 v55, v2
	v_mov_b32_e32 v56, v2
	v_mov_b32_e32 v57, v2
	v_mov_b32_e32 v10, v2
	v_mov_b32_e32 v11, v2
	v_mov_b32_e32 v12, v2
	v_mov_b32_e32 v13, v2
	v_mov_b32_e32 v14, v2
	v_mov_b32_e32 v15, v2
	v_mov_b32_e32 v16, v2
	v_mov_b32_e32 v17, v2
	v_mov_b32_e32 v26, v2
	v_mov_b32_e32 v27, v2
	v_mov_b32_e32 v28, v2
	v_mov_b32_e32 v29, v2
	v_mov_b32_e32 v30, v2
	v_mov_b32_e32 v31, v2
	v_mov_b32_e32 v32, v2
	v_mov_b32_e32 v33, v2
	v_mov_b32_e32 v42, v2
	v_mov_b32_e32 v43, v2
	v_mov_b32_e32 v44, v2
	v_mov_b32_e32 v45, v2
	v_mov_b32_e32 v46, v2
	v_mov_b32_e32 v47, v2
	v_mov_b32_e32 v48, v2
	v_mov_b32_e32 v49, v2
	v_mov_b32_e32 v58, v2
	v_mov_b32_e32 v59, v2
	v_mov_b32_e32 v60, v2
	v_mov_b32_e32 v61, v2
	v_mov_b32_e32 v62, v2
	v_mov_b32_e32 v63, v2
	v_mov_b32_e32 v64, v2
	v_mov_b32_e32 v65, v2
	v_mov_b32_e32 v66, v2
	v_mov_b32_e32 v67, v2
	v_mov_b32_e32 v68, v2
	v_mov_b32_e32 v69, v2
	v_mov_b32_e32 v70, v2
	v_mov_b32_e32 v71, v2
	v_mov_b32_e32 v72, v2
	v_mov_b32_e32 v73, v2
	v_mov_b32_e32 v82, v2
	v_mov_b32_e32 v83, v2
	v_mov_b32_e32 v84, v2
	v_mov_b32_e32 v85, v2
	v_mov_b32_e32 v86, v2
	v_mov_b32_e32 v87, v2
	v_mov_b32_e32 v88, v2
	v_mov_b32_e32 v89, v2
	v_mov_b32_e32 v98, v2
	v_mov_b32_e32 v99, v2
	v_mov_b32_e32 v100, v2
	v_mov_b32_e32 v101, v2
	v_mov_b32_e32 v102, v2
	v_mov_b32_e32 v103, v2
	v_mov_b32_e32 v104, v2
	v_mov_b32_e32 v105, v2
	v_mov_b32_e32 v114, v2
	v_mov_b32_e32 v115, v2
	v_mov_b32_e32 v116, v2
	v_mov_b32_e32 v117, v2
	v_mov_b32_e32 v118, v2
	v_mov_b32_e32 v119, v2
	v_mov_b32_e32 v120, v2
	v_mov_b32_e32 v121, v2
	v_mov_b32_e32 v74, v2
	v_mov_b32_e32 v75, v2
	v_mov_b32_e32 v76, v2
	v_mov_b32_e32 v77, v2
	v_mov_b32_e32 v78, v2
	v_mov_b32_e32 v79, v2
	v_mov_b32_e32 v80, v2
	v_mov_b32_e32 v81, v2
	v_mov_b32_e32 v90, v2
	v_mov_b32_e32 v91, v2
	v_mov_b32_e32 v92, v2
	v_mov_b32_e32 v93, v2
	v_mov_b32_e32 v94, v2
	v_mov_b32_e32 v95, v2
	v_mov_b32_e32 v96, v2
	v_mov_b32_e32 v97, v2
	v_mov_b32_e32 v106, v2
	v_mov_b32_e32 v107, v2
	v_mov_b32_e32 v108, v2
	v_mov_b32_e32 v109, v2
	v_mov_b32_e32 v110, v2
	v_mov_b32_e32 v111, v2
	v_mov_b32_e32 v112, v2
	v_mov_b32_e32 v113, v2
	v_mov_b32_e32 v122, v2
	v_mov_b32_e32 v123, v2
	v_mov_b32_e32 v124, v2
	v_mov_b32_e32 v125, v2
	v_mov_b32_e32 v126, v2
	v_mov_b32_e32 v127, v2
	v_mov_b32_e32 v128, v2
	v_mov_b32_e32 v129, v2
	v_and_b32_e32 v156, 63, v0
	v_lshrrev_b32_e32 v157, 6, v0
	v_and_b32_e32 v158, 15, v156
	v_lshrrev_b32_e32 v159, 4, v156
	v_bfe_u32 v160, v158, 1, 3
	v_xor_b32_e32 v159, v159, v160
	v_lshlrev_b32_e32 v159, 4, v159
	v_and_b32_e32 v160, 7, v158
	v_lshl_add_u32 v159, v160, 7, v159
	v_lshrrev_b32_e32 v160, 3, v158
	v_lshl_add_u32 v159, v160, 10, v159
	v_lshrrev_b32_e32 v160, 2, v157
	v_lshl_add_u32 v154, v160, 13, v159
	v_and_b32_e32 v160, 3, v157
	v_lshl_add_u32 v150, v160, 12, v159
	v_add_u32_e32 v152, 0x10000, v150
	v_add_u32_e32 v153, 0x14000, v150
	v_xor_b32_e32 v146, 64, v154
	v_xor_b32_e32 v147, 64, v152
	v_xor_b32_e32 v220, 64, v153
	v_add_u32_e32 v221, 0x18000, v150
	v_xor_b32_e32 v222, 64, v221
	v_add_u32_e32 v223, 0x1c000, v150
	v_xor_b32_e32 v224, 64, v223
; #define PG8_STAGE(bufoff, gbase, voff) do { _Pragma("unroll") for (int _i = 0; _i < 2; ++_i) \
;         __builtin_amdgcn_global_load_lds((const unsigned*)((const char*)(gbase) + (voff)[_i]), (PG8_LAS unsigned*)(lds + (bufoff) + ldsw + _i * 8192), 16, 0, 0); } while (0)
; #define PG8_LDA(dst, b, h) do { _Pragma("unroll") for (int m = 0; m < 4; ++m) _Pragma("unroll") for (int k = 0; k < 2; ++k) dst[m][k] = *(const PG8_LAS bf16x8*)(lds + PG8_SA(b, h) + aoff + m * 2048 + k * 1024); } while (0)
; #define PG8_LDB(dst, b, h) do { _Pragma("unroll") for (int n = 0; n < 2; ++n) _Pragma("unroll") for (int k = 0; k < 2; ++k) dst[n][k] = *(const PG8_LAS bf16x8*)(lds + PG8_SB(b, h) + boff + n * 2048 + k * 1024); } while (0)
; #define PG8_MMA(ai, bj, At, Bt) do { __builtin_amdgcn_s_setprio(1); _Pragma("unroll") for (int m = 0; m < 4; ++m) _Pragma("unroll") for (int n = 0; n < 2; ++n) _Pragma("unroll") for (int k = 0; k < 2; ++k) \
;         acc[ai][bj][m][n] = __builtin_amdgcn_mfma_f32_16x16x32_bf16(Bt[n][k], At[m][k], acc[ai][bj][m][n], 0, 0, 0); __builtin_amdgcn_s_setprio(0); } while (0)
; #define PG8_WAIT_V(n) asm volatile("s_waitcnt vmcnt(" #n ")" ::: "memory")
; #define PG8_WAIT_L(n) asm volatile("s_waitcnt lgkmcnt(" #n ")" ::: "memory")
; #define PG8_BAR __builtin_amdgcn_s_barrier()
; #define PG8_SCHED __builtin_amdgcn_sched_barrier(0)
; template <class Epi, class Sched, bool ALIGN_EPI = false, bool SP2 = false>
; __device__ __forceinline__ void gemm_phase(PG8_LAS unsigned char* lds, const Gemm g, const Sched& S, const Epi& E) {
;     ...
;             PG8_LDB(B0, 0, 0); PG8_LDB(B1, 0, 1); PG8_SCHED; PG8_LDA(At, 0, 0); PG8_STAGE(PG8_SA(1, 1), a1 + hstep, voffA);
;             PG8_WAIT_V(8); PG8_WAIT_L(0); PG8_BAR; PG8_MMA(0, 0, At, B0); PG8_MMA(0, 1, At, B1); PG8_BAR; PG8_SCHED;
;             PG8_LDA(At, 0, 1); PG8_STAGE(PG8_SB(0, 0), b2, voffB); PG8_STAGE(PG8_SB(0, 1), b2 + hstep, voffB); PG8_STAGE(PG8_SA(0, 0), a2, voffA);
;             PG8_WAIT_V(8); PG8_WAIT_L(0); PG8_BAR; PG8_MMA(1, 0, At, B0); PG8_MMA(1, 1, At, B1); PG8_BAR; PG8_SCHED;
.LBB0_913:
	ds_read_b128 v[156:159], v152
	ds_read_b128 v[160:163], v147
	ds_read_b128 v[164:167], v152 offset:2048
	ds_read_b128 v[168:171], v147 offset:2048
	ds_read_b128 v[172:175], v153
	ds_read_b128 v[176:179], v220
	ds_read_b128 v[180:183], v153 offset:2048
	ds_read_b128 v[184:187], v220 offset:2048
	s_add_u32 s4, s34, 0xfff80080
	s_addc_u32 s5, s35, -1
	s_cmp_eq_u32 s69, 28
	s_cselect_b32 s39, s25, s5
	s_cselect_b32 s38, s65, s4
	s_cselect_b32 s37, s23, s68
	s_cselect_b32 s36, s66, s67
	s_add_i32 m0, s31, 0xc000
	ds_read_b128 v[188:191], v154
	ds_read_b128 v[192:195], v146
	ds_read_b128 v[196:199], v154 offset:2048
	ds_read_b128 v[200:203], v146 offset:2048
	ds_read_b128 v[204:207], v154 offset:4096
	ds_read_b128 v[208:211], v146 offset:4096
	ds_read_b128 v[212:215], v154 offset:6144
	ds_read_b128 v[216:219], v146 offset:6144
	global_load_lds_dwordx4 v138, s[34:35]
	s_add_i32 m0, s31, 0xe000
	s_nop 0
	global_load_lds_dwordx4 v140, s[34:35]
	s_waitcnt vmcnt(8)
	s_waitcnt lgkmcnt(0)
	s_barrier
	s_setprio 1
	s_waitcnt lgkmcnt(0)
	v_mfma_f32_16x16x32_bf16 v[126:129], v[156:159], v[188:191], v[126:129]
	v_mfma_f32_16x16x32_bf16 v[122:125], v[164:167], v[188:191], v[122:125]
	v_mfma_f32_16x16x32_bf16 v[110:113], v[156:159], v[196:199], v[110:113]
	v_mfma_f32_16x16x32_bf16 v[106:109], v[164:167], v[196:199], v[106:109]
	v_mfma_f32_16x16x32_bf16 v[94:97], v[156:159], v[204:207], v[94:97]
	v_mfma_f32_16x16x32_bf16 v[90:93], v[164:167], v[204:207], v[90:93]
	v_mfma_f32_16x16x32_bf16 v[78:81], v[156:159], v[212:215], v[78:81]
	v_mfma_f32_16x16x32_bf16 v[74:77], v[164:167], v[212:215], v[74:77]
	v_mfma_f32_16x16x32_bf16 v[126:129], v[160:163], v[192:195], v[126:129]
	v_mfma_f32_16x16x32_bf16 v[122:125], v[168:171], v[192:195], v[122:125]
	v_mfma_f32_16x16x32_bf16 v[110:113], v[160:163], v[200:203], v[110:113]
	v_mfma_f32_16x16x32_bf16 v[106:109], v[168:171], v[200:203], v[106:109]
	v_mfma_f32_16x16x32_bf16 v[94:97], v[160:163], v[208:211], v[94:97]
	v_mfma_f32_16x16x32_bf16 v[90:93], v[168:171], v[208:211], v[90:93]
	v_mfma_f32_16x16x32_bf16 v[78:81], v[160:163], v[216:219], v[78:81]
	v_mfma_f32_16x16x32_bf16 v[74:77], v[168:171], v[216:219], v[74:77]
	s_setprio 0
	s_setprio 1
	v_mfma_f32_16x16x32_bf16 v[118:121], v[172:175], v[188:191], v[118:121]
	v_mfma_f32_16x16x32_bf16 v[114:117], v[180:183], v[188:191], v[114:117]
	v_mfma_f32_16x16x32_bf16 v[102:105], v[172:175], v[196:199], v[102:105]
	v_mfma_f32_16x16x32_bf16 v[98:101], v[180:183], v[196:199], v[98:101]
	v_mfma_f32_16x16x32_bf16 v[86:89], v[172:175], v[204:207], v[86:89]
	v_mfma_f32_16x16x32_bf16 v[82:85], v[180:183], v[204:207], v[82:85]
	v_mfma_f32_16x16x32_bf16 v[70:73], v[172:175], v[212:215], v[70:73]
	v_mfma_f32_16x16x32_bf16 v[66:69], v[180:183], v[212:215], v[66:69]
	v_mfma_f32_16x16x32_bf16 v[118:121], v[176:179], v[192:195], v[118:121]
	v_mfma_f32_16x16x32_bf16 v[114:117], v[184:187], v[192:195], v[114:117]
	v_mfma_f32_16x16x32_bf16 v[102:105], v[176:179], v[200:203], v[102:105]
	v_mfma_f32_16x16x32_bf16 v[98:101], v[184:187], v[200:203], v[98:101]
	v_mfma_f32_16x16x32_bf16 v[86:89], v[176:179], v[208:211], v[86:89]
	v_mfma_f32_16x16x32_bf16 v[82:85], v[184:187], v[208:211], v[82:85]
	v_mfma_f32_16x16x32_bf16 v[70:73], v[176:179], v[216:219], v[70:73]
	v_mfma_f32_16x16x32_bf16 v[66:69], v[184:187], v[216:219], v[66:69]
	s_setprio 0
	s_barrier
	s_add_i32 s4, s61, s40
	s_mov_b32 m0, s4
	ds_read_b128 v[188:191], v154 offset:16384
	ds_read_b128 v[192:195], v146 offset:16384
	ds_read_b128 v[196:199], v154 offset:18432
	ds_read_b128 v[200:203], v146 offset:18432
	ds_read_b128 v[204:207], v154 offset:20480
	ds_read_b128 v[208:211], v146 offset:20480
	ds_read_b128 v[212:215], v154 offset:22528
	ds_read_b128 v[216:219], v146 offset:22528
	global_load_lds_dwordx4 v134, s[36:37]
	s_add_i32 m0, s4, 0x2000
	s_add_u32 s4, s36, 0x80000
	s_addc_u32 s5, s37, 0
	s_add_i32 s70, s62, s40
	global_load_lds_dwordx4 v130, s[36:37]
	s_mov_b32 m0, s70
	s_nop 0
	global_load_lds_dwordx4 v134, s[4:5]
	s_add_i32 m0, s70, 0x2000
	s_nop 0
	global_load_lds_dwordx4 v130, s[4:5]
	s_waitcnt vmcnt(6)
	s_waitcnt lgkmcnt(0)
	s_barrier
	s_setprio 1
	s_waitcnt lgkmcnt(0)
	v_mfma_f32_16x16x32_bf16 v[62:65], v[156:159], v[188:191], v[62:65]
	v_mfma_f32_16x16x32_bf16 v[58:61], v[164:167], v[188:191], v[58:61]
	v_mfma_f32_16x16x32_bf16 v[46:49], v[156:159], v[196:199], v[46:49]
	v_mfma_f32_16x16x32_bf16 v[42:45], v[164:167], v[196:199], v[42:45]
	v_mfma_f32_16x16x32_bf16 v[30:33], v[156:159], v[204:207], v[30:33]
	v_mfma_f32_16x16x32_bf16 v[26:29], v[164:167], v[204:207], v[26:29]
	v_mfma_f32_16x16x32_bf16 v[14:17], v[156:159], v[212:215], v[14:17]
	v_mfma_f32_16x16x32_bf16 v[10:13], v[164:167], v[212:215], v[10:13]
	v_mfma_f32_16x16x32_bf16 v[62:65], v[160:163], v[192:195], v[62:65]
	v_mfma_f32_16x16x32_bf16 v[58:61], v[168:171], v[192:195], v[58:61]
	v_mfma_f32_16x16x32_bf16 v[46:49], v[160:163], v[200:203], v[46:49]
	v_mfma_f32_16x16x32_bf16 v[42:45], v[168:171], v[200:203], v[42:45]
	v_mfma_f32_16x16x32_bf16 v[30:33], v[160:163], v[208:211], v[30:33]
	v_mfma_f32_16x16x32_bf16 v[26:29], v[168:171], v[208:211], v[26:29]
	v_mfma_f32_16x16x32_bf16 v[14:17], v[160:163], v[216:219], v[14:17]
	v_mfma_f32_16x16x32_bf16 v[10:13], v[168:171], v[216:219], v[10:13]
	s_setprio 0
	s_setprio 1
	v_mfma_f32_16x16x32_bf16 v[54:57], v[172:175], v[188:191], v[54:57]
	v_mfma_f32_16x16x32_bf16 v[50:53], v[180:183], v[188:191], v[50:53]
	v_mfma_f32_16x16x32_bf16 v[38:41], v[172:175], v[196:199], v[38:41]
	v_mfma_f32_16x16x32_bf16 v[34:37], v[180:183], v[196:199], v[34:37]
	v_mfma_f32_16x16x32_bf16 v[22:25], v[172:175], v[204:207], v[22:25]
	v_mfma_f32_16x16x32_bf16 v[18:21], v[180:183], v[204:207], v[18:21]
	v_mfma_f32_16x16x32_bf16 v[6:9], v[172:175], v[212:215], v[6:9]
	v_mfma_f32_16x16x32_bf16 v[2:5], v[180:183], v[212:215], v[2:5]
	v_mfma_f32_16x16x32_bf16 v[54:57], v[176:179], v[192:195], v[54:57]
	v_mfma_f32_16x16x32_bf16 v[50:53], v[184:187], v[192:195], v[50:53]
	v_mfma_f32_16x16x32_bf16 v[38:41], v[176:179], v[200:203], v[38:41]
	v_mfma_f32_16x16x32_bf16 v[34:37], v[184:187], v[200:203], v[34:37]
	v_mfma_f32_16x16x32_bf16 v[22:25], v[176:179], v[208:211], v[22:25]
	v_mfma_f32_16x16x32_bf16 v[18:21], v[184:187], v[208:211], v[18:21]
	v_mfma_f32_16x16x32_bf16 v[6:9], v[176:179], v[216:219], v[6:9]
	v_mfma_f32_16x16x32_bf16 v[2:5], v[184:187], v[216:219], v[2:5]
	s_setprio 0
	s_barrier
; #define PG8_STAGE(bufoff, gbase, voff) do { _Pragma("unroll") for (int _i = 0; _i < 2; ++_i) \
;         __builtin_amdgcn_global_load_lds((const unsigned*)((const char*)(gbase) + (voff)[_i]), (PG8_LAS unsigned*)(lds + (bufoff) + ldsw + _i * 8192), 16, 0, 0); } while (0)
; #define PG8_LDA(dst, b, h) do { _Pragma("unroll") for (int m = 0; m < 4; ++m) _Pragma("unroll") for (int k = 0; k < 2; ++k) dst[m][k] = *(const PG8_LAS bf16x8*)(lds + PG8_SA(b, h) + aoff + m * 2048 + k * 1024); } while (0)
; #define PG8_LDB(dst, b, h) do { _Pragma("unroll") for (int n = 0; n < 2; ++n) _Pragma("unroll") for (int k = 0; k < 2; ++k) dst[n][k] = *(const PG8_LAS bf16x8*)(lds + PG8_SB(b, h) + boff + n * 2048 + k * 1024); } while (0)
; #define PG8_MMA(ai, bj, At, Bt) do { __builtin_amdgcn_s_setprio(1); _Pragma("unroll") for (int m = 0; m < 4; ++m) _Pragma("unroll") for (int n = 0; n < 2; ++n) _Pragma("unroll") for (int k = 0; k < 2; ++k) \
;         acc[ai][bj][m][n] = __builtin_amdgcn_mfma_f32_16x16x32_bf16(Bt[n][k], At[m][k], acc[ai][bj][m][n], 0, 0, 0); __builtin_amdgcn_s_setprio(0); } while (0)
; #define PG8_WAIT_V(n) asm volatile("s_waitcnt vmcnt(" #n ")" ::: "memory")
; #define PG8_WAIT_L(n) asm volatile("s_waitcnt lgkmcnt(" #n ")" ::: "memory")
; #define PG8_BAR __builtin_amdgcn_s_barrier()
; #define PG8_SCHED __builtin_amdgcn_sched_barrier(0)
; template <class Epi, class Sched, bool ALIGN_EPI = false, bool SP2 = false>
; __device__ __forceinline__ void gemm_phase(PG8_LAS unsigned char* lds, const Gemm g, const Sched& S, const Epi& E) {
;     ...
;             PG8_LDB(B0, 1, 0); PG8_LDB(B1, 1, 1); PG8_SCHED; PG8_LDA(At, 1, 0); PG8_STAGE(PG8_SA(0, 1), a2 + hstep, voffA);
;             PG8_WAIT_V(8); PG8_WAIT_L(0); PG8_BAR; PG8_MMA(0, 0, At, B0); PG8_MMA(0, 1, At, B1); PG8_BAR; PG8_SCHED;
;             PG8_LDA(At, 1, 1); PG8_STAGE(PG8_SB(1, 0), b3, voffB); PG8_STAGE(PG8_SB(1, 1), b3 + hstep, voffB); PG8_STAGE(PG8_SA(1, 0), a3, voffA);
;             PG8_WAIT_V(8); PG8_WAIT_L(0); PG8_BAR; PG8_MMA(1, 0, At, B0); PG8_MMA(1, 1, At, B1); PG8_BAR; PG8_SCHED;
	s_add_i32 s70, 0, 0x18000
	s_add_i32 s71, 0, 0x1c000
	ds_read_b128 v[156:159], v221
	ds_read_b128 v[160:163], v222
	ds_read_b128 v[164:167], v221 offset:2048
	ds_read_b128 v[168:171], v222 offset:2048
	ds_read_b128 v[172:175], v223
	ds_read_b128 v[176:179], v224
	ds_read_b128 v[180:183], v223 offset:2048
	ds_read_b128 v[184:187], v224 offset:2048
	s_add_u32 s4, s38, 0x80000
	s_addc_u32 s5, s39, 0
	s_mov_b32 m0, s31
	s_nop 0
	global_load_lds_dwordx4 v136, s[38:39]
	s_mov_b32 m0, s49
	s_nop 0
	global_load_lds_dwordx4 v132, s[38:39]
	s_mov_b32 m0, s50
	ds_read_b128 v[188:191], v154 offset:32768
	ds_read_b128 v[192:195], v146 offset:32768
	ds_read_b128 v[196:199], v154 offset:34816
	ds_read_b128 v[200:203], v146 offset:34816
	ds_read_b128 v[204:207], v154 offset:36864
	ds_read_b128 v[208:211], v146 offset:36864
	ds_read_b128 v[212:215], v154 offset:38912
	ds_read_b128 v[216:219], v146 offset:38912
	global_load_lds_dwordx4 v136, s[4:5]
	s_mov_b32 m0, s51
	s_nop 0
	global_load_lds_dwordx4 v132, s[4:5]
	s_waitcnt vmcnt(8)
	s_waitcnt lgkmcnt(0)
	s_barrier
	s_setprio 1
	s_waitcnt lgkmcnt(0)
	v_mfma_f32_16x16x32_bf16 v[126:129], v[156:159], v[188:191], v[126:129]
	v_mfma_f32_16x16x32_bf16 v[122:125], v[164:167], v[188:191], v[122:125]
	v_mfma_f32_16x16x32_bf16 v[110:113], v[156:159], v[196:199], v[110:113]
	v_mfma_f32_16x16x32_bf16 v[106:109], v[164:167], v[196:199], v[106:109]
	v_mfma_f32_16x16x32_bf16 v[94:97], v[156:159], v[204:207], v[94:97]
	v_mfma_f32_16x16x32_bf16 v[90:93], v[164:167], v[204:207], v[90:93]
	v_mfma_f32_16x16x32_bf16 v[78:81], v[156:159], v[212:215], v[78:81]
	v_mfma_f32_16x16x32_bf16 v[74:77], v[164:167], v[212:215], v[74:77]
	v_mfma_f32_16x16x32_bf16 v[126:129], v[160:163], v[192:195], v[126:129]
	v_mfma_f32_16x16x32_bf16 v[122:125], v[168:171], v[192:195], v[122:125]
	v_mfma_f32_16x16x32_bf16 v[110:113], v[160:163], v[200:203], v[110:113]
	v_mfma_f32_16x16x32_bf16 v[106:109], v[168:171], v[200:203], v[106:109]
	v_mfma_f32_16x16x32_bf16 v[94:97], v[160:163], v[208:211], v[94:97]
	v_mfma_f32_16x16x32_bf16 v[90:93], v[168:171], v[208:211], v[90:93]
	v_mfma_f32_16x16x32_bf16 v[78:81], v[160:163], v[216:219], v[78:81]
	v_mfma_f32_16x16x32_bf16 v[74:77], v[168:171], v[216:219], v[74:77]
	s_setprio 0
	s_setprio 1
	v_mfma_f32_16x16x32_bf16 v[118:121], v[172:175], v[188:191], v[118:121]
	v_mfma_f32_16x16x32_bf16 v[114:117], v[180:183], v[188:191], v[114:117]
	v_mfma_f32_16x16x32_bf16 v[102:105], v[172:175], v[196:199], v[102:105]
	v_mfma_f32_16x16x32_bf16 v[98:101], v[180:183], v[196:199], v[98:101]
	v_mfma_f32_16x16x32_bf16 v[86:89], v[172:175], v[204:207], v[86:89]
	v_mfma_f32_16x16x32_bf16 v[82:85], v[180:183], v[204:207], v[82:85]
	v_mfma_f32_16x16x32_bf16 v[70:73], v[172:175], v[212:215], v[70:73]
	v_mfma_f32_16x16x32_bf16 v[66:69], v[180:183], v[212:215], v[66:69]
	v_mfma_f32_16x16x32_bf16 v[118:121], v[176:179], v[192:195], v[118:121]
	v_mfma_f32_16x16x32_bf16 v[114:117], v[184:187], v[192:195], v[114:117]
	v_mfma_f32_16x16x32_bf16 v[102:105], v[176:179], v[200:203], v[102:105]
	v_mfma_f32_16x16x32_bf16 v[98:101], v[184:187], v[200:203], v[98:101]
	v_mfma_f32_16x16x32_bf16 v[86:89], v[176:179], v[208:211], v[86:89]
	v_mfma_f32_16x16x32_bf16 v[82:85], v[184:187], v[208:211], v[82:85]
	v_mfma_f32_16x16x32_bf16 v[70:73], v[176:179], v[216:219], v[70:73]
	v_mfma_f32_16x16x32_bf16 v[66:69], v[184:187], v[216:219], v[66:69]
	s_setprio 0
	s_barrier
	s_add_i32 s4, s70, s40
	s_add_i32 m0, s4, 0xffffff80
	ds_read_b128 v[188:191], v154 offset:49152
	ds_read_b128 v[192:195], v146 offset:49152
	ds_read_b128 v[196:199], v154 offset:51200
	ds_read_b128 v[200:203], v146 offset:51200
	ds_read_b128 v[204:207], v154 offset:53248
	ds_read_b128 v[208:211], v146 offset:53248
	ds_read_b128 v[212:215], v154 offset:55296
	ds_read_b128 v[216:219], v146 offset:55296
	global_load_lds_dwordx4 v134, s[36:37] offset:128
	s_add_i32 m0, s4, 0x1f80
	s_add_u32 s4, s36, 0x80080
	s_addc_u32 s5, s37, 0
	global_load_lds_dwordx4 v130, s[36:37] offset:128
	s_add_i32 s36, s71, s40
	s_mov_b32 m0, s36
	s_nop 0
	global_load_lds_dwordx4 v134, s[4:5]
	s_add_i32 m0, s36, 0x2000
	s_nop 0
	global_load_lds_dwordx4 v130, s[4:5]
	s_add_i32 m0, s53, 0xffffff80
	s_nop 0
	global_load_lds_dwordx4 v136, s[38:39] offset:128
	s_add_i32 m0, s58, 0xffffff80
	s_nop 0
	global_load_lds_dwordx4 v132, s[38:39] offset:128
	s_waitcnt vmcnt(8)
	s_waitcnt lgkmcnt(0)
	s_barrier
	s_setprio 1
	s_waitcnt lgkmcnt(0)
	v_mfma_f32_16x16x32_bf16 v[62:65], v[156:159], v[188:191], v[62:65]
	v_mfma_f32_16x16x32_bf16 v[58:61], v[164:167], v[188:191], v[58:61]
	v_mfma_f32_16x16x32_bf16 v[46:49], v[156:159], v[196:199], v[46:49]
	v_mfma_f32_16x16x32_bf16 v[42:45], v[164:167], v[196:199], v[42:45]
	v_mfma_f32_16x16x32_bf16 v[30:33], v[156:159], v[204:207], v[30:33]
	v_mfma_f32_16x16x32_bf16 v[26:29], v[164:167], v[204:207], v[26:29]
	v_mfma_f32_16x16x32_bf16 v[14:17], v[156:159], v[212:215], v[14:17]
	v_mfma_f32_16x16x32_bf16 v[10:13], v[164:167], v[212:215], v[10:13]
	v_mfma_f32_16x16x32_bf16 v[62:65], v[160:163], v[192:195], v[62:65]
	v_mfma_f32_16x16x32_bf16 v[58:61], v[168:171], v[192:195], v[58:61]
	v_mfma_f32_16x16x32_bf16 v[46:49], v[160:163], v[200:203], v[46:49]
	v_mfma_f32_16x16x32_bf16 v[42:45], v[168:171], v[200:203], v[42:45]
	v_mfma_f32_16x16x32_bf16 v[30:33], v[160:163], v[208:211], v[30:33]
	v_mfma_f32_16x16x32_bf16 v[26:29], v[168:171], v[208:211], v[26:29]
	v_mfma_f32_16x16x32_bf16 v[14:17], v[160:163], v[216:219], v[14:17]
	v_mfma_f32_16x16x32_bf16 v[10:13], v[168:171], v[216:219], v[10:13]
	s_setprio 0
	s_setprio 1
	v_mfma_f32_16x16x32_bf16 v[54:57], v[172:175], v[188:191], v[54:57]
	v_mfma_f32_16x16x32_bf16 v[50:53], v[180:183], v[188:191], v[50:53]
	v_mfma_f32_16x16x32_bf16 v[38:41], v[172:175], v[196:199], v[38:41]
	v_mfma_f32_16x16x32_bf16 v[34:37], v[180:183], v[196:199], v[34:37]
	v_mfma_f32_16x16x32_bf16 v[22:25], v[172:175], v[204:207], v[22:25]
	v_mfma_f32_16x16x32_bf16 v[18:21], v[180:183], v[204:207], v[18:21]
	v_mfma_f32_16x16x32_bf16 v[6:9], v[172:175], v[212:215], v[6:9]
	v_mfma_f32_16x16x32_bf16 v[2:5], v[180:183], v[212:215], v[2:5]
	v_mfma_f32_16x16x32_bf16 v[54:57], v[176:179], v[192:195], v[54:57]
	v_mfma_f32_16x16x32_bf16 v[50:53], v[184:187], v[192:195], v[50:53]
	v_mfma_f32_16x16x32_bf16 v[38:41], v[176:179], v[200:203], v[38:41]
	v_mfma_f32_16x16x32_bf16 v[34:37], v[184:187], v[200:203], v[34:37]
	v_mfma_f32_16x16x32_bf16 v[22:25], v[176:179], v[208:211], v[22:25]
	v_mfma_f32_16x16x32_bf16 v[18:21], v[184:187], v[208:211], v[18:21]
	v_mfma_f32_16x16x32_bf16 v[6:9], v[176:179], v[216:219], v[6:9]
	v_mfma_f32_16x16x32_bf16 v[2:5], v[184:187], v[216:219], v[2:5]
	s_setprio 0
	s_barrier
	s_add_i32 s69, s69, 2
	s_add_u32 s34, s34, 0x100
	s_addc_u32 s35, s35, 0
	s_add_u32 s67, s67, 0x100
	s_addc_u32 s68, s68, 0
	s_cmp_gt_u32 s69, 29
	s_cbranch_scc0 .LBB0_913
	s_and_b64 vcc, exec, s[20:21]
	s_cbranch_vccz .LBB0_916
	s_barrier

; #define PG8_STAGE(bufoff, gbase, voff) do { _Pragma("unroll") for (int _i = 0; _i < 2; ++_i) \
;         __builtin_amdgcn_global_load_lds((const unsigned*)((const char*)(gbase) + (voff)[_i]), (PG8_LAS unsigned*)(lds + (bufoff) + ldsw + _i * 8192), 16, 0, 0); } while (0)
; #define PG8_WAIT_V(n) asm volatile("s_waitcnt vmcnt(" #n ")" ::: "memory")
; #define PG8_BAR __builtin_amdgcn_s_barrier()
; template <class Epi, class Sched, bool ALIGN_EPI = false, bool SP2 = false>
; __device__ __forceinline__ void gemm_phase(PG8_LAS unsigned char* lds, const Gemm g, const Sched& S, const Epi& E) {
;     ...
;     unsigned voffA[2], voffB[2];
; #pragma unroll
;     for (int i = 0; i < 2; ++i) { int R, C; stage_rc(tid * 16 + i * 8192, R, C); const int Rb = Epi::PERM ? ((R & ~31) + perm32(R & 31)) : R;
;         voffA[i] = (unsigned)(R * K + C) * 2u; voffB[i] = (unsigned)(Rb * K + C) * 2u; }
;     ...
;     const char* cA = (const char*)g.A + (size_t)cur.pm * tstep; const char* cB = (const char*)g.Bt + (size_t)cur.pn * tstep;
;     S.a_ready(cur);
;     if constexpr (SP2) {
;         PG8_STAGE(PG8_SB(0, 0), cB, voffB); PG8_STAGE(PG8_SB(0, 1), cB + hstep, voffB); PG8_STAGE(PG8_SA(0, 0), cA, voffA); PG8_STAGE(PG8_SA(0, 1), cA + hstep, voffA);
;         if (wr == 1) PG8_BAR;
;         PG8_WAIT_V(2); PG8_BAR;
.LBB0_1001:
	v_ashrrev_i32_e32 v2, 31, v10
	v_lshrrev_b32_e32 v2, 26, v2
	v_add_u32_e32 v2, v10, v2
	v_ashrrev_i32_e32 v11, 6, v2
	v_bfe_i32 v2, v10, 27, 1
	v_lshlrev_b32_e32 v1, 4, v10
	v_lshrrev_b32_e32 v2, 22, v2
	v_add_u32_e32 v2, v1, v2
	v_and_b32_e32 v2, 0xfffffc00, v2
	v_sub_u32_e32 v2, v1, v2
	v_lshrrev_b32_e32 v3, 4, v2
	v_bitop3_b32 v2, v3, v2, 32 bitop3:0x6c
	v_ashrrev_i32_e32 v4, 31, v2
	v_lshrrev_b32_e32 v4, 26, v4
	v_lshlrev_b32_e32 v3, 3, v11
	v_add_u32_e32 v4, v2, v4
	v_and_b32_e32 v3, -16, v3
	v_ashrrev_i32_e32 v12, 6, v4
	v_and_b32_e32 v4, 0xc0, v4
	v_add_u32_e32 v3, v12, v3
	s_waitcnt lgkmcnt(0)
	v_lshlrev_b32_e32 v5, 5, v11
	v_sub_u32_e32 v2, v2, v4
	v_mov_b32_e32 v4, 1
	v_and_b32_e32 v13, 32, v5
	v_ashrrev_i16_sdwa v2, v4, sext(v2) dst_sel:DWORD dst_unused:UNUSED_PAD src0_sel:DWORD src1_sel:BYTE_0
	v_lshlrev_b32_e32 v5, 1, v3
	v_lshrrev_b32_e32 v6, 2, v3
	v_and_b32_e32 v7, 3, v12
	s_mov_b32 s4, 0x7fffe0
	v_bfe_i32 v14, v2, 0, 16
	v_and_b32_e32 v5, 24, v5
	v_and_b32_e32 v6, 4, v6
	v_and_or_b32 v7, v3, s4, v7
	s_movk_i32 s6, 0x1600
	v_add_u32_e32 v2, v13, v14
	v_or3_b32 v5, v7, v6, v5
	v_mul_lo_u32 v3, v3, s6
	v_and_b32_e32 v158, 63, v0
	v_lshrrev_b32_e32 v159, 6, v0
	v_lshrrev_b32_e32 v160, 3, v158
	v_lshl_add_u32 v160, v159, 3, v160
	v_and_b32_e32 v161, 1, v159
	v_lshrrev_b32_e32 v162, 4, v158
	v_lshl_add_u32 v161, v161, 2, v162
	v_and_b32_e32 v162, 7, v158
	v_xor_b32_e32 v161, v161, v162
	v_lshlrev_b32_e32 v161, 4, v161
	v_mul_u32_u24_e32 v162, 0x2c00, v160
	v_add_u32_e32 v154, v162, v161
	v_add_u32_e32 v155, 0xb0000, v154
	v_and_b32_e32 v162, 31, v160
	v_bfe_u32 v163, v162, 2, 2
	v_lshlrev_b32_e32 v163, 3, v163
	v_lshrrev_b32_e32 v158, 4, v162
	v_lshl_add_u32 v163, v158, 2, v163
	v_and_b32_e32 v158, 3, v162
	v_add_u32_e32 v163, v163, v158
	v_and_b32_e32 v158, -32, v160
	v_add_u32_e32 v163, v163, v158
	v_mul_u32_u24_e32 v163, 0x2c00, v163
	v_add_u32_e32 v156, v163, v161
	v_add_u32_e32 v157, 0xb0000, v156
	v_mov_b32_e32 v130, v154
	v_mul_u32_u24_e32 v3, 0x1600, v5
	v_add_u32_e32 v1, 0x2000, v1
	v_mov_b32_e32 v132, v156
	v_ashrrev_i32_e32 v2, 31, v1
	v_lshrrev_b32_e32 v2, 22, v2
	v_add_u32_e32 v2, v1, v2
	v_ashrrev_i32_e32 v15, 10, v2
	v_mul_i32_i24_e32 v2, 0x400, v15
	v_sub_u32_e32 v1, v1, v2
	v_lshrrev_b32_e32 v2, 4, v1
	v_bitop3_b32 v1, v2, v1, 32 bitop3:0x6c
	v_ashrrev_i32_e32 v3, 31, v1
	v_lshrrev_b32_e32 v3, 26, v3
	v_lshlrev_b32_e32 v2, 3, v15
	v_add_u32_e32 v3, v1, v3
	v_and_b32_e32 v2, -16, v2
	v_ashrrev_i32_e32 v16, 6, v3
	v_lshlrev_b32_e32 v5, 5, v15
	s_add_u32 s40, s42, 0x5800000
	v_add_u32_e32 v2, v16, v2
	v_and_b32_e32 v17, 32, v5
	v_and_b32_e32 v5, 3, v16
	s_addc_u32 s41, s43, 0
	v_and_or_b32 v5, v2, s4, v5
	s_add_i32 s4, s14, s15
	s_ashr_i32 s5, s4, 31
	s_lshr_b32 s5, s5, 26
	s_add_i32 s5, s4, s5
	s_ashr_i32 s14, s5, 6
	s_and_b32 s5, s5, 0xffc0
	s_sub_i32 s4, s4, s5
	s_bfe_i32 s5, s4, 0x80000
	s_bfe_u32 s5, s5, 0x3000c
	s_add_i32 s5, s4, s5
	s_bfe_i32 s15, s5, 0x80000
	s_and_b32 s5, s5, 0xf8
	s_sub_i32 s4, s4, s5
	s_lshl_b32 s14, s14, 3
	s_sext_i32_i16 s15, s15
	s_sext_i32_i8 s4, s4
	s_ashr_i32 s7, s8, 6
	v_and_b32_e32 v3, 0xc0, v3
	s_add_i32 s70, s14, s4
	s_ashr_i32 s4, s15, 3
	v_sub_u32_e32 v1, v1, v3
	s_ashr_i32 s9, s8, 8
	s_lshl_b32 s48, s7, 10
	s_lshr_b32 s18, s15, 3
	s_mul_hi_i32 s5, s4, 0x2c0000
	s_mul_i32 s4, s4, 0x2c0000
	v_ashrrev_i16_sdwa v1, v4, sext(v1) dst_sel:DWORD dst_unused:UNUSED_PAD src0_sel:DWORD src1_sel:BYTE_0
	v_lshlrev_b32_e32 v3, 1, v2
	v_lshrrev_b32_e32 v4, 2, v2
	s_add_u32 s34, s40, s4
	v_bfe_i32 v18, v1, 0, 16
	v_and_b32_e32 v3, 24, v3
	v_and_b32_e32 v4, 4, v4
	s_addc_u32 s35, s41, s5
	s_add_i32 s49, s48, 0
	v_add_u32_e32 v1, v17, v18
	v_or3_b32 v3, v5, v4, v3
	v_mul_lo_u32 v2, v2, s6
	s_add_i32 m0, s49, 0x10000
	v_mov_b32_e32 v134, v155
	v_mul_u32_u24_e32 v2, 0x1600, v3
	global_load_lds_dwordx4 v132, s[34:35]
	s_add_i32 m0, s49, 0x12000
	v_mov_b32_e32 v136, v157
	s_add_u32 s4, s34, 0x160000
	global_load_lds_dwordx4 v136, s[34:35]
	s_addc_u32 s5, s35, 0
	s_add_i32 m0, s49, 0x14000
	s_mul_i32 s16, s70, 0x2c0000
	global_load_lds_dwordx4 v132, s[4:5]
	s_add_i32 m0, s49, 0x16000
	s_mul_hi_i32 s14, s70, 0x2c0000
	s_add_u32 s30, s56, s16
	s_addc_u32 s31, s57, s14
	s_add_i32 s50, s49, 0x2000
	global_load_lds_dwordx4 v136, s[4:5]
	s_mov_b32 m0, s49
	s_add_u32 s4, s30, 0x160000
	global_load_lds_dwordx4 v130, s[30:31]
	s_mov_b32 m0, s50
	s_addc_u32 s5, s31, 0
	s_add_i32 s51, s49, 0x4000
	global_load_lds_dwordx4 v134, s[30:31]
	s_mov_b32 m0, s51
	s_add_i32 s52, s49, 0x6000
	global_load_lds_dwordx4 v130, s[4:5]
	s_mov_b32 m0, s52
	v_mov_b32_e32 v133, 0
	global_load_lds_dwordx4 v134, s[4:5]
	v_mov_b32_e32 v137, v133
	v_mov_b32_e32 v131, v133
	v_mov_b32_e32 v135, v133
	s_cmp_eq_u32 s9, 1
	s_mov_b32 s53, 0
	v_lshl_add_u64 v[8:9], s[34:35], 0, v[132:133]
	v_lshl_add_u64 v[4:5], s[34:35], 0, v[136:137]
	s_mov_b32 s20, 0x16000
	v_lshl_add_u64 v[2:3], s[30:31], 0, v[130:131]
	s_cselect_b64 s[14:15], -1, 0
	s_cmp_lg_u32 s9, 1
	v_lshl_add_u64 v[6:7], s[30:31], 0, v[134:135]
	s_cbranch_scc1 .LBB0_1003
	s_barrier
; #define PG8_STAGE(bufoff, gbase, voff) do { _Pragma("unroll") for (int _i = 0; _i < 2; ++_i) \
;         __builtin_amdgcn_global_load_lds((const unsigned*)((const char*)(gbase) + (voff)[_i]), (PG8_LAS unsigned*)(lds + (bufoff) + ldsw + _i * 8192), 16, 0, 0); } while (0)
; #define PG8_WAIT_V(n) asm volatile("s_waitcnt vmcnt(" #n ")" ::: "memory")
; #define PG8_BAR __builtin_amdgcn_s_barrier()
; template <class Epi, class Sched, bool ALIGN_EPI = false, bool SP2 = false>
; __device__ __forceinline__ void gemm_phase(PG8_LAS unsigned char* lds, const Gemm g, const Sched& S, const Epi& E) {
;     ...
;     const size_t kstep = (size_t)(BK * 2);
;     const size_t hstep = (size_t)HALF * K * 2;
;     const size_t tstep = 2 * hstep;
;     const unsigned ldsw = (unsigned)wid * 1024u;
;     const int aoff = lds_byte(wr * 64 + fr, fq * 8), boff = lds_byte(wc * 32 + fr, fq * 8);
;     ...
;         PG8_STAGE(PG8_SB(1, 0), cB + kstep, voffB); PG8_STAGE(PG8_SA(1, 0), cA + kstep, voffA); PG8_STAGE(PG8_SB(1, 1), cB + hstep + kstep, voffB);
;         PG8_WAIT_V(6); PG8_BAR;
.LBB0_1003:
	s_lshl_b32 s4, s7, 5
	s_mov_b64 s[16:17], 0x80
	s_and_b32 s7, s4, 0x60
	s_add_i32 m0, s49, 0x18000
	v_lshl_add_u64 v[8:9], v[8:9], 0, s[16:17]
	s_lshl_b32 s19, s9, 13
	s_lshl_b32 s21, s7, 7
	s_waitcnt vmcnt(2)
	s_barrier
	global_load_lds_dwordx4 v[8:9], off
	v_lshl_add_u64 v[4:5], v[4:5], 0, s[16:17]
	s_add_i32 m0, s49, 0x1a000
	s_add_i32 s58, s49, 0x8000
	s_add_i32 s59, s49, 0xa000
	global_load_lds_dwordx4 v[4:5], off
	v_lshl_add_u64 v[2:3], v[2:3], 0, s[16:17]
	s_mov_b32 m0, s58
	s_add_u32 s4, s34, 0x160080
	global_load_lds_dwordx4 v[2:3], off
	v_lshl_add_u64 v[2:3], v[6:7], 0, s[16:17]
	s_mov_b32 m0, s59
	s_addc_u32 s5, s35, 0
	global_load_lds_dwordx4 v[2:3], off
	s_add_i32 m0, s49, 0x1c000
	v_lshl_add_u64 v[2:3], s[4:5], 0, v[132:133]
	global_load_lds_dwordx4 v[2:3], off
	v_lshl_add_u64 v[2:3], s[4:5], 0, v[136:137]
	s_add_i32 m0, s49, 0x1e000
	s_cmpk_lt_u32 s8, 0x100
	global_load_lds_dwordx4 v[2:3], off
	v_lshrrev_b32_e32 v3, 1, v10
	v_and_b32_e32 v3, 24, v3
	v_and_b32_e32 v2, 15, v10
	v_lshlrev_b32_e32 v4, 1, v3
	v_lshl_or_b32 v1, s9, 6, v2
	v_lshl_or_b32 v2, v2, 6, v4
	v_lshlrev_b32_e32 v4, 2, v10
	v_and_b32_e32 v4, 32, v4
	v_bitop3_b32 v5, v2, s19, v4 bitop3:0xde
	v_bitop3_b32 v148, v2, s21, v4 bitop3:0xde
	v_or_b32_e32 v149, s7, v3
	v_lshrrev_b32_e32 v3, 1, v11
	v_mul_lo_u32 v2, v12, s6
	v_mad_u64_u32 v[2:3], s[8:9], v3, s20, v[2:3]
	v_or_b32_e32 v2, v2, v13
	s_mov_b64 s[4:5], 0x160080
	v_add_lshl_u32 v2, v2, v14, 1
	v_mov_b32_e32 v3, v133
	v_lshl_add_u64 v[138:139], v[2:3], 0, s[4:5]
	v_lshrrev_b32_e32 v3, 1, v15
	v_mul_lo_u32 v2, v16, s6
	v_mad_u64_u32 v[2:3], s[6:7], v3, s20, v[2:3]
	s_waitcnt vmcnt(6)
	v_or_b32_e32 v2, v2, v17
	s_sext_i32_i8 s71, s18
	s_cselect_b64 s[18:19], -1, 0
	v_add_lshl_u32 v2, v2, v18, 1
	v_mov_b32_e32 v3, v133
	s_add_i32 s62, 0, 0x10000
	s_add_i32 s63, 0, 0x14000
	s_ashr_i32 s60, s46, 31
	s_mov_b32 s61, s46
	v_lshl_add_u64 v[140:141], v[2:3], 0, s[4:5]
	v_and_b32_e32 v158, 63, v0
	v_lshrrev_b32_e32 v159, 6, v0
	v_lshrrev_b32_e32 v160, 1, v159
	v_lshrrev_b32_e32 v161, 2, v158
	v_lshl_add_u32 v160, v160, 4, v161
	v_and_b32_e32 v161, 3, v158
	v_lshlrev_b32_e32 v161, 4, v161
	v_bfe_u32 v162, v158, 5, 1
	v_lshlrev_b32_e32 v162, 5, v162
	v_xor_b32_e32 v161, v161, v162
	v_and_b32_e32 v162, 1, v159
	v_lshl_add_u32 v161, v162, 6, v161
	v_mul_u32_u24_e32 v160, 0x2c00, v160
	v_add_u32_e32 v160, v160, v161
	v_sub_u32_e32 v160, v130, v160
	v_add_u32_e32 v138, v138, v160
	v_add_u32_e32 v140, v140, v160
	v_mov_b64_e32 v[142:143], 0x200
	v_mov_b64_e32 v[144:145], 0x1ff
	v_add_u32_e32 v150, s62, v148
	v_add_u32_e32 v151, s63, v148
	v_add_u32_e32 v152, 0, v5
	s_mov_b64 s[20:21], 0x80000
	s_mov_b32 s64, 0x80000
	s_mov_b64 s[22:23], 0x90000
	s_mov_b32 s65, 0x90000
	s_mov_b64 s[24:25], 0xa0000
	s_mov_b32 s66, 0xa0000
	s_mov_b64 s[26:27], 0xb0000
	s_mov_b32 s67, 0xb0000
	s_barrier
	s_branch .LBB0_1006

; #define PG8_STAGE(bufoff, gbase, voff) do { _Pragma("unroll") for (int _i = 0; _i < 2; ++_i) \
;         __builtin_amdgcn_global_load_lds((const unsigned*)((const char*)(gbase) + (voff)[_i]), (PG8_LAS unsigned*)(lds + (bufoff) + ldsw + _i * 8192), 16, 0, 0); } while (0)
; #define PG8_LDA(dst, b, h) do { _Pragma("unroll") for (int m = 0; m < 4; ++m) _Pragma("unroll") for (int k = 0; k < 2; ++k) dst[m][k] = *(const PG8_LAS bf16x8*)(lds + PG8_SA(b, h) + aoff + m * 2048 + k * 1024); } while (0)
; #define PG8_LDB(dst, b, h) do { _Pragma("unroll") for (int n = 0; n < 2; ++n) _Pragma("unroll") for (int k = 0; k < 2; ++k) dst[n][k] = *(const PG8_LAS bf16x8*)(lds + PG8_SB(b, h) + boff + n * 2048 + k * 1024); } while (0)
; #define PG8_MMA(ai, bj, At, Bt) do { __builtin_amdgcn_s_setprio(1); _Pragma("unroll") for (int m = 0; m < 4; ++m) _Pragma("unroll") for (int n = 0; n < 2; ++n) _Pragma("unroll") for (int k = 0; k < 2; ++k) \
;         acc[ai][bj][m][n] = __builtin_amdgcn_mfma_f32_16x16x32_bf16(Bt[n][k], At[m][k], acc[ai][bj][m][n], 0, 0, 0); __builtin_amdgcn_s_setprio(0); } while (0)
; #define PG8_WAIT_V(n) asm volatile("s_waitcnt vmcnt(" #n ")" ::: "memory")
; #define PG8_WAIT_L(n) asm volatile("s_waitcnt lgkmcnt(" #n ")" ::: "memory")
; #define PG8_BAR __builtin_amdgcn_s_barrier()
; #define PG8_SCHED __builtin_amdgcn_sched_barrier(0)
; template <class Epi, class Sched, bool ALIGN_EPI = false, bool SP2 = false>
; __device__ __forceinline__ void gemm_phase(PG8_LAS unsigned char* lds, const Gemm g, const Sched& S, const Epi& E) {
;     ...
;             PG8_LDB(B0, 0, 0); PG8_LDB(B1, 0, 1); PG8_SCHED; PG8_LDA(At, 0, 0); PG8_STAGE(PG8_SA(1, 1), a1 + hstep, voffA);
;             PG8_WAIT_V(8); PG8_WAIT_L(0); PG8_BAR; PG8_MMA(0, 0, At, B0); PG8_MMA(0, 1, At, B1); PG8_BAR; PG8_SCHED;
;     ...
;         if (!has_next) break;
; #pragma unroll
;         for (int a = 0; a < 2; ++a)
; #pragma unroll
;             for (int b = 0; b < 2; ++b)
; #pragma unroll
;                 for (int m = 0; m < 4; ++m)
; #pragma unroll
;                     for (int n = 0; n < 2; ++n) acc[a][b][m][n] = (f32x4){0.f, 0.f, 0.f, 0.f};
;         cur = nxt; cA = nA; cB = nB; ++ui;
.LBB0_1016:
	s_add_u32 s72, s34, 0x100
	v_mov_b32_e32 v2, 0
	s_addc_u32 s73, s35, 0
	s_mov_b32 s74, -2
	v_mov_b32_e32 v3, v2
	v_mov_b32_e32 v4, v2
	v_mov_b32_e32 v5, v2
	v_mov_b32_e32 v6, v2
	v_mov_b32_e32 v7, v2
	v_mov_b32_e32 v8, v2
	v_mov_b32_e32 v9, v2
	v_mov_b32_e32 v14, v2
	v_mov_b32_e32 v15, v2
	v_mov_b32_e32 v16, v2
	v_mov_b32_e32 v17, v2
	v_mov_b32_e32 v22, v2
	v_mov_b32_e32 v23, v2
	v_mov_b32_e32 v24, v2
	v_mov_b32_e32 v25, v2
	v_mov_b32_e32 v30, v2
	v_mov_b32_e32 v31, v2
	v_mov_b32_e32 v32, v2
	v_mov_b32_e32 v33, v2
	v_mov_b32_e32 v38, v2
	v_mov_b32_e32 v39, v2
	v_mov_b32_e32 v40, v2
	v_mov_b32_e32 v41, v2
	v_mov_b32_e32 v46, v2
	v_mov_b32_e32 v47, v2
	v_mov_b32_e32 v48, v2
	v_mov_b32_e32 v49, v2
	v_mov_b32_e32 v54, v2
	v_mov_b32_e32 v55, v2
	v_mov_b32_e32 v56, v2
	v_mov_b32_e32 v57, v2
	v_mov_b32_e32 v10, v2
	v_mov_b32_e32 v11, v2
	v_mov_b32_e32 v12, v2
	v_mov_b32_e32 v13, v2
	v_mov_b32_e32 v18, v2
	v_mov_b32_e32 v19, v2
	v_mov_b32_e32 v20, v2
	v_mov_b32_e32 v21, v2
	v_mov_b32_e32 v26, v2
	v_mov_b32_e32 v27, v2
	v_mov_b32_e32 v28, v2
	v_mov_b32_e32 v29, v2
	v_mov_b32_e32 v34, v2
	v_mov_b32_e32 v35, v2
	v_mov_b32_e32 v36, v2
	v_mov_b32_e32 v37, v2
	v_mov_b32_e32 v42, v2
	v_mov_b32_e32 v43, v2
	v_mov_b32_e32 v44, v2
	v_mov_b32_e32 v45, v2
	v_mov_b32_e32 v50, v2
	v_mov_b32_e32 v51, v2
	v_mov_b32_e32 v52, v2
	v_mov_b32_e32 v53, v2
	v_mov_b32_e32 v58, v2
	v_mov_b32_e32 v59, v2
	v_mov_b32_e32 v60, v2
	v_mov_b32_e32 v61, v2
	v_mov_b32_e32 v62, v2
	v_mov_b32_e32 v63, v2
	v_mov_b32_e32 v64, v2
	v_mov_b32_e32 v65, v2
	v_mov_b32_e32 v66, v2
	v_mov_b32_e32 v67, v2
	v_mov_b32_e32 v68, v2
	v_mov_b32_e32 v69, v2
	v_mov_b32_e32 v70, v2
	v_mov_b32_e32 v71, v2
	v_mov_b32_e32 v72, v2
	v_mov_b32_e32 v73, v2
	v_mov_b32_e32 v78, v2
	v_mov_b32_e32 v79, v2
	v_mov_b32_e32 v80, v2
	v_mov_b32_e32 v81, v2
	v_mov_b32_e32 v86, v2
	v_mov_b32_e32 v87, v2
	v_mov_b32_e32 v88, v2
	v_mov_b32_e32 v89, v2
	v_mov_b32_e32 v94, v2
	v_mov_b32_e32 v95, v2
	v_mov_b32_e32 v96, v2
	v_mov_b32_e32 v97, v2
	v_mov_b32_e32 v102, v2
	v_mov_b32_e32 v103, v2
	v_mov_b32_e32 v104, v2
	v_mov_b32_e32 v105, v2
	v_mov_b32_e32 v110, v2
	v_mov_b32_e32 v111, v2
	v_mov_b32_e32 v112, v2
	v_mov_b32_e32 v113, v2
	v_mov_b32_e32 v118, v2
	v_mov_b32_e32 v119, v2
	v_mov_b32_e32 v120, v2
	v_mov_b32_e32 v121, v2
	v_mov_b32_e32 v74, v2
	v_mov_b32_e32 v75, v2
	v_mov_b32_e32 v76, v2
	v_mov_b32_e32 v77, v2
	v_mov_b32_e32 v82, v2
	v_mov_b32_e32 v83, v2
	v_mov_b32_e32 v84, v2
	v_mov_b32_e32 v85, v2
	v_mov_b32_e32 v90, v2
	v_mov_b32_e32 v91, v2
	v_mov_b32_e32 v92, v2
	v_mov_b32_e32 v93, v2
	v_mov_b32_e32 v98, v2
	v_mov_b32_e32 v99, v2
	v_mov_b32_e32 v100, v2
	v_mov_b32_e32 v101, v2
	v_mov_b32_e32 v106, v2
	v_mov_b32_e32 v107, v2
	v_mov_b32_e32 v108, v2
	v_mov_b32_e32 v109, v2
	v_mov_b32_e32 v114, v2
	v_mov_b32_e32 v115, v2
	v_mov_b32_e32 v116, v2
	v_mov_b32_e32 v117, v2
	v_mov_b32_e32 v122, v2
	v_mov_b32_e32 v123, v2
	v_mov_b32_e32 v124, v2
	v_mov_b32_e32 v125, v2
	v_mov_b32_e32 v126, v2
	v_mov_b32_e32 v127, v2
	v_mov_b32_e32 v128, v2
	v_mov_b32_e32 v129, v2
	v_and_b32_e32 v154, 63, v0
	v_lshrrev_b32_e32 v155, 6, v0
	v_and_b32_e32 v156, 15, v154
	v_lshrrev_b32_e32 v157, 4, v154
	v_bfe_u32 v158, v156, 1, 3
	v_xor_b32_e32 v157, v157, v158
	v_lshlrev_b32_e32 v157, 4, v157
	v_and_b32_e32 v158, 7, v156
	v_lshl_add_u32 v157, v158, 7, v157
	v_lshrrev_b32_e32 v158, 3, v156
	v_lshl_add_u32 v157, v158, 10, v157
	v_lshrrev_b32_e32 v158, 2, v155
	v_lshl_add_u32 v152, v158, 13, v157
	v_and_b32_e32 v158, 3, v155
	v_lshl_add_u32 v148, v158, 12, v157
	v_add_u32_e32 v150, 0x10000, v148
	v_add_u32_e32 v151, 0x14000, v148
	v_xor_b32_e32 v146, 64, v152
	v_xor_b32_e32 v147, 64, v150
	v_xor_b32_e32 v218, 64, v151
	v_add_u32_e32 v219, 0x18000, v148
	v_xor_b32_e32 v220, 64, v219
	v_add_u32_e32 v221, 0x1c000, v148
	v_xor_b32_e32 v222, 64, v221
.LBB0_1017:
	ds_read_b128 v[154:157], v150
	ds_read_b128 v[158:161], v147
	ds_read_b128 v[162:165], v150 offset:2048
	ds_read_b128 v[166:169], v147 offset:2048
	ds_read_b128 v[170:173], v151
	ds_read_b128 v[174:177], v218
	ds_read_b128 v[178:181], v151 offset:2048
	ds_read_b128 v[182:185], v218 offset:2048
	s_add_u32 s34, s30, 0x100
	s_addc_u32 s35, s31, 0
	s_cmpk_eq_i32 s74, 0x54
	s_cselect_b32 s39, s9, s35
	s_cselect_b32 s38, s8, s34
	s_cselect_b32 s37, s29, s73
	s_cselect_b32 s36, s28, s72
	s_add_i32 m0, s49, 0xc000
	ds_read_b128 v[186:189], v152
	ds_read_b128 v[190:193], v146
	ds_read_b128 v[194:197], v152 offset:2048
	ds_read_b128 v[198:201], v146 offset:2048
	ds_read_b128 v[202:205], v152 offset:4096
	ds_read_b128 v[206:209], v146 offset:4096
	ds_read_b128 v[210:213], v152 offset:6144
	ds_read_b128 v[214:217], v146 offset:6144
	global_load_lds_dwordx4 v138, s[30:31]
	s_add_i32 m0, s49, 0xe000
	s_nop 0
	global_load_lds_dwordx4 v140, s[30:31]
	s_waitcnt vmcnt(8)
	s_waitcnt lgkmcnt(0)
	s_barrier
; #define PG8_STAGE(bufoff, gbase, voff) do { _Pragma("unroll") for (int _i = 0; _i < 2; ++_i) \
;         __builtin_amdgcn_global_load_lds((const unsigned*)((const char*)(gbase) + (voff)[_i]), (PG8_LAS unsigned*)(lds + (bufoff) + ldsw + _i * 8192), 16, 0, 0); } while (0)
; #define PG8_LDA(dst, b, h) do { _Pragma("unroll") for (int m = 0; m < 4; ++m) _Pragma("unroll") for (int k = 0; k < 2; ++k) dst[m][k] = *(const PG8_LAS bf16x8*)(lds + PG8_SA(b, h) + aoff + m * 2048 + k * 1024); } while (0)
; #define PG8_MMA(ai, bj, At, Bt) do { __builtin_amdgcn_s_setprio(1); _Pragma("unroll") for (int m = 0; m < 4; ++m) _Pragma("unroll") for (int n = 0; n < 2; ++n) _Pragma("unroll") for (int k = 0; k < 2; ++k) \
;         acc[ai][bj][m][n] = __builtin_amdgcn_mfma_f32_16x16x32_bf16(Bt[n][k], At[m][k], acc[ai][bj][m][n], 0, 0, 0); __builtin_amdgcn_s_setprio(0); } while (0)
; #define PG8_WAIT_V(n) asm volatile("s_waitcnt vmcnt(" #n ")" ::: "memory")
; #define PG8_WAIT_L(n) asm volatile("s_waitcnt lgkmcnt(" #n ")" ::: "memory")
; #define PG8_BAR __builtin_amdgcn_s_barrier()
; #define PG8_SCHED __builtin_amdgcn_sched_barrier(0)
; template <class Epi, class Sched, bool ALIGN_EPI = false, bool SP2 = false>
; __device__ __forceinline__ void gemm_phase(PG8_LAS unsigned char* lds, const Gemm g, const Sched& S, const Epi& E) {
;     ...
;             PG8_WAIT_V(8); PG8_WAIT_L(0); PG8_BAR; PG8_MMA(0, 0, At, B0); PG8_MMA(0, 1, At, B1); PG8_BAR; PG8_SCHED;
;             PG8_LDA(At, 0, 1); PG8_STAGE(PG8_SB(0, 0), b2, voffB); PG8_STAGE(PG8_SB(0, 1), b2 + hstep, voffB); PG8_STAGE(PG8_SA(0, 0), a2, voffA);
;             PG8_WAIT_V(8); PG8_WAIT_L(0); PG8_BAR; PG8_MMA(1, 0, At, B0); PG8_MMA(1, 1, At, B1); PG8_BAR; PG8_SCHED;
	s_setprio 1
	s_waitcnt lgkmcnt(0)
	v_mfma_f32_16x16x32_bf16 v[126:129], v[154:157], v[186:189], v[126:129]
	v_mfma_f32_16x16x32_bf16 v[122:125], v[162:165], v[186:189], v[122:125]
	v_mfma_f32_16x16x32_bf16 v[114:117], v[154:157], v[194:197], v[114:117]
	v_mfma_f32_16x16x32_bf16 v[106:109], v[162:165], v[194:197], v[106:109]
	v_mfma_f32_16x16x32_bf16 v[98:101], v[154:157], v[202:205], v[98:101]
	v_mfma_f32_16x16x32_bf16 v[90:93], v[162:165], v[202:205], v[90:93]
	v_mfma_f32_16x16x32_bf16 v[82:85], v[154:157], v[210:213], v[82:85]
	v_mfma_f32_16x16x32_bf16 v[74:77], v[162:165], v[210:213], v[74:77]
	v_mfma_f32_16x16x32_bf16 v[126:129], v[158:161], v[190:193], v[126:129]
	v_mfma_f32_16x16x32_bf16 v[122:125], v[166:169], v[190:193], v[122:125]
	v_mfma_f32_16x16x32_bf16 v[114:117], v[158:161], v[198:201], v[114:117]
	v_mfma_f32_16x16x32_bf16 v[106:109], v[166:169], v[198:201], v[106:109]
	v_mfma_f32_16x16x32_bf16 v[98:101], v[158:161], v[206:209], v[98:101]
	v_mfma_f32_16x16x32_bf16 v[90:93], v[166:169], v[206:209], v[90:93]
	v_mfma_f32_16x16x32_bf16 v[82:85], v[158:161], v[214:217], v[82:85]
	v_mfma_f32_16x16x32_bf16 v[74:77], v[166:169], v[214:217], v[74:77]
	s_setprio 0
	s_setprio 1
	v_mfma_f32_16x16x32_bf16 v[118:121], v[170:173], v[186:189], v[118:121]
	v_mfma_f32_16x16x32_bf16 v[110:113], v[178:181], v[186:189], v[110:113]
	v_mfma_f32_16x16x32_bf16 v[102:105], v[170:173], v[194:197], v[102:105]
	v_mfma_f32_16x16x32_bf16 v[94:97], v[178:181], v[194:197], v[94:97]
	v_mfma_f32_16x16x32_bf16 v[86:89], v[170:173], v[202:205], v[86:89]
	v_mfma_f32_16x16x32_bf16 v[78:81], v[178:181], v[202:205], v[78:81]
	v_mfma_f32_16x16x32_bf16 v[70:73], v[170:173], v[210:213], v[70:73]
	v_mfma_f32_16x16x32_bf16 v[66:69], v[178:181], v[210:213], v[66:69]
	v_mfma_f32_16x16x32_bf16 v[118:121], v[174:177], v[190:193], v[118:121]
	v_mfma_f32_16x16x32_bf16 v[110:113], v[182:185], v[190:193], v[110:113]
	v_mfma_f32_16x16x32_bf16 v[102:105], v[174:177], v[198:201], v[102:105]
	v_mfma_f32_16x16x32_bf16 v[94:97], v[182:185], v[198:201], v[94:97]
	v_mfma_f32_16x16x32_bf16 v[86:89], v[174:177], v[206:209], v[86:89]
	v_mfma_f32_16x16x32_bf16 v[78:81], v[182:185], v[206:209], v[78:81]
	v_mfma_f32_16x16x32_bf16 v[70:73], v[174:177], v[214:217], v[70:73]
	v_mfma_f32_16x16x32_bf16 v[66:69], v[182:185], v[214:217], v[66:69]
	s_setprio 0
	s_barrier
	s_add_i32 s4, s62, s48
	s_mov_b32 m0, s4
	ds_read_b128 v[186:189], v152 offset:16384
	ds_read_b128 v[190:193], v146 offset:16384
	ds_read_b128 v[194:197], v152 offset:18432
	ds_read_b128 v[198:201], v146 offset:18432
	ds_read_b128 v[202:205], v152 offset:20480
	ds_read_b128 v[206:209], v146 offset:20480
	ds_read_b128 v[210:213], v152 offset:22528
	ds_read_b128 v[214:217], v146 offset:22528
	global_load_lds_dwordx4 v132, s[36:37]
	s_add_i32 m0, s4, 0x2000
	s_add_u32 s4, s36, 0x160000
	s_addc_u32 s5, s37, 0
	s_add_i32 s30, s63, s48
	global_load_lds_dwordx4 v136, s[36:37]
	s_mov_b32 m0, s30
	s_nop 0
	global_load_lds_dwordx4 v132, s[4:5]
	s_add_i32 m0, s30, 0x2000
	s_nop 0
	global_load_lds_dwordx4 v136, s[4:5]
	s_waitcnt vmcnt(6)
	s_waitcnt lgkmcnt(0)
	s_barrier
	s_setprio 1
	s_waitcnt lgkmcnt(0)
	v_mfma_f32_16x16x32_bf16 v[62:65], v[154:157], v[186:189], v[62:65]
	v_mfma_f32_16x16x32_bf16 v[58:61], v[162:165], v[186:189], v[58:61]
	v_mfma_f32_16x16x32_bf16 v[50:53], v[154:157], v[194:197], v[50:53]
	v_mfma_f32_16x16x32_bf16 v[42:45], v[162:165], v[194:197], v[42:45]
	v_mfma_f32_16x16x32_bf16 v[34:37], v[154:157], v[202:205], v[34:37]
	v_mfma_f32_16x16x32_bf16 v[26:29], v[162:165], v[202:205], v[26:29]
	v_mfma_f32_16x16x32_bf16 v[18:21], v[154:157], v[210:213], v[18:21]
	v_mfma_f32_16x16x32_bf16 v[10:13], v[162:165], v[210:213], v[10:13]
	v_mfma_f32_16x16x32_bf16 v[62:65], v[158:161], v[190:193], v[62:65]
	v_mfma_f32_16x16x32_bf16 v[58:61], v[166:169], v[190:193], v[58:61]
	v_mfma_f32_16x16x32_bf16 v[50:53], v[158:161], v[198:201], v[50:53]
	v_mfma_f32_16x16x32_bf16 v[42:45], v[166:169], v[198:201], v[42:45]
	v_mfma_f32_16x16x32_bf16 v[34:37], v[158:161], v[206:209], v[34:37]
	v_mfma_f32_16x16x32_bf16 v[26:29], v[166:169], v[206:209], v[26:29]
	v_mfma_f32_16x16x32_bf16 v[18:21], v[158:161], v[214:217], v[18:21]
	v_mfma_f32_16x16x32_bf16 v[10:13], v[166:169], v[214:217], v[10:13]
	s_setprio 0
	s_setprio 1
	v_mfma_f32_16x16x32_bf16 v[54:57], v[170:173], v[186:189], v[54:57]
	v_mfma_f32_16x16x32_bf16 v[46:49], v[178:181], v[186:189], v[46:49]
	v_mfma_f32_16x16x32_bf16 v[38:41], v[170:173], v[194:197], v[38:41]
	v_mfma_f32_16x16x32_bf16 v[30:33], v[178:181], v[194:197], v[30:33]
	v_mfma_f32_16x16x32_bf16 v[22:25], v[170:173], v[202:205], v[22:25]
	v_mfma_f32_16x16x32_bf16 v[14:17], v[178:181], v[202:205], v[14:17]
	v_mfma_f32_16x16x32_bf16 v[6:9], v[170:173], v[210:213], v[6:9]
	v_mfma_f32_16x16x32_bf16 v[2:5], v[178:181], v[210:213], v[2:5]
	v_mfma_f32_16x16x32_bf16 v[54:57], v[174:177], v[190:193], v[54:57]
	v_mfma_f32_16x16x32_bf16 v[46:49], v[182:185], v[190:193], v[46:49]
	v_mfma_f32_16x16x32_bf16 v[38:41], v[174:177], v[198:201], v[38:41]
	v_mfma_f32_16x16x32_bf16 v[30:33], v[182:185], v[198:201], v[30:33]
	v_mfma_f32_16x16x32_bf16 v[22:25], v[174:177], v[206:209], v[22:25]
	v_mfma_f32_16x16x32_bf16 v[14:17], v[182:185], v[206:209], v[14:17]
	v_mfma_f32_16x16x32_bf16 v[6:9], v[174:177], v[214:217], v[6:9]
	v_mfma_f32_16x16x32_bf16 v[2:5], v[182:185], v[214:217], v[2:5]
	s_setprio 0
	s_barrier
; #define PG8_STAGE(bufoff, gbase, voff) do { _Pragma("unroll") for (int _i = 0; _i < 2; ++_i) \
;         __builtin_amdgcn_global_load_lds((const unsigned*)((const char*)(gbase) + (voff)[_i]), (PG8_LAS unsigned*)(lds + (bufoff) + ldsw + _i * 8192), 16, 0, 0); } while (0)
; #define PG8_LDA(dst, b, h) do { _Pragma("unroll") for (int m = 0; m < 4; ++m) _Pragma("unroll") for (int k = 0; k < 2; ++k) dst[m][k] = *(const PG8_LAS bf16x8*)(lds + PG8_SA(b, h) + aoff + m * 2048 + k * 1024); } while (0)
; #define PG8_LDB(dst, b, h) do { _Pragma("unroll") for (int n = 0; n < 2; ++n) _Pragma("unroll") for (int k = 0; k < 2; ++k) dst[n][k] = *(const PG8_LAS bf16x8*)(lds + PG8_SB(b, h) + boff + n * 2048 + k * 1024); } while (0)
; #define PG8_MMA(ai, bj, At, Bt) do { __builtin_amdgcn_s_setprio(1); _Pragma("unroll") for (int m = 0; m < 4; ++m) _Pragma("unroll") for (int n = 0; n < 2; ++n) _Pragma("unroll") for (int k = 0; k < 2; ++k) \
;         acc[ai][bj][m][n] = __builtin_amdgcn_mfma_f32_16x16x32_bf16(Bt[n][k], At[m][k], acc[ai][bj][m][n], 0, 0, 0); __builtin_amdgcn_s_setprio(0); } while (0)
; #define PG8_WAIT_V(n) asm volatile("s_waitcnt vmcnt(" #n ")" ::: "memory")
; #define PG8_WAIT_L(n) asm volatile("s_waitcnt lgkmcnt(" #n ")" ::: "memory")
; #define PG8_BAR __builtin_amdgcn_s_barrier()
; #define PG8_SCHED __builtin_amdgcn_sched_barrier(0)
; template <class Epi, class Sched, bool ALIGN_EPI = false, bool SP2 = false>
; __device__ __forceinline__ void gemm_phase(PG8_LAS unsigned char* lds, const Gemm g, const Sched& S, const Epi& E) {
;     ...
;             PG8_LDB(B0, 1, 0); PG8_LDB(B1, 1, 1); PG8_SCHED; PG8_LDA(At, 1, 0); PG8_STAGE(PG8_SA(0, 1), a2 + hstep, voffA);
;             PG8_WAIT_V(8); PG8_WAIT_L(0); PG8_BAR; PG8_MMA(0, 0, At, B0); PG8_MMA(0, 1, At, B1); PG8_BAR; PG8_SCHED;
;             PG8_LDA(At, 1, 1); PG8_STAGE(PG8_SB(1, 0), b3, voffB); PG8_STAGE(PG8_SB(1, 1), b3 + hstep, voffB); PG8_STAGE(PG8_SA(1, 0), a3, voffA);
;             PG8_WAIT_V(8); PG8_WAIT_L(0); PG8_BAR; PG8_MMA(1, 0, At, B0); PG8_MMA(1, 1, At, B1); PG8_BAR; PG8_SCHED;
	s_add_i32 s30, 0, 0x18000
	s_add_i32 s31, 0, 0x1c000
	ds_read_b128 v[154:157], v219
	ds_read_b128 v[158:161], v220
	ds_read_b128 v[162:165], v219 offset:2048
	ds_read_b128 v[166:169], v220 offset:2048
	ds_read_b128 v[170:173], v221
	ds_read_b128 v[174:177], v222
	ds_read_b128 v[178:181], v221 offset:2048
	ds_read_b128 v[182:185], v222 offset:2048
	s_add_u32 s4, s38, 0x160000
	s_addc_u32 s5, s39, 0
	s_mov_b32 m0, s49
	s_nop 0
	global_load_lds_dwordx4 v130, s[38:39]
	s_mov_b32 m0, s50
	s_nop 0
	global_load_lds_dwordx4 v134, s[38:39]
	s_mov_b32 m0, s51
	ds_read_b128 v[186:189], v152 offset:32768
	ds_read_b128 v[190:193], v146 offset:32768
	ds_read_b128 v[194:197], v152 offset:34816
	ds_read_b128 v[198:201], v146 offset:34816
	ds_read_b128 v[202:205], v152 offset:36864
	ds_read_b128 v[206:209], v146 offset:36864
	ds_read_b128 v[210:213], v152 offset:38912
	ds_read_b128 v[214:217], v146 offset:38912
	global_load_lds_dwordx4 v130, s[4:5]
	s_mov_b32 m0, s52
	s_nop 0
	global_load_lds_dwordx4 v134, s[4:5]
	s_waitcnt vmcnt(8)
	s_waitcnt lgkmcnt(0)
	s_barrier
	s_setprio 1
	s_waitcnt lgkmcnt(0)
	v_mfma_f32_16x16x32_bf16 v[126:129], v[154:157], v[186:189], v[126:129]
	v_mfma_f32_16x16x32_bf16 v[122:125], v[162:165], v[186:189], v[122:125]
	v_mfma_f32_16x16x32_bf16 v[114:117], v[154:157], v[194:197], v[114:117]
	v_mfma_f32_16x16x32_bf16 v[106:109], v[162:165], v[194:197], v[106:109]
	v_mfma_f32_16x16x32_bf16 v[98:101], v[154:157], v[202:205], v[98:101]
	v_mfma_f32_16x16x32_bf16 v[90:93], v[162:165], v[202:205], v[90:93]
	v_mfma_f32_16x16x32_bf16 v[82:85], v[154:157], v[210:213], v[82:85]
	v_mfma_f32_16x16x32_bf16 v[74:77], v[162:165], v[210:213], v[74:77]
	v_mfma_f32_16x16x32_bf16 v[126:129], v[158:161], v[190:193], v[126:129]
	v_mfma_f32_16x16x32_bf16 v[122:125], v[166:169], v[190:193], v[122:125]
	v_mfma_f32_16x16x32_bf16 v[114:117], v[158:161], v[198:201], v[114:117]
	v_mfma_f32_16x16x32_bf16 v[106:109], v[166:169], v[198:201], v[106:109]
	v_mfma_f32_16x16x32_bf16 v[98:101], v[158:161], v[206:209], v[98:101]
	v_mfma_f32_16x16x32_bf16 v[90:93], v[166:169], v[206:209], v[90:93]
	v_mfma_f32_16x16x32_bf16 v[82:85], v[158:161], v[214:217], v[82:85]
	v_mfma_f32_16x16x32_bf16 v[74:77], v[166:169], v[214:217], v[74:77]
	s_setprio 0
	s_setprio 1
	v_mfma_f32_16x16x32_bf16 v[118:121], v[170:173], v[186:189], v[118:121]
	v_mfma_f32_16x16x32_bf16 v[110:113], v[178:181], v[186:189], v[110:113]
	v_mfma_f32_16x16x32_bf16 v[102:105], v[170:173], v[194:197], v[102:105]
	v_mfma_f32_16x16x32_bf16 v[94:97], v[178:181], v[194:197], v[94:97]
	v_mfma_f32_16x16x32_bf16 v[86:89], v[170:173], v[202:205], v[86:89]
	v_mfma_f32_16x16x32_bf16 v[78:81], v[178:181], v[202:205], v[78:81]
	v_mfma_f32_16x16x32_bf16 v[70:73], v[170:173], v[210:213], v[70:73]
	v_mfma_f32_16x16x32_bf16 v[66:69], v[178:181], v[210:213], v[66:69]
	v_mfma_f32_16x16x32_bf16 v[118:121], v[174:177], v[190:193], v[118:121]
	v_mfma_f32_16x16x32_bf16 v[110:113], v[182:185], v[190:193], v[110:113]
	v_mfma_f32_16x16x32_bf16 v[102:105], v[174:177], v[198:201], v[102:105]
	v_mfma_f32_16x16x32_bf16 v[94:97], v[182:185], v[198:201], v[94:97]
	v_mfma_f32_16x16x32_bf16 v[86:89], v[174:177], v[206:209], v[86:89]
	v_mfma_f32_16x16x32_bf16 v[78:81], v[182:185], v[206:209], v[78:81]
	v_mfma_f32_16x16x32_bf16 v[70:73], v[174:177], v[214:217], v[70:73]
	v_mfma_f32_16x16x32_bf16 v[66:69], v[182:185], v[214:217], v[66:69]
	s_setprio 0
	s_barrier
	s_add_i32 s4, s30, s48
	s_add_i32 m0, s4, 0xffffff80
	ds_read_b128 v[186:189], v152 offset:49152
	ds_read_b128 v[190:193], v146 offset:49152
	ds_read_b128 v[194:197], v152 offset:51200
	ds_read_b128 v[198:201], v146 offset:51200
	ds_read_b128 v[202:205], v152 offset:53248
	ds_read_b128 v[206:209], v146 offset:53248
	ds_read_b128 v[210:213], v152 offset:55296
	ds_read_b128 v[214:217], v146 offset:55296
	global_load_lds_dwordx4 v132, s[36:37] offset:128
	s_add_i32 m0, s4, 0x1f80
	s_add_u32 s4, s36, 0x160080
	s_addc_u32 s5, s37, 0
	s_add_i32 s30, s31, s48
	global_load_lds_dwordx4 v136, s[36:37] offset:128
	s_mov_b32 m0, s30
	s_nop 0
	global_load_lds_dwordx4 v132, s[4:5]
	s_add_i32 m0, s30, 0x2000
	s_nop 0
	global_load_lds_dwordx4 v136, s[4:5]
	s_add_i32 m0, s58, 0xffffff80
	s_nop 0
	global_load_lds_dwordx4 v130, s[38:39] offset:128
	s_add_i32 m0, s59, 0xffffff80
	s_nop 0
	global_load_lds_dwordx4 v134, s[38:39] offset:128
	s_waitcnt vmcnt(8)
	s_waitcnt lgkmcnt(0)
	s_barrier
	s_setprio 1
	s_waitcnt lgkmcnt(0)
	v_mfma_f32_16x16x32_bf16 v[62:65], v[154:157], v[186:189], v[62:65]
	v_mfma_f32_16x16x32_bf16 v[58:61], v[162:165], v[186:189], v[58:61]
	v_mfma_f32_16x16x32_bf16 v[50:53], v[154:157], v[194:197], v[50:53]
	v_mfma_f32_16x16x32_bf16 v[42:45], v[162:165], v[194:197], v[42:45]
	v_mfma_f32_16x16x32_bf16 v[34:37], v[154:157], v[202:205], v[34:37]
	v_mfma_f32_16x16x32_bf16 v[26:29], v[162:165], v[202:205], v[26:29]
	v_mfma_f32_16x16x32_bf16 v[18:21], v[154:157], v[210:213], v[18:21]
	v_mfma_f32_16x16x32_bf16 v[10:13], v[162:165], v[210:213], v[10:13]
	v_mfma_f32_16x16x32_bf16 v[62:65], v[158:161], v[190:193], v[62:65]
	v_mfma_f32_16x16x32_bf16 v[58:61], v[166:169], v[190:193], v[58:61]
	v_mfma_f32_16x16x32_bf16 v[50:53], v[158:161], v[198:201], v[50:53]
	v_mfma_f32_16x16x32_bf16 v[42:45], v[166:169], v[198:201], v[42:45]
	v_mfma_f32_16x16x32_bf16 v[34:37], v[158:161], v[206:209], v[34:37]
	v_mfma_f32_16x16x32_bf16 v[26:29], v[166:169], v[206:209], v[26:29]
	v_mfma_f32_16x16x32_bf16 v[18:21], v[158:161], v[214:217], v[18:21]
	v_mfma_f32_16x16x32_bf16 v[10:13], v[166:169], v[214:217], v[10:13]
	s_setprio 0
	s_setprio 1
	v_mfma_f32_16x16x32_bf16 v[54:57], v[170:173], v[186:189], v[54:57]
	v_mfma_f32_16x16x32_bf16 v[46:49], v[178:181], v[186:189], v[46:49]
	v_mfma_f32_16x16x32_bf16 v[38:41], v[170:173], v[194:197], v[38:41]
	v_mfma_f32_16x16x32_bf16 v[30:33], v[178:181], v[194:197], v[30:33]
	v_mfma_f32_16x16x32_bf16 v[22:25], v[170:173], v[202:205], v[22:25]
	v_mfma_f32_16x16x32_bf16 v[14:17], v[178:181], v[202:205], v[14:17]
	v_mfma_f32_16x16x32_bf16 v[6:9], v[170:173], v[210:213], v[6:9]
	v_mfma_f32_16x16x32_bf16 v[2:5], v[178:181], v[210:213], v[2:5]
	v_mfma_f32_16x16x32_bf16 v[54:57], v[174:177], v[190:193], v[54:57]
	v_mfma_f32_16x16x32_bf16 v[46:49], v[182:185], v[190:193], v[46:49]
	v_mfma_f32_16x16x32_bf16 v[38:41], v[174:177], v[198:201], v[38:41]
	v_mfma_f32_16x16x32_bf16 v[30:33], v[182:185], v[198:201], v[30:33]
	v_mfma_f32_16x16x32_bf16 v[22:25], v[174:177], v[206:209], v[22:25]
	v_mfma_f32_16x16x32_bf16 v[14:17], v[182:185], v[206:209], v[14:17]
	v_mfma_f32_16x16x32_bf16 v[6:9], v[174:177], v[214:217], v[6:9]
	v_mfma_f32_16x16x32_bf16 v[2:5], v[182:185], v[214:217], v[2:5]
	s_setprio 0
	s_barrier
	s_add_i32 s74, s74, 2
	s_add_u32 s72, s72, 0x100
	s_addc_u32 s73, s73, 0
	s_cmpk_gt_u32 s74, 0x55
	s_mov_b64 s[30:31], s[34:35]
	s_cbranch_scc0 .LBB0_1017
	s_and_b64 vcc, exec, s[18:19]
	s_cbranch_vccz .LBB0_1020
	s_barrier
